# GEMM K-loops: removed the back-to-back s_setprio 0 / s_setprio 1 flip between the two MFMA groups of a super-phase (priority simply stays raised)
# baseline (speedup 1.0000x reference)
; #define PG8_STAGE(bufoff, gbase, voff) do { _Pragma("unroll") for (int _i = 0; _i < 2; ++_i) \
;         __builtin_amdgcn_global_load_lds((const unsigned*)((const char*)(gbase) + (voff)[_i]), (PG8_LAS unsigned*)(lds + (bufoff) + ldsw + _i * 8192), 16, 0, 0); } while (0)
; #define PG8_LDA(dst, b, h) do { _Pragma("unroll") for (int m = 0; m < 4; ++m) _Pragma("unroll") for (int k = 0; k < 2; ++k) dst[m][k] = *(const PG8_LAS bf16x8*)(lds + PG8_SA(b, h) + aoff + m * 2048 + k * 1024); } while (0)
; #define PG8_LDB(dst, b, h) do { _Pragma("unroll") for (int n = 0; n < 2; ++n) _Pragma("unroll") for (int k = 0; k < 2; ++k) dst[n][k] = *(const PG8_LAS bf16x8*)(lds + PG8_SB(b, h) + boff + n * 2048 + k * 1024); } while (0)
; #define PG8_MMA(ai, bj, At, Bt) do { __builtin_amdgcn_s_setprio(1); _Pragma("unroll") for (int m = 0; m < 4; ++m) _Pragma("unroll") for (int n = 0; n < 2; ++n) _Pragma("unroll") for (int k = 0; k < 2; ++k) \
;         acc[ai][bj][m][n] = __builtin_amdgcn_mfma_f32_16x16x32_bf16(Bt[n][k], At[m][k], acc[ai][bj][m][n], 0, 0, 0); __builtin_amdgcn_s_setprio(0); } while (0)
; #define PG8_WAIT_V(n) asm volatile("s_waitcnt vmcnt(" #n ")" ::: "memory")
; #define PG8_WAIT_L(n) asm volatile("s_waitcnt lgkmcnt(" #n ")" ::: "memory")
; #define PG8_BAR __builtin_amdgcn_s_barrier()
; #define PG8_SCHED __builtin_amdgcn_sched_barrier(0)
; template <class Epi, class Sched, bool ALIGN_EPI = false, bool SP2 = false, bool HALFM = false>
; __device__ __forceinline__ void gemm_phase(PG8_LAS unsigned char* lds, const Gemm g, const Sched& S, const Epi& E, const int tid_in) {
;     ...
;             if constexpr (SP2) {
;             PG8_LDB(B0, 0, 0); PG8_LDB(B1, 0, 1); PG8_SCHED; PG8_LDA(At, 0, 0); PG8_STAGE(PG8_SA(1, 1), a1 + hstep, voffA);
;             PG8_WAIT_V(8); PG8_WAIT_L(0); PG8_BAR; PG8_MMA(0, 0, At, B0); PG8_MMA(0, 1, At, B1); PG8_BAR; PG8_SCHED;
;             PG8_LDA(At, 0, 1); PG8_STAGE(PG8_SB(0, 0), b2, voffB); PG8_STAGE(PG8_SB(0, 1), b2 + hstep, voffB); PG8_STAGE(PG8_SA(0, 0), a2, voffA);
;             PG8_WAIT_V(8); PG8_WAIT_L(0); PG8_BAR; if constexpr (!HALFM) { PG8_MMA(1, 0, At, B0); PG8_MMA(1, 1, At, B1); } PG8_BAR; PG8_SCHED;
.LBB0_71:
	s_add_u32 s0, s16, s18
	s_addc_u32 s1, s17, s19
	s_add_u32 s0, s0, 0x100
	s_addc_u32 s1, s1, 0
	s_add_u32 s12, s44, s18
	s_addc_u32 s13, s45, s19
	s_add_i32 s24, 0, 0x10000
	s_cmpk_eq_i32 s18, 0xb00
	s_cselect_b32 s23, s7, s1
	s_cselect_b32 s22, s6, s0
	v_add_u32_e32 v105, s24, v102
	s_cselect_b32 s21, s15, s13
	s_cselect_b32 s20, s14, s12
	s_add_i32 s12, 0, 0x14000
	ds_read_b128 v[96:99], v105
	ds_read_b128 v[106:109], v105 offset:1024
	ds_read_b128 v[110:113], v105 offset:2048
	ds_read_b128 v[114:117], v105 offset:3072
	v_add_u32_e32 v105, s12, v102
	ds_read_b128 v[118:121], v105
	ds_read_b128 v[122:125], v105 offset:1024
	ds_read_b128 v[126:129], v105 offset:2048
	ds_read_b128 v[130:133], v105 offset:3072
	v_lshl_add_u64 v[166:167], v[92:93], 0, s[18:19]
	s_add_i32 m0, s35, 0xc000
	ds_read_b128 v[134:137], v104
	ds_read_b128 v[138:141], v104 offset:1024
	ds_read_b128 v[142:145], v104 offset:2048
	ds_read_b128 v[146:149], v104 offset:3072
	ds_read_b128 v[150:153], v104 offset:4096
	ds_read_b128 v[154:157], v104 offset:5120
	ds_read_b128 v[158:161], v104 offset:6144
	ds_read_b128 v[162:165], v104 offset:7168
	global_load_lds_dwordx4 v[166:167], off
	v_lshl_add_u64 v[166:167], v[94:95], 0, s[18:19]
	s_add_i32 m0, s35, 0xe000
	s_nop 0
	global_load_lds_dwordx4 v[166:167], off
	s_waitcnt vmcnt(8)
	s_waitcnt lgkmcnt(0)
	s_barrier
	s_setprio 1
	s_waitcnt lgkmcnt(0)
	v_mfma_f32_16x16x32_bf16 v[62:65], v[96:99], v[134:137], v[62:65]
	v_mfma_f32_16x16x32_bf16 v[58:61], v[110:113], v[134:137], v[58:61]
	v_mfma_f32_16x16x32_bf16 v[46:49], v[96:99], v[142:145], v[46:49]
	v_mfma_f32_16x16x32_bf16 v[42:45], v[110:113], v[142:145], v[42:45]
	v_mfma_f32_16x16x32_bf16 v[30:33], v[96:99], v[150:153], v[30:33]
	v_mfma_f32_16x16x32_bf16 v[26:29], v[110:113], v[150:153], v[26:29]
	v_mfma_f32_16x16x32_bf16 v[14:17], v[96:99], v[158:161], v[14:17]
	v_mfma_f32_16x16x32_bf16 v[10:13], v[110:113], v[158:161], v[10:13]
	v_mfma_f32_16x16x32_bf16 v[62:65], v[106:109], v[138:141], v[62:65]
	v_mfma_f32_16x16x32_bf16 v[58:61], v[114:117], v[138:141], v[58:61]
	v_mfma_f32_16x16x32_bf16 v[46:49], v[106:109], v[146:149], v[46:49]
	v_mfma_f32_16x16x32_bf16 v[42:45], v[114:117], v[146:149], v[42:45]
	v_mfma_f32_16x16x32_bf16 v[30:33], v[106:109], v[154:157], v[30:33]
	v_mfma_f32_16x16x32_bf16 v[26:29], v[114:117], v[154:157], v[26:29]
	v_mfma_f32_16x16x32_bf16 v[14:17], v[106:109], v[162:165], v[14:17]
	v_mfma_f32_16x16x32_bf16 v[10:13], v[114:117], v[162:165], v[10:13]
	v_mfma_f32_16x16x32_bf16 v[54:57], v[118:121], v[134:137], v[54:57]
	v_mfma_f32_16x16x32_bf16 v[50:53], v[126:129], v[134:137], v[50:53]
	v_mfma_f32_16x16x32_bf16 v[38:41], v[118:121], v[142:145], v[38:41]
	v_mfma_f32_16x16x32_bf16 v[34:37], v[126:129], v[142:145], v[34:37]
	v_mfma_f32_16x16x32_bf16 v[22:25], v[118:121], v[150:153], v[22:25]
	v_mfma_f32_16x16x32_bf16 v[18:21], v[126:129], v[150:153], v[18:21]
	v_mfma_f32_16x16x32_bf16 v[6:9], v[118:121], v[158:161], v[6:9]
	v_mfma_f32_16x16x32_bf16 v[2:5], v[126:129], v[158:161], v[2:5]
	v_mfma_f32_16x16x32_bf16 v[54:57], v[122:125], v[138:141], v[54:57]
	v_mfma_f32_16x16x32_bf16 v[50:53], v[130:133], v[138:141], v[50:53]
	v_mfma_f32_16x16x32_bf16 v[38:41], v[122:125], v[146:149], v[38:41]
	v_mfma_f32_16x16x32_bf16 v[34:37], v[130:133], v[146:149], v[34:37]
	v_mfma_f32_16x16x32_bf16 v[22:25], v[122:125], v[154:157], v[22:25]
	v_mfma_f32_16x16x32_bf16 v[18:21], v[130:133], v[154:157], v[18:21]
	v_mfma_f32_16x16x32_bf16 v[6:9], v[122:125], v[162:165], v[6:9]
	v_mfma_f32_16x16x32_bf16 v[2:5], v[130:133], v[162:165], v[2:5]
	s_setprio 0
	s_barrier
	s_add_i32 s0, s24, s34
	v_lshl_add_u64 v[166:167], s[20:21], 0, v[0:1]
	s_mov_b32 m0, s0
	v_lshl_add_u64 v[168:169], s[20:21], 0, v[66:67]
	global_load_lds_dwordx4 v[166:167], off
	s_add_i32 m0, s0, 0x2000
	s_add_u32 s0, s20, 0x60000
	s_addc_u32 s1, s21, 0
	s_add_i32 s12, s12, s34
	global_load_lds_dwordx4 v[168:169], off
	v_lshl_add_u64 v[96:97], s[0:1], 0, v[0:1]
	s_mov_b32 m0, s12
	v_lshl_add_u64 v[170:171], s[22:23], 0, v[0:1]
	global_load_lds_dwordx4 v[96:97], off
	v_lshl_add_u64 v[96:97], s[0:1], 0, v[66:67]
	s_add_i32 m0, s12, 0x2000
	v_lshl_add_u64 v[172:173], s[22:23], 0, v[66:67]
	global_load_lds_dwordx4 v[96:97], off
	s_mov_b32 m0, s35
	s_nop 0
	global_load_lds_dwordx4 v[170:171], off
	s_mov_b32 m0, s36
	s_nop 0
	global_load_lds_dwordx4 v[172:173], off
	s_waitcnt vmcnt(8)
	s_waitcnt lgkmcnt(0)
	s_barrier
; #define PG8_STAGE(bufoff, gbase, voff) do { _Pragma("unroll") for (int _i = 0; _i < 2; ++_i) \
;         __builtin_amdgcn_global_load_lds((const unsigned*)((const char*)(gbase) + (voff)[_i]), (PG8_LAS unsigned*)(lds + (bufoff) + ldsw + _i * 8192), 16, 0, 0); } while (0)
; #define PG8_LDA(dst, b, h) do { _Pragma("unroll") for (int m = 0; m < 4; ++m) _Pragma("unroll") for (int k = 0; k < 2; ++k) dst[m][k] = *(const PG8_LAS bf16x8*)(lds + PG8_SA(b, h) + aoff + m * 2048 + k * 1024); } while (0)
; #define PG8_LDB(dst, b, h) do { _Pragma("unroll") for (int n = 0; n < 2; ++n) _Pragma("unroll") for (int k = 0; k < 2; ++k) dst[n][k] = *(const PG8_LAS bf16x8*)(lds + PG8_SB(b, h) + boff + n * 2048 + k * 1024); } while (0)
; #define PG8_MMA(ai, bj, At, Bt) do { __builtin_amdgcn_s_setprio(1); _Pragma("unroll") for (int m = 0; m < 4; ++m) _Pragma("unroll") for (int n = 0; n < 2; ++n) _Pragma("unroll") for (int k = 0; k < 2; ++k) \
;         acc[ai][bj][m][n] = __builtin_amdgcn_mfma_f32_16x16x32_bf16(Bt[n][k], At[m][k], acc[ai][bj][m][n], 0, 0, 0); __builtin_amdgcn_s_setprio(0); } while (0)
; #define PG8_WAIT_V(n) asm volatile("s_waitcnt vmcnt(" #n ")" ::: "memory")
; #define PG8_WAIT_L(n) asm volatile("s_waitcnt lgkmcnt(" #n ")" ::: "memory")
; #define PG8_BAR __builtin_amdgcn_s_barrier()
; #define PG8_SCHED __builtin_amdgcn_sched_barrier(0)
; template <class Epi, class Sched, bool ALIGN_EPI = false, bool SP2 = false, bool HALFM = false>
; __device__ __forceinline__ void gemm_phase(PG8_LAS unsigned char* lds, const Gemm g, const Sched& S, const Epi& E, const int tid_in) {
;     ...
;             PG8_WAIT_V(8); PG8_WAIT_L(0); PG8_BAR; if constexpr (!HALFM) { PG8_MMA(1, 0, At, B0); PG8_MMA(1, 1, At, B1); } PG8_BAR; PG8_SCHED;
;             PG8_LDB(B0, 1, 0); PG8_LDB(B1, 1, 1); PG8_SCHED; PG8_LDA(At, 1, 0); PG8_STAGE(PG8_SA(0, 1), a2 + hstep, voffA);
;             PG8_WAIT_V(8); PG8_WAIT_L(0); PG8_BAR; PG8_MMA(0, 0, At, B0); PG8_MMA(0, 1, At, B1); PG8_BAR; PG8_SCHED;
;             PG8_LDA(At, 1, 1); PG8_STAGE(PG8_SB(1, 0), b3, voffB); PG8_STAGE(PG8_SB(1, 1), b3 + hstep, voffB); PG8_STAGE(PG8_SA(1, 0), a3, voffA);
;             PG8_WAIT_V(8); PG8_WAIT_L(0); PG8_BAR; if constexpr (!HALFM) { PG8_MMA(1, 0, At, B0); PG8_MMA(1, 1, At, B1); } PG8_BAR; PG8_SCHED;
	s_barrier
	s_add_i32 s12, 0, 0x18000
	v_add_u32_e32 v105, s12, v102
	s_add_i32 s13, 0, 0x1c000
	ds_read_b128 v[96:99], v105
	ds_read_b128 v[106:109], v105 offset:1024
	ds_read_b128 v[110:113], v105 offset:2048
	ds_read_b128 v[114:117], v105 offset:3072
	v_add_u32_e32 v105, s13, v102
	ds_read_b128 v[118:121], v105
	ds_read_b128 v[122:125], v105 offset:1024
	ds_read_b128 v[126:129], v105 offset:2048
	ds_read_b128 v[130:133], v105 offset:3072
	s_add_u32 s0, s22, 0x60000
	s_addc_u32 s1, s23, 0
	s_mov_b32 m0, s37
	v_lshl_add_u64 v[174:175], s[0:1], 0, v[0:1]
	ds_read_b128 v[134:137], v104 offset:32768
	ds_read_b128 v[138:141], v104 offset:33792
	ds_read_b128 v[142:145], v104 offset:34816
	ds_read_b128 v[146:149], v104 offset:35840
	ds_read_b128 v[150:153], v104 offset:36864
	ds_read_b128 v[154:157], v104 offset:37888
	ds_read_b128 v[158:161], v104 offset:38912
	ds_read_b128 v[162:165], v104 offset:39936
	global_load_lds_dwordx4 v[174:175], off
	v_lshl_add_u64 v[174:175], s[0:1], 0, v[66:67]
	s_mov_b32 m0, s38
	s_nop 0
	global_load_lds_dwordx4 v[174:175], off
	s_waitcnt vmcnt(8)
	s_waitcnt lgkmcnt(0)
	s_barrier
	s_setprio 1
	s_waitcnt lgkmcnt(0)
	v_mfma_f32_16x16x32_bf16 v[62:65], v[96:99], v[134:137], v[62:65]
	v_mfma_f32_16x16x32_bf16 v[58:61], v[110:113], v[134:137], v[58:61]
	v_mfma_f32_16x16x32_bf16 v[46:49], v[96:99], v[142:145], v[46:49]
	v_mfma_f32_16x16x32_bf16 v[42:45], v[110:113], v[142:145], v[42:45]
	v_mfma_f32_16x16x32_bf16 v[30:33], v[96:99], v[150:153], v[30:33]
	v_mfma_f32_16x16x32_bf16 v[26:29], v[110:113], v[150:153], v[26:29]
	v_mfma_f32_16x16x32_bf16 v[14:17], v[96:99], v[158:161], v[14:17]
	v_mfma_f32_16x16x32_bf16 v[10:13], v[110:113], v[158:161], v[10:13]
	v_mfma_f32_16x16x32_bf16 v[62:65], v[106:109], v[138:141], v[62:65]
	v_mfma_f32_16x16x32_bf16 v[58:61], v[114:117], v[138:141], v[58:61]
	v_mfma_f32_16x16x32_bf16 v[46:49], v[106:109], v[146:149], v[46:49]
	v_mfma_f32_16x16x32_bf16 v[42:45], v[114:117], v[146:149], v[42:45]
	v_mfma_f32_16x16x32_bf16 v[30:33], v[106:109], v[154:157], v[30:33]
	v_mfma_f32_16x16x32_bf16 v[26:29], v[114:117], v[154:157], v[26:29]
	v_mfma_f32_16x16x32_bf16 v[14:17], v[106:109], v[162:165], v[14:17]
	v_mfma_f32_16x16x32_bf16 v[10:13], v[114:117], v[162:165], v[10:13]
	v_mfma_f32_16x16x32_bf16 v[54:57], v[118:121], v[134:137], v[54:57]
	v_mfma_f32_16x16x32_bf16 v[50:53], v[126:129], v[134:137], v[50:53]
	v_mfma_f32_16x16x32_bf16 v[38:41], v[118:121], v[142:145], v[38:41]
	v_mfma_f32_16x16x32_bf16 v[34:37], v[126:129], v[142:145], v[34:37]
	v_mfma_f32_16x16x32_bf16 v[22:25], v[118:121], v[150:153], v[22:25]
	v_mfma_f32_16x16x32_bf16 v[18:21], v[126:129], v[150:153], v[18:21]
	v_mfma_f32_16x16x32_bf16 v[6:9], v[118:121], v[158:161], v[6:9]
	v_mfma_f32_16x16x32_bf16 v[2:5], v[126:129], v[158:161], v[2:5]
	v_mfma_f32_16x16x32_bf16 v[54:57], v[122:125], v[138:141], v[54:57]
	v_mfma_f32_16x16x32_bf16 v[50:53], v[130:133], v[138:141], v[50:53]
	v_mfma_f32_16x16x32_bf16 v[38:41], v[122:125], v[146:149], v[38:41]
	v_mfma_f32_16x16x32_bf16 v[34:37], v[130:133], v[146:149], v[34:37]
	v_mfma_f32_16x16x32_bf16 v[22:25], v[122:125], v[154:157], v[22:25]
	v_mfma_f32_16x16x32_bf16 v[18:21], v[130:133], v[154:157], v[18:21]
	v_mfma_f32_16x16x32_bf16 v[6:9], v[122:125], v[162:165], v[6:9]
	v_mfma_f32_16x16x32_bf16 v[2:5], v[130:133], v[162:165], v[2:5]
	s_setprio 0
	s_barrier
	s_add_i32 s0, s12, s34
	v_lshl_add_u64 v[96:97], v[166:167], 0, s[86:87]
	s_mov_b32 m0, s0
	s_nop 0
	global_load_lds_dwordx4 v[96:97], off
	s_add_i32 m0, s0, 0x2000
	s_add_u32 s0, s20, 0x60080
	v_lshl_add_u64 v[96:97], v[168:169], 0, s[86:87]
	s_addc_u32 s1, s21, 0
	s_add_i32 s12, s13, s34
	global_load_lds_dwordx4 v[96:97], off
	v_lshl_add_u64 v[96:97], s[0:1], 0, v[0:1]
	s_mov_b32 m0, s12
	s_nop 0
	global_load_lds_dwordx4 v[96:97], off
	v_lshl_add_u64 v[96:97], s[0:1], 0, v[66:67]
	s_add_i32 m0, s12, 0x2000
	s_nop 0
	global_load_lds_dwordx4 v[96:97], off
	v_lshl_add_u64 v[96:97], v[170:171], 0, s[86:87]
	s_mov_b32 m0, s39
	s_nop 0
	global_load_lds_dwordx4 v[96:97], off
	v_lshl_add_u64 v[96:97], v[172:173], 0, s[86:87]
	s_mov_b32 m0, s40
	s_nop 0
	global_load_lds_dwordx4 v[96:97], off
	s_waitcnt vmcnt(8)
	s_waitcnt lgkmcnt(0)
	s_barrier
	s_barrier
	s_add_i32 s0, s46, 2
	s_add_u32 s18, s18, 0x100
	s_addc_u32 s19, s19, 0
	s_cmp_gt_u32 s46, 21
	s_mov_b32 s46, s0
	s_cbranch_scc1 .LBB0_80

; #define PG8_STAGE(bufoff, gbase, voff) do { _Pragma("unroll") for (int _i = 0; _i < 2; ++_i) \
;         __builtin_amdgcn_global_load_lds((const unsigned*)((const char*)(gbase) + (voff)[_i]), (PG8_LAS unsigned*)(lds + (bufoff) + ldsw + _i * 8192), 16, 0, 0); } while (0)
; #define PG8_LDA(dst, b, h) do { _Pragma("unroll") for (int m = 0; m < 4; ++m) _Pragma("unroll") for (int k = 0; k < 2; ++k) dst[m][k] = *(const PG8_LAS bf16x8*)(lds + PG8_SA(b, h) + aoff + m * 2048 + k * 1024); } while (0)
; #define PG8_LDB(dst, b, h) do { _Pragma("unroll") for (int n = 0; n < 2; ++n) _Pragma("unroll") for (int k = 0; k < 2; ++k) dst[n][k] = *(const PG8_LAS bf16x8*)(lds + PG8_SB(b, h) + boff + n * 2048 + k * 1024); } while (0)
; #define PG8_MMA(ai, bj, At, Bt) do { __builtin_amdgcn_s_setprio(1); _Pragma("unroll") for (int m = 0; m < 4; ++m) _Pragma("unroll") for (int n = 0; n < 2; ++n) _Pragma("unroll") for (int k = 0; k < 2; ++k) \
;         acc[ai][bj][m][n] = __builtin_amdgcn_mfma_f32_16x16x32_bf16(Bt[n][k], At[m][k], acc[ai][bj][m][n], 0, 0, 0); __builtin_amdgcn_s_setprio(0); } while (0)
; #define PG8_WAIT_V(n) asm volatile("s_waitcnt vmcnt(" #n ")" ::: "memory")
; #define PG8_WAIT_L(n) asm volatile("s_waitcnt lgkmcnt(" #n ")" ::: "memory")
; #define PG8_BAR __builtin_amdgcn_s_barrier()
; #define PG8_SCHED __builtin_amdgcn_sched_barrier(0)
; template <class Epi, class Sched, bool ALIGN_EPI = false, bool SP2 = false, bool HALFM = false>
; __device__ __forceinline__ void gemm_phase(PG8_LAS unsigned char* lds, const Gemm g, const Sched& S, const Epi& E, const int tid_in) {
;     ...
;             PG8_LDB(B0, 0, 0); PG8_LDB(B1, 0, 1); PG8_SCHED; PG8_LDA(At, 0, 0); PG8_STAGE(PG8_SA(1, 1), a1 + hstep, voffA);
;             PG8_WAIT_V(8); PG8_WAIT_L(0); PG8_BAR; PG8_MMA(0, 0, At, B0); PG8_MMA(0, 1, At, B1); PG8_BAR; PG8_SCHED;
;             PG8_LDA(At, 0, 1); PG8_STAGE(PG8_SB(0, 0), b2, voffB); PG8_STAGE(PG8_SB(0, 1), b2 + hstep, voffB); PG8_STAGE(PG8_SA(0, 0), a2, voffA);
.LBB0_186:
	s_add_i32 s57, s8, 2
	s_add_u32 s0, s6, 0x80
	s_addc_u32 s1, s7, 0
	s_add_i32 vcc_lo, 0, 0x10000
	s_cmp_eq_u32 s13, s8
	s_cselect_b32 s9, s53, s1
	s_cselect_b32 s8, s52, s0
	s_cselect_b32 s1, s55, s56
	s_cselect_b32 s0, s54, s31
	s_add_i32 vcc_hi, 0, 0x14000
	v_add_u32_e32 v168, vcc_lo, v157
	v_add_u32_e32 v184, vcc_hi, v157
	ds_read_b128 v[142:145], v168
	ds_read_b128 v[160:163], v168 offset:1024
	ds_read_b128 v[164:167], v168 offset:2048
	ds_read_b128 v[168:171], v168 offset:3072
	ds_read_b128 v[172:175], v184
	ds_read_b128 v[176:179], v184 offset:1024
	ds_read_b128 v[180:183], v184 offset:2048
	ds_read_b128 v[184:187], v184 offset:3072
	v_lshl_add_u64 v[222:223], s[6:7], 0, v[138:139]
	s_add_i32 m0, s77, 0xc000
	ds_read_b128 v[188:191], v159
	ds_read_b128 v[192:195], v159 offset:1024
	ds_read_b128 v[198:201], v159 offset:2048
	ds_read_b128 v[202:205], v159 offset:3072
	ds_read_b128 v[206:209], v159 offset:4096
	ds_read_b128 v[210:213], v159 offset:5120
	ds_read_b128 v[214:217], v159 offset:6144
	ds_read_b128 v[218:221], v159 offset:7168
	global_load_lds_dwordx4 v[222:223], off
	v_lshl_add_u64 v[222:223], s[6:7], 0, v[140:141]
	s_add_i32 m0, s77, 0xe000
	s_nop 0
	global_load_lds_dwordx4 v[222:223], off
	s_waitcnt vmcnt(8)
	s_waitcnt lgkmcnt(0)
	s_barrier
	s_setprio 1
	s_waitcnt lgkmcnt(0)
	v_mfma_f32_16x16x32_bf16 v[126:129], v[142:145], v[188:191], v[126:129]
	v_mfma_f32_16x16x32_bf16 v[122:125], v[164:167], v[188:191], v[122:125]
	v_mfma_f32_16x16x32_bf16 v[110:113], v[142:145], v[198:201], v[110:113]
	v_mfma_f32_16x16x32_bf16 v[106:109], v[164:167], v[198:201], v[106:109]
	v_mfma_f32_16x16x32_bf16 v[94:97], v[142:145], v[206:209], v[94:97]
	v_mfma_f32_16x16x32_bf16 v[90:93], v[164:167], v[206:209], v[90:93]
	v_mfma_f32_16x16x32_bf16 v[78:81], v[142:145], v[214:217], v[78:81]
	v_mfma_f32_16x16x32_bf16 v[74:77], v[164:167], v[214:217], v[74:77]
	v_mfma_f32_16x16x32_bf16 v[126:129], v[160:163], v[192:195], v[126:129]
	v_mfma_f32_16x16x32_bf16 v[122:125], v[168:171], v[192:195], v[122:125]
	v_mfma_f32_16x16x32_bf16 v[110:113], v[160:163], v[202:205], v[110:113]
	v_mfma_f32_16x16x32_bf16 v[106:109], v[168:171], v[202:205], v[106:109]
	v_mfma_f32_16x16x32_bf16 v[94:97], v[160:163], v[210:213], v[94:97]
	v_mfma_f32_16x16x32_bf16 v[90:93], v[168:171], v[210:213], v[90:93]
	v_mfma_f32_16x16x32_bf16 v[78:81], v[160:163], v[218:221], v[78:81]
	v_mfma_f32_16x16x32_bf16 v[74:77], v[168:171], v[218:221], v[74:77]
	v_mfma_f32_16x16x32_bf16 v[118:121], v[172:175], v[188:191], v[118:121]
	v_mfma_f32_16x16x32_bf16 v[114:117], v[180:183], v[188:191], v[114:117]
	v_mfma_f32_16x16x32_bf16 v[102:105], v[172:175], v[198:201], v[102:105]
	v_mfma_f32_16x16x32_bf16 v[98:101], v[180:183], v[198:201], v[98:101]
	v_mfma_f32_16x16x32_bf16 v[86:89], v[172:175], v[206:209], v[86:89]
	v_mfma_f32_16x16x32_bf16 v[82:85], v[180:183], v[206:209], v[82:85]
	v_mfma_f32_16x16x32_bf16 v[70:73], v[172:175], v[214:217], v[70:73]
	v_mfma_f32_16x16x32_bf16 v[66:69], v[180:183], v[214:217], v[66:69]
	v_mfma_f32_16x16x32_bf16 v[118:121], v[176:179], v[192:195], v[118:121]
	v_mfma_f32_16x16x32_bf16 v[114:117], v[184:187], v[192:195], v[114:117]
	v_mfma_f32_16x16x32_bf16 v[102:105], v[176:179], v[202:205], v[102:105]
	v_mfma_f32_16x16x32_bf16 v[98:101], v[184:187], v[202:205], v[98:101]
	v_mfma_f32_16x16x32_bf16 v[86:89], v[176:179], v[210:213], v[86:89]
	v_mfma_f32_16x16x32_bf16 v[82:85], v[184:187], v[210:213], v[82:85]
	v_mfma_f32_16x16x32_bf16 v[70:73], v[176:179], v[218:221], v[70:73]
	v_mfma_f32_16x16x32_bf16 v[66:69], v[184:187], v[218:221], v[66:69]
	s_setprio 0
	s_barrier
	s_add_i32 vcc_lo, vcc_lo, s76
	v_lshl_add_u64 v[222:223], s[0:1], 0, v[0:1]
	s_mov_b32 m0, vcc_lo
	ds_read_b128 v[188:191], v159 offset:16384
	ds_read_b128 v[192:195], v159 offset:17408
	ds_read_b128 v[198:201], v159 offset:18432
	ds_read_b128 v[202:205], v159 offset:19456
	ds_read_b128 v[206:209], v159 offset:20480
	ds_read_b128 v[210:213], v159 offset:21504
	ds_read_b128 v[214:217], v159 offset:22528
	ds_read_b128 v[218:221], v159 offset:23552
	global_load_lds_dwordx4 v[222:223], off
	s_add_i32 m0, vcc_lo, 0x2000
	v_lshl_add_u64 v[224:225], s[0:1], 0, v[136:137]
	s_add_u32 s0, s0, s92
	s_addc_u32 s1, s1, 0
	s_add_i32 vcc_lo, vcc_hi, s76
	global_load_lds_dwordx4 v[224:225], off
	v_lshl_add_u64 v[226:227], s[0:1], 0, v[0:1]
	s_mov_b32 m0, vcc_lo
	v_lshl_add_u64 v[228:229], s[0:1], 0, v[136:137]
	global_load_lds_dwordx4 v[226:227], off
	s_add_i32 m0, vcc_lo, 0x2000
	v_lshl_add_u64 v[230:231], s[8:9], 0, v[132:133]
	global_load_lds_dwordx4 v[228:229], off
	s_mov_b32 m0, s77
	v_lshl_add_u64 v[232:233], s[8:9], 0, v[134:135]
	global_load_lds_dwordx4 v[230:231], off
	s_mov_b32 m0, s88
	s_nop 0
	global_load_lds_dwordx4 v[232:233], off
	s_waitcnt vmcnt(8)
	s_waitcnt lgkmcnt(0)
	s_barrier
; #define PG8_STAGE(bufoff, gbase, voff) do { _Pragma("unroll") for (int _i = 0; _i < 2; ++_i) \
;         __builtin_amdgcn_global_load_lds((const unsigned*)((const char*)(gbase) + (voff)[_i]), (PG8_LAS unsigned*)(lds + (bufoff) + ldsw + _i * 8192), 16, 0, 0); } while (0)
; #define PG8_LDA(dst, b, h) do { _Pragma("unroll") for (int m = 0; m < 4; ++m) _Pragma("unroll") for (int k = 0; k < 2; ++k) dst[m][k] = *(const PG8_LAS bf16x8*)(lds + PG8_SA(b, h) + aoff + m * 2048 + k * 1024); } while (0)
; #define PG8_LDB(dst, b, h) do { _Pragma("unroll") for (int n = 0; n < 2; ++n) _Pragma("unroll") for (int k = 0; k < 2; ++k) dst[n][k] = *(const PG8_LAS bf16x8*)(lds + PG8_SB(b, h) + boff + n * 2048 + k * 1024); } while (0)
; #define PG8_MMA(ai, bj, At, Bt) do { __builtin_amdgcn_s_setprio(1); _Pragma("unroll") for (int m = 0; m < 4; ++m) _Pragma("unroll") for (int n = 0; n < 2; ++n) _Pragma("unroll") for (int k = 0; k < 2; ++k) \
;         acc[ai][bj][m][n] = __builtin_amdgcn_mfma_f32_16x16x32_bf16(Bt[n][k], At[m][k], acc[ai][bj][m][n], 0, 0, 0); __builtin_amdgcn_s_setprio(0); } while (0)
; #define PG8_WAIT_V(n) asm volatile("s_waitcnt vmcnt(" #n ")" ::: "memory")
; #define PG8_WAIT_L(n) asm volatile("s_waitcnt lgkmcnt(" #n ")" ::: "memory")
; #define PG8_BAR __builtin_amdgcn_s_barrier()
; #define PG8_SCHED __builtin_amdgcn_sched_barrier(0)
; template <class Epi, class Sched, bool ALIGN_EPI = false, bool SP2 = false, bool HALFM = false>
; __device__ __forceinline__ void gemm_phase(PG8_LAS unsigned char* lds, const Gemm g, const Sched& S, const Epi& E, const int tid_in) {
;     ...
;             PG8_WAIT_V(8); PG8_WAIT_L(0); PG8_BAR; if constexpr (!HALFM) { PG8_MMA(1, 0, At, B0); PG8_MMA(1, 1, At, B1); } PG8_BAR; PG8_SCHED;
;             PG8_LDB(B0, 1, 0); PG8_LDB(B1, 1, 1); PG8_SCHED; PG8_LDA(At, 1, 0); PG8_STAGE(PG8_SA(0, 1), a2 + hstep, voffA);
;             PG8_WAIT_V(8); PG8_WAIT_L(0); PG8_BAR; PG8_MMA(0, 0, At, B0); PG8_MMA(0, 1, At, B1); PG8_BAR; PG8_SCHED;
	s_setprio 1
	s_waitcnt lgkmcnt(0)
	v_mfma_f32_16x16x32_bf16 v[62:65], v[142:145], v[188:191], v[62:65]
	v_mfma_f32_16x16x32_bf16 v[58:61], v[164:167], v[188:191], v[58:61]
	v_mfma_f32_16x16x32_bf16 v[46:49], v[142:145], v[198:201], v[46:49]
	v_mfma_f32_16x16x32_bf16 v[42:45], v[164:167], v[198:201], v[42:45]
	v_mfma_f32_16x16x32_bf16 v[30:33], v[142:145], v[206:209], v[30:33]
	v_mfma_f32_16x16x32_bf16 v[26:29], v[164:167], v[206:209], v[26:29]
	v_mfma_f32_16x16x32_bf16 v[14:17], v[142:145], v[214:217], v[14:17]
	v_mfma_f32_16x16x32_bf16 v[10:13], v[164:167], v[214:217], v[10:13]
	v_mfma_f32_16x16x32_bf16 v[62:65], v[160:163], v[192:195], v[62:65]
	v_mfma_f32_16x16x32_bf16 v[58:61], v[168:171], v[192:195], v[58:61]
	v_mfma_f32_16x16x32_bf16 v[46:49], v[160:163], v[202:205], v[46:49]
	v_mfma_f32_16x16x32_bf16 v[42:45], v[168:171], v[202:205], v[42:45]
	v_mfma_f32_16x16x32_bf16 v[30:33], v[160:163], v[210:213], v[30:33]
	v_mfma_f32_16x16x32_bf16 v[26:29], v[168:171], v[210:213], v[26:29]
	v_mfma_f32_16x16x32_bf16 v[14:17], v[160:163], v[218:221], v[14:17]
	v_mfma_f32_16x16x32_bf16 v[10:13], v[168:171], v[218:221], v[10:13]
	v_mfma_f32_16x16x32_bf16 v[54:57], v[172:175], v[188:191], v[54:57]
	v_mfma_f32_16x16x32_bf16 v[50:53], v[180:183], v[188:191], v[50:53]
	v_mfma_f32_16x16x32_bf16 v[38:41], v[172:175], v[198:201], v[38:41]
	v_mfma_f32_16x16x32_bf16 v[34:37], v[180:183], v[198:201], v[34:37]
	v_mfma_f32_16x16x32_bf16 v[22:25], v[172:175], v[206:209], v[22:25]
	v_mfma_f32_16x16x32_bf16 v[18:21], v[180:183], v[206:209], v[18:21]
	v_mfma_f32_16x16x32_bf16 v[6:9], v[172:175], v[214:217], v[6:9]
	v_mfma_f32_16x16x32_bf16 v[2:5], v[180:183], v[214:217], v[2:5]
	v_mfma_f32_16x16x32_bf16 v[54:57], v[176:179], v[192:195], v[54:57]
	v_mfma_f32_16x16x32_bf16 v[50:53], v[184:187], v[192:195], v[50:53]
	v_mfma_f32_16x16x32_bf16 v[38:41], v[176:179], v[202:205], v[38:41]
	v_mfma_f32_16x16x32_bf16 v[34:37], v[184:187], v[202:205], v[34:37]
	v_mfma_f32_16x16x32_bf16 v[22:25], v[176:179], v[210:213], v[22:25]
	v_mfma_f32_16x16x32_bf16 v[18:21], v[184:187], v[210:213], v[18:21]
	v_mfma_f32_16x16x32_bf16 v[6:9], v[176:179], v[218:221], v[6:9]
	v_mfma_f32_16x16x32_bf16 v[2:5], v[184:187], v[218:221], v[2:5]
	s_setprio 0
	s_barrier
	s_add_i32 vcc_lo, 0, 0x18000
	s_add_i32 vcc_hi, 0, 0x1c000
	v_add_u32_e32 v168, vcc_lo, v157
	v_add_u32_e32 v184, vcc_hi, v157
	ds_read_b128 v[142:145], v168
	ds_read_b128 v[160:163], v168 offset:1024
	ds_read_b128 v[164:167], v168 offset:2048
	ds_read_b128 v[168:171], v168 offset:3072
	ds_read_b128 v[172:175], v184
	ds_read_b128 v[176:179], v184 offset:1024
	ds_read_b128 v[180:183], v184 offset:2048
	ds_read_b128 v[184:187], v184 offset:3072
	s_add_u32 s0, s8, s92
	s_addc_u32 s1, s9, 0
	s_mov_b32 m0, s89
	v_lshl_add_u64 v[234:235], s[0:1], 0, v[132:133]
	ds_read_b128 v[188:191], v159 offset:32768
	ds_read_b128 v[192:195], v159 offset:33792
	ds_read_b128 v[198:201], v159 offset:34816
	ds_read_b128 v[202:205], v159 offset:35840
	ds_read_b128 v[206:209], v159 offset:36864
	ds_read_b128 v[210:213], v159 offset:37888
	ds_read_b128 v[214:217], v159 offset:38912
	ds_read_b128 v[218:221], v159 offset:39936
	global_load_lds_dwordx4 v[234:235], off
	v_lshl_add_u64 v[234:235], s[0:1], 0, v[134:135]
	s_mov_b32 m0, s97
	s_nop 0
	global_load_lds_dwordx4 v[234:235], off
	s_waitcnt vmcnt(8)
	s_waitcnt lgkmcnt(0)
	s_barrier
	s_setprio 1
	s_waitcnt lgkmcnt(0)
	v_mfma_f32_16x16x32_bf16 v[126:129], v[142:145], v[188:191], v[126:129]
	v_mfma_f32_16x16x32_bf16 v[122:125], v[164:167], v[188:191], v[122:125]
	v_mfma_f32_16x16x32_bf16 v[110:113], v[142:145], v[198:201], v[110:113]
	v_mfma_f32_16x16x32_bf16 v[106:109], v[164:167], v[198:201], v[106:109]
	v_mfma_f32_16x16x32_bf16 v[94:97], v[142:145], v[206:209], v[94:97]
	v_mfma_f32_16x16x32_bf16 v[90:93], v[164:167], v[206:209], v[90:93]
	v_mfma_f32_16x16x32_bf16 v[78:81], v[142:145], v[214:217], v[78:81]
	v_mfma_f32_16x16x32_bf16 v[74:77], v[164:167], v[214:217], v[74:77]
	v_mfma_f32_16x16x32_bf16 v[126:129], v[160:163], v[192:195], v[126:129]
	v_mfma_f32_16x16x32_bf16 v[122:125], v[168:171], v[192:195], v[122:125]
	v_mfma_f32_16x16x32_bf16 v[110:113], v[160:163], v[202:205], v[110:113]
	v_mfma_f32_16x16x32_bf16 v[106:109], v[168:171], v[202:205], v[106:109]
	v_mfma_f32_16x16x32_bf16 v[94:97], v[160:163], v[210:213], v[94:97]
	v_mfma_f32_16x16x32_bf16 v[90:93], v[168:171], v[210:213], v[90:93]
	v_mfma_f32_16x16x32_bf16 v[78:81], v[160:163], v[218:221], v[78:81]
	v_mfma_f32_16x16x32_bf16 v[74:77], v[168:171], v[218:221], v[74:77]
	v_mfma_f32_16x16x32_bf16 v[118:121], v[172:175], v[188:191], v[118:121]
	v_mfma_f32_16x16x32_bf16 v[114:117], v[180:183], v[188:191], v[114:117]
	v_mfma_f32_16x16x32_bf16 v[102:105], v[172:175], v[198:201], v[102:105]
	v_mfma_f32_16x16x32_bf16 v[98:101], v[180:183], v[198:201], v[98:101]
	v_mfma_f32_16x16x32_bf16 v[86:89], v[172:175], v[206:209], v[86:89]
	v_mfma_f32_16x16x32_bf16 v[82:85], v[180:183], v[206:209], v[82:85]
	v_mfma_f32_16x16x32_bf16 v[70:73], v[172:175], v[214:217], v[70:73]
	v_mfma_f32_16x16x32_bf16 v[66:69], v[180:183], v[214:217], v[66:69]
	v_mfma_f32_16x16x32_bf16 v[118:121], v[176:179], v[192:195], v[118:121]
	v_mfma_f32_16x16x32_bf16 v[114:117], v[184:187], v[192:195], v[114:117]
	v_mfma_f32_16x16x32_bf16 v[102:105], v[176:179], v[202:205], v[102:105]
	v_mfma_f32_16x16x32_bf16 v[98:101], v[184:187], v[202:205], v[98:101]
	v_mfma_f32_16x16x32_bf16 v[86:89], v[176:179], v[210:213], v[86:89]
	v_mfma_f32_16x16x32_bf16 v[82:85], v[184:187], v[210:213], v[82:85]
	v_mfma_f32_16x16x32_bf16 v[70:73], v[176:179], v[218:221], v[70:73]
	v_mfma_f32_16x16x32_bf16 v[66:69], v[184:187], v[218:221], v[66:69]
	s_setprio 0
	s_barrier
; #define PG8_STAGE(bufoff, gbase, voff) do { _Pragma("unroll") for (int _i = 0; _i < 2; ++_i) \
;         __builtin_amdgcn_global_load_lds((const unsigned*)((const char*)(gbase) + (voff)[_i]), (PG8_LAS unsigned*)(lds + (bufoff) + ldsw + _i * 8192), 16, 0, 0); } while (0)
; #define PG8_LDA(dst, b, h) do { _Pragma("unroll") for (int m = 0; m < 4; ++m) _Pragma("unroll") for (int k = 0; k < 2; ++k) dst[m][k] = *(const PG8_LAS bf16x8*)(lds + PG8_SA(b, h) + aoff + m * 2048 + k * 1024); } while (0)
; #define PG8_MMA(ai, bj, At, Bt) do { __builtin_amdgcn_s_setprio(1); _Pragma("unroll") for (int m = 0; m < 4; ++m) _Pragma("unroll") for (int n = 0; n < 2; ++n) _Pragma("unroll") for (int k = 0; k < 2; ++k) \
;         acc[ai][bj][m][n] = __builtin_amdgcn_mfma_f32_16x16x32_bf16(Bt[n][k], At[m][k], acc[ai][bj][m][n], 0, 0, 0); __builtin_amdgcn_s_setprio(0); } while (0)
; #define PG8_WAIT_V(n) asm volatile("s_waitcnt vmcnt(" #n ")" ::: "memory")
; #define PG8_WAIT_L(n) asm volatile("s_waitcnt lgkmcnt(" #n ")" ::: "memory")
; #define PG8_BAR __builtin_amdgcn_s_barrier()
; #define PG8_SCHED __builtin_amdgcn_sched_barrier(0)
; template <class Epi, class Sched, bool ALIGN_EPI = false, bool SP2 = false, bool HALFM = false>
; __device__ __forceinline__ void gemm_phase(PG8_LAS unsigned char* lds, const Gemm g, const Sched& S, const Epi& E, const int tid_in) {
;     ...
;             PG8_LDA(At, 1, 1); PG8_STAGE(PG8_SB(1, 0), b3, voffB); PG8_STAGE(PG8_SB(1, 1), b3 + hstep, voffB); PG8_STAGE(PG8_SA(1, 0), a3, voffA);
;             PG8_WAIT_V(8); PG8_WAIT_L(0); PG8_BAR; if constexpr (!HALFM) { PG8_MMA(1, 0, At, B0); PG8_MMA(1, 1, At, B1); } PG8_BAR; PG8_SCHED;
	s_add_i32 s0, vcc_lo, s76
	v_lshl_add_u64 v[222:223], v[222:223], 0, s[86:87]
	s_mov_b32 m0, s0
	ds_read_b128 v[188:191], v159 offset:49152
	ds_read_b128 v[192:195], v159 offset:50176
	ds_read_b128 v[198:201], v159 offset:51200
	ds_read_b128 v[202:205], v159 offset:52224
	ds_read_b128 v[206:209], v159 offset:53248
	ds_read_b128 v[210:213], v159 offset:54272
	ds_read_b128 v[214:217], v159 offset:55296
	ds_read_b128 v[218:221], v159 offset:56320
	global_load_lds_dwordx4 v[222:223], off
	v_lshl_add_u64 v[222:223], v[224:225], 0, s[86:87]
	s_add_i32 m0, s0, 0x2000
	s_add_i32 s0, vcc_hi, s76
	global_load_lds_dwordx4 v[222:223], off
	v_lshl_add_u64 v[222:223], v[226:227], 0, s[86:87]
	s_mov_b32 m0, s0
	s_nop 0
	global_load_lds_dwordx4 v[222:223], off
	v_lshl_add_u64 v[222:223], v[228:229], 0, s[86:87]
	s_add_i32 m0, s0, 0x2000
	s_nop 0
	global_load_lds_dwordx4 v[222:223], off
	v_lshl_add_u64 v[222:223], v[230:231], 0, s[86:87]
	s_mov_b32 m0, s61
	s_nop 0
	global_load_lds_dwordx4 v[222:223], off
	v_lshl_add_u64 v[222:223], v[232:233], 0, s[86:87]
	s_mov_b32 m0, s12
	s_nop 0
	global_load_lds_dwordx4 v[222:223], off
	s_waitcnt vmcnt(8)
	s_waitcnt lgkmcnt(0)
	s_barrier
	s_setprio 1
	s_waitcnt lgkmcnt(0)
	v_mfma_f32_16x16x32_bf16 v[62:65], v[142:145], v[188:191], v[62:65]
	v_mfma_f32_16x16x32_bf16 v[58:61], v[164:167], v[188:191], v[58:61]
	v_mfma_f32_16x16x32_bf16 v[46:49], v[142:145], v[198:201], v[46:49]
	v_mfma_f32_16x16x32_bf16 v[42:45], v[164:167], v[198:201], v[42:45]
	v_mfma_f32_16x16x32_bf16 v[30:33], v[142:145], v[206:209], v[30:33]
	v_mfma_f32_16x16x32_bf16 v[26:29], v[164:167], v[206:209], v[26:29]
	v_mfma_f32_16x16x32_bf16 v[14:17], v[142:145], v[214:217], v[14:17]
	v_mfma_f32_16x16x32_bf16 v[10:13], v[164:167], v[214:217], v[10:13]
	v_mfma_f32_16x16x32_bf16 v[62:65], v[160:163], v[192:195], v[62:65]
	v_mfma_f32_16x16x32_bf16 v[58:61], v[168:171], v[192:195], v[58:61]
	v_mfma_f32_16x16x32_bf16 v[46:49], v[160:163], v[202:205], v[46:49]
	v_mfma_f32_16x16x32_bf16 v[42:45], v[168:171], v[202:205], v[42:45]
	v_mfma_f32_16x16x32_bf16 v[30:33], v[160:163], v[210:213], v[30:33]
	v_mfma_f32_16x16x32_bf16 v[26:29], v[168:171], v[210:213], v[26:29]
	v_mfma_f32_16x16x32_bf16 v[14:17], v[160:163], v[218:221], v[14:17]
	v_mfma_f32_16x16x32_bf16 v[10:13], v[168:171], v[218:221], v[10:13]
	v_mfma_f32_16x16x32_bf16 v[54:57], v[172:175], v[188:191], v[54:57]
	v_mfma_f32_16x16x32_bf16 v[50:53], v[180:183], v[188:191], v[50:53]
	v_mfma_f32_16x16x32_bf16 v[38:41], v[172:175], v[198:201], v[38:41]
	v_mfma_f32_16x16x32_bf16 v[34:37], v[180:183], v[198:201], v[34:37]
	v_mfma_f32_16x16x32_bf16 v[22:25], v[172:175], v[206:209], v[22:25]
	v_mfma_f32_16x16x32_bf16 v[18:21], v[180:183], v[206:209], v[18:21]
	v_mfma_f32_16x16x32_bf16 v[6:9], v[172:175], v[214:217], v[6:9]
	v_mfma_f32_16x16x32_bf16 v[2:5], v[180:183], v[214:217], v[2:5]
	v_mfma_f32_16x16x32_bf16 v[54:57], v[176:179], v[192:195], v[54:57]
	v_mfma_f32_16x16x32_bf16 v[50:53], v[184:187], v[192:195], v[50:53]
	v_mfma_f32_16x16x32_bf16 v[38:41], v[176:179], v[202:205], v[38:41]
	v_mfma_f32_16x16x32_bf16 v[34:37], v[184:187], v[202:205], v[34:37]
	v_mfma_f32_16x16x32_bf16 v[22:25], v[176:179], v[210:213], v[22:25]
	v_mfma_f32_16x16x32_bf16 v[18:21], v[184:187], v[210:213], v[18:21]
	v_mfma_f32_16x16x32_bf16 v[6:9], v[176:179], v[218:221], v[6:9]
	v_mfma_f32_16x16x32_bf16 v[2:5], v[184:187], v[218:221], v[2:5]
	s_setprio 0
	s_barrier
	s_add_u32 s6, s6, 0x100
	s_addc_u32 s7, s7, 0
	s_add_u32 s31, s31, 0x100
	s_addc_u32 s56, s56, 0
	s_cmp_ge_u32 s57, s18
	s_mov_b32 s8, s57
	s_cbranch_scc0 .LBB0_186
	s_and_b64 vcc, exec, s[50:51]
	s_cbranch_vccz .LBB0_189
	s_barrier

; #define PG8_STAGE(bufoff, gbase, voff) do { _Pragma("unroll") for (int _i = 0; _i < 2; ++_i) \
;         __builtin_amdgcn_global_load_lds((const unsigned*)((const char*)(gbase) + (voff)[_i]), (PG8_LAS unsigned*)(lds + (bufoff) + ldsw + _i * 8192), 16, 0, 0); } while (0)
; #define PG8_LDA(dst, b, h) do { _Pragma("unroll") for (int m = 0; m < 4; ++m) _Pragma("unroll") for (int k = 0; k < 2; ++k) dst[m][k] = *(const PG8_LAS bf16x8*)(lds + PG8_SA(b, h) + aoff + m * 2048 + k * 1024); } while (0)
; #define PG8_LDB(dst, b, h) do { _Pragma("unroll") for (int n = 0; n < 2; ++n) _Pragma("unroll") for (int k = 0; k < 2; ++k) dst[n][k] = *(const PG8_LAS bf16x8*)(lds + PG8_SB(b, h) + boff + n * 2048 + k * 1024); } while (0)
; #define PG8_MMA(ai, bj, At, Bt) do { __builtin_amdgcn_s_setprio(1); _Pragma("unroll") for (int m = 0; m < 4; ++m) _Pragma("unroll") for (int n = 0; n < 2; ++n) _Pragma("unroll") for (int k = 0; k < 2; ++k) \
;         acc[ai][bj][m][n] = __builtin_amdgcn_mfma_f32_16x16x32_bf16(Bt[n][k], At[m][k], acc[ai][bj][m][n], 0, 0, 0); __builtin_amdgcn_s_setprio(0); } while (0)
; #define PG8_WAIT_V(n) asm volatile("s_waitcnt vmcnt(" #n ")" ::: "memory")
; #define PG8_WAIT_L(n) asm volatile("s_waitcnt lgkmcnt(" #n ")" ::: "memory")
; #define PG8_BAR __builtin_amdgcn_s_barrier()
; #define PG8_SCHED __builtin_amdgcn_sched_barrier(0)
; template <class Epi, class Sched, bool ALIGN_EPI = false, bool SP2 = false, bool HALFM = false>
; __device__ __forceinline__ void gemm_phase(PG8_LAS unsigned char* lds, const Gemm g, const Sched& S, const Epi& E, const int tid_in) {
;     ...
;             PG8_LDB(B0, 0, 0); PG8_LDB(B1, 0, 1); PG8_SCHED; PG8_LDA(At, 0, 0); PG8_STAGE(PG8_SA(1, 1), a1 + hstep, voffA);
;             PG8_WAIT_V(8); PG8_WAIT_L(0); PG8_BAR; PG8_MMA(0, 0, At, B0); PG8_MMA(0, 1, At, B1); PG8_BAR; PG8_SCHED;
;             PG8_LDA(At, 0, 1); PG8_STAGE(PG8_SB(0, 0), b2, voffB); PG8_STAGE(PG8_SB(0, 1), b2 + hstep, voffB); PG8_STAGE(PG8_SA(0, 0), a2, voffA);
;             PG8_WAIT_V(8); PG8_WAIT_L(0); PG8_BAR; if constexpr (!HALFM) { PG8_MMA(1, 0, At, B0); PG8_MMA(1, 1, At, B1); } PG8_BAR; PG8_SCHED;
.LBB0_244:
	s_add_i32 s58, s8, 2
	s_add_u32 s0, s6, 0x80
	s_addc_u32 s1, s7, 0
	s_add_i32 s59, 0, 0x10000
	s_cmp_eq_u32 s29, s8
	s_cselect_b32 s9, s55, s1
	s_cselect_b32 s8, s54, s0
	s_cselect_b32 s1, s57, s11
	s_cselect_b32 s0, s56, s10
	s_add_i32 s89, 0, 0x14000
	v_add_u32_e32 v92, s59, v81
	v_add_u32_e32 v108, s89, v81
	ds_read_b128 v[76:79], v92
	ds_read_b128 v[84:87], v92 offset:1024
	ds_read_b128 v[88:91], v92 offset:2048
	ds_read_b128 v[92:95], v92 offset:3072
	ds_read_b128 v[96:99], v108
	ds_read_b128 v[100:103], v108 offset:1024
	ds_read_b128 v[104:107], v108 offset:2048
	ds_read_b128 v[108:111], v108 offset:3072
	v_lshl_add_u64 v[128:129], s[6:7], 0, v[72:73]
	s_add_i32 m0, s18, 0xc000
	ds_read_b128 v[112:115], v83
	ds_read_b128 v[116:119], v83 offset:1024
	ds_read_b128 v[120:123], v83 offset:2048
	ds_read_b128 v[124:127], v83 offset:3072
	ds_read_b128 v[132:135], v83 offset:4096
	ds_read_b128 v[136:139], v83 offset:5120
	ds_read_b128 v[140:143], v83 offset:6144
	ds_read_b128 v[156:159], v83 offset:7168
	global_load_lds_dwordx4 v[128:129], off
	v_lshl_add_u64 v[128:129], s[6:7], 0, v[74:75]
	s_add_i32 m0, s18, 0xe000
	s_nop 0
	global_load_lds_dwordx4 v[128:129], off
	s_waitcnt vmcnt(8)
	s_waitcnt lgkmcnt(0)
	s_barrier
	s_setprio 1
	s_waitcnt lgkmcnt(0)
	v_mfma_f32_16x16x32_bf16 v[62:65], v[76:79], v[112:115], v[62:65]
	v_mfma_f32_16x16x32_bf16 v[58:61], v[88:91], v[112:115], v[58:61]
	v_mfma_f32_16x16x32_bf16 v[46:49], v[76:79], v[120:123], v[46:49]
	v_mfma_f32_16x16x32_bf16 v[42:45], v[88:91], v[120:123], v[42:45]
	v_mfma_f32_16x16x32_bf16 v[30:33], v[76:79], v[132:135], v[30:33]
	v_mfma_f32_16x16x32_bf16 v[26:29], v[88:91], v[132:135], v[26:29]
	v_mfma_f32_16x16x32_bf16 v[14:17], v[76:79], v[140:143], v[14:17]
	v_mfma_f32_16x16x32_bf16 v[10:13], v[88:91], v[140:143], v[10:13]
	v_mfma_f32_16x16x32_bf16 v[62:65], v[84:87], v[116:119], v[62:65]
	v_mfma_f32_16x16x32_bf16 v[58:61], v[92:95], v[116:119], v[58:61]
	v_mfma_f32_16x16x32_bf16 v[46:49], v[84:87], v[124:127], v[46:49]
	v_mfma_f32_16x16x32_bf16 v[42:45], v[92:95], v[124:127], v[42:45]
	v_mfma_f32_16x16x32_bf16 v[30:33], v[84:87], v[136:139], v[30:33]
	v_mfma_f32_16x16x32_bf16 v[26:29], v[92:95], v[136:139], v[26:29]
	v_mfma_f32_16x16x32_bf16 v[14:17], v[84:87], v[156:159], v[14:17]
	v_mfma_f32_16x16x32_bf16 v[10:13], v[92:95], v[156:159], v[10:13]
	v_mfma_f32_16x16x32_bf16 v[54:57], v[96:99], v[112:115], v[54:57]
	v_mfma_f32_16x16x32_bf16 v[50:53], v[104:107], v[112:115], v[50:53]
	v_mfma_f32_16x16x32_bf16 v[38:41], v[96:99], v[120:123], v[38:41]
	v_mfma_f32_16x16x32_bf16 v[34:37], v[104:107], v[120:123], v[34:37]
	v_mfma_f32_16x16x32_bf16 v[22:25], v[96:99], v[132:135], v[22:25]
	v_mfma_f32_16x16x32_bf16 v[18:21], v[104:107], v[132:135], v[18:21]
	v_mfma_f32_16x16x32_bf16 v[6:9], v[96:99], v[140:143], v[6:9]
	v_mfma_f32_16x16x32_bf16 v[2:5], v[104:107], v[140:143], v[2:5]
	v_mfma_f32_16x16x32_bf16 v[54:57], v[100:103], v[116:119], v[54:57]
	v_mfma_f32_16x16x32_bf16 v[50:53], v[108:111], v[116:119], v[50:53]
	v_mfma_f32_16x16x32_bf16 v[38:41], v[100:103], v[124:127], v[38:41]
	v_mfma_f32_16x16x32_bf16 v[34:37], v[108:111], v[124:127], v[34:37]
	v_mfma_f32_16x16x32_bf16 v[22:25], v[100:103], v[136:139], v[22:25]
	v_mfma_f32_16x16x32_bf16 v[18:21], v[108:111], v[136:139], v[18:21]
	v_mfma_f32_16x16x32_bf16 v[6:9], v[100:103], v[156:159], v[6:9]
	v_mfma_f32_16x16x32_bf16 v[2:5], v[108:111], v[156:159], v[2:5]
	s_setprio 0
	s_barrier
	s_add_i32 s59, s59, s13
	v_lshl_add_u64 v[128:129], s[0:1], 0, v[0:1]
	s_mov_b32 m0, s59
	v_lshl_add_u64 v[144:145], s[0:1], 0, v[70:71]
	global_load_lds_dwordx4 v[128:129], off
	s_add_i32 m0, s59, 0x2000
	s_add_u32 s0, s0, s92
	s_addc_u32 s1, s1, 0
	s_add_i32 s59, s89, s13
	global_load_lds_dwordx4 v[144:145], off
	v_lshl_add_u64 v[160:161], s[0:1], 0, v[0:1]
	s_mov_b32 m0, s59
	v_lshl_add_u64 v[162:163], s[0:1], 0, v[70:71]
	global_load_lds_dwordx4 v[160:161], off
	s_add_i32 m0, s59, 0x2000
	v_lshl_add_u64 v[164:165], s[8:9], 0, v[66:67]
	global_load_lds_dwordx4 v[162:163], off
	s_mov_b32 m0, s18
	v_lshl_add_u64 v[166:167], s[8:9], 0, v[68:69]
	global_load_lds_dwordx4 v[164:165], off
	s_mov_b32 m0, s19
	s_nop 0
	global_load_lds_dwordx4 v[166:167], off
	s_waitcnt vmcnt(8)
	s_waitcnt lgkmcnt(0)
	s_barrier
	s_barrier
; #define PG8_STAGE(bufoff, gbase, voff) do { _Pragma("unroll") for (int _i = 0; _i < 2; ++_i) \
;         __builtin_amdgcn_global_load_lds((const unsigned*)((const char*)(gbase) + (voff)[_i]), (PG8_LAS unsigned*)(lds + (bufoff) + ldsw + _i * 8192), 16, 0, 0); } while (0)
; #define PG8_LDA(dst, b, h) do { _Pragma("unroll") for (int m = 0; m < 4; ++m) _Pragma("unroll") for (int k = 0; k < 2; ++k) dst[m][k] = *(const PG8_LAS bf16x8*)(lds + PG8_SA(b, h) + aoff + m * 2048 + k * 1024); } while (0)
; #define PG8_LDB(dst, b, h) do { _Pragma("unroll") for (int n = 0; n < 2; ++n) _Pragma("unroll") for (int k = 0; k < 2; ++k) dst[n][k] = *(const PG8_LAS bf16x8*)(lds + PG8_SB(b, h) + boff + n * 2048 + k * 1024); } while (0)
; #define PG8_MMA(ai, bj, At, Bt) do { __builtin_amdgcn_s_setprio(1); _Pragma("unroll") for (int m = 0; m < 4; ++m) _Pragma("unroll") for (int n = 0; n < 2; ++n) _Pragma("unroll") for (int k = 0; k < 2; ++k) \
;         acc[ai][bj][m][n] = __builtin_amdgcn_mfma_f32_16x16x32_bf16(Bt[n][k], At[m][k], acc[ai][bj][m][n], 0, 0, 0); __builtin_amdgcn_s_setprio(0); } while (0)
; #define PG8_WAIT_V(n) asm volatile("s_waitcnt vmcnt(" #n ")" ::: "memory")
; #define PG8_WAIT_L(n) asm volatile("s_waitcnt lgkmcnt(" #n ")" ::: "memory")
; #define PG8_BAR __builtin_amdgcn_s_barrier()
; #define PG8_SCHED __builtin_amdgcn_sched_barrier(0)
; template <class Epi, class Sched, bool ALIGN_EPI = false, bool SP2 = false, bool HALFM = false>
; __device__ __forceinline__ void gemm_phase(PG8_LAS unsigned char* lds, const Gemm g, const Sched& S, const Epi& E, const int tid_in) {
;     ...
;             PG8_LDB(B0, 1, 0); PG8_LDB(B1, 1, 1); PG8_SCHED; PG8_LDA(At, 1, 0); PG8_STAGE(PG8_SA(0, 1), a2 + hstep, voffA);
;             PG8_WAIT_V(8); PG8_WAIT_L(0); PG8_BAR; PG8_MMA(0, 0, At, B0); PG8_MMA(0, 1, At, B1); PG8_BAR; PG8_SCHED;
;             PG8_LDA(At, 1, 1); PG8_STAGE(PG8_SB(1, 0), b3, voffB); PG8_STAGE(PG8_SB(1, 1), b3 + hstep, voffB); PG8_STAGE(PG8_SA(1, 0), a3, voffA);
;             PG8_WAIT_V(8); PG8_WAIT_L(0); PG8_BAR; if constexpr (!HALFM) { PG8_MMA(1, 0, At, B0); PG8_MMA(1, 1, At, B1); } PG8_BAR; PG8_SCHED;
	s_add_i32 s59, 0, 0x18000
	s_add_i32 s89, 0, 0x1c000
	v_add_u32_e32 v92, s59, v81
	v_add_u32_e32 v108, s89, v81
	ds_read_b128 v[76:79], v92
	ds_read_b128 v[84:87], v92 offset:1024
	ds_read_b128 v[88:91], v92 offset:2048
	ds_read_b128 v[92:95], v92 offset:3072
	ds_read_b128 v[96:99], v108
	ds_read_b128 v[100:103], v108 offset:1024
	ds_read_b128 v[104:107], v108 offset:2048
	ds_read_b128 v[108:111], v108 offset:3072
	s_add_u32 s0, s8, s92
	s_addc_u32 s1, s9, 0
	s_mov_b32 m0, s20
	v_lshl_add_u64 v[168:169], s[0:1], 0, v[66:67]
	ds_read_b128 v[112:115], v83 offset:32768
	ds_read_b128 v[116:119], v83 offset:33792
	ds_read_b128 v[120:123], v83 offset:34816
	ds_read_b128 v[124:127], v83 offset:35840
	ds_read_b128 v[132:135], v83 offset:36864
	ds_read_b128 v[136:139], v83 offset:37888
	ds_read_b128 v[140:143], v83 offset:38912
	ds_read_b128 v[156:159], v83 offset:39936
	global_load_lds_dwordx4 v[168:169], off
	v_lshl_add_u64 v[168:169], s[0:1], 0, v[68:69]
	s_mov_b32 m0, s21
	s_nop 0
	global_load_lds_dwordx4 v[168:169], off
	s_waitcnt vmcnt(8)
	s_waitcnt lgkmcnt(0)
	s_barrier
	s_setprio 1
	s_waitcnt lgkmcnt(0)
	v_mfma_f32_16x16x32_bf16 v[62:65], v[76:79], v[112:115], v[62:65]
	v_mfma_f32_16x16x32_bf16 v[58:61], v[88:91], v[112:115], v[58:61]
	v_mfma_f32_16x16x32_bf16 v[46:49], v[76:79], v[120:123], v[46:49]
	v_mfma_f32_16x16x32_bf16 v[42:45], v[88:91], v[120:123], v[42:45]
	v_mfma_f32_16x16x32_bf16 v[30:33], v[76:79], v[132:135], v[30:33]
	v_mfma_f32_16x16x32_bf16 v[26:29], v[88:91], v[132:135], v[26:29]
	v_mfma_f32_16x16x32_bf16 v[14:17], v[76:79], v[140:143], v[14:17]
	v_mfma_f32_16x16x32_bf16 v[10:13], v[88:91], v[140:143], v[10:13]
	v_mfma_f32_16x16x32_bf16 v[62:65], v[84:87], v[116:119], v[62:65]
	v_mfma_f32_16x16x32_bf16 v[58:61], v[92:95], v[116:119], v[58:61]
	v_mfma_f32_16x16x32_bf16 v[46:49], v[84:87], v[124:127], v[46:49]
	v_mfma_f32_16x16x32_bf16 v[42:45], v[92:95], v[124:127], v[42:45]
	v_mfma_f32_16x16x32_bf16 v[30:33], v[84:87], v[136:139], v[30:33]
	v_mfma_f32_16x16x32_bf16 v[26:29], v[92:95], v[136:139], v[26:29]
	v_mfma_f32_16x16x32_bf16 v[14:17], v[84:87], v[156:159], v[14:17]
	v_mfma_f32_16x16x32_bf16 v[10:13], v[92:95], v[156:159], v[10:13]
	v_mfma_f32_16x16x32_bf16 v[54:57], v[96:99], v[112:115], v[54:57]
	v_mfma_f32_16x16x32_bf16 v[50:53], v[104:107], v[112:115], v[50:53]
	v_mfma_f32_16x16x32_bf16 v[38:41], v[96:99], v[120:123], v[38:41]
	v_mfma_f32_16x16x32_bf16 v[34:37], v[104:107], v[120:123], v[34:37]
	v_mfma_f32_16x16x32_bf16 v[22:25], v[96:99], v[132:135], v[22:25]
	v_mfma_f32_16x16x32_bf16 v[18:21], v[104:107], v[132:135], v[18:21]
	v_mfma_f32_16x16x32_bf16 v[6:9], v[96:99], v[140:143], v[6:9]
	v_mfma_f32_16x16x32_bf16 v[2:5], v[104:107], v[140:143], v[2:5]
	v_mfma_f32_16x16x32_bf16 v[54:57], v[100:103], v[116:119], v[54:57]
	v_mfma_f32_16x16x32_bf16 v[50:53], v[108:111], v[116:119], v[50:53]
	v_mfma_f32_16x16x32_bf16 v[38:41], v[100:103], v[124:127], v[38:41]
	v_mfma_f32_16x16x32_bf16 v[34:37], v[108:111], v[124:127], v[34:37]
	v_mfma_f32_16x16x32_bf16 v[22:25], v[100:103], v[136:139], v[22:25]
	v_mfma_f32_16x16x32_bf16 v[18:21], v[108:111], v[136:139], v[18:21]
	v_mfma_f32_16x16x32_bf16 v[6:9], v[100:103], v[156:159], v[6:9]
	v_mfma_f32_16x16x32_bf16 v[2:5], v[108:111], v[156:159], v[2:5]
	s_setprio 0
	s_barrier
	s_add_i32 s0, s59, s13
	v_lshl_add_u64 v[76:77], v[128:129], 0, s[86:87]
	s_mov_b32 m0, s0
	s_nop 0
	global_load_lds_dwordx4 v[76:77], off
	v_lshl_add_u64 v[76:77], v[144:145], 0, s[86:87]
	s_add_i32 m0, s0, 0x2000
	s_add_i32 s0, s89, s13
	global_load_lds_dwordx4 v[76:77], off
	v_lshl_add_u64 v[76:77], v[160:161], 0, s[86:87]
	s_mov_b32 m0, s0
	s_nop 0
	global_load_lds_dwordx4 v[76:77], off
	v_lshl_add_u64 v[76:77], v[162:163], 0, s[86:87]
	s_add_i32 m0, s0, 0x2000
	s_nop 0
	global_load_lds_dwordx4 v[76:77], off
	v_lshl_add_u64 v[76:77], v[164:165], 0, s[86:87]
	s_mov_b32 m0, s22
	s_nop 0
	global_load_lds_dwordx4 v[76:77], off
	v_lshl_add_u64 v[76:77], v[166:167], 0, s[86:87]
	s_mov_b32 m0, s23
	s_nop 0
	global_load_lds_dwordx4 v[76:77], off
	s_waitcnt vmcnt(8)
	s_waitcnt lgkmcnt(0)
	s_barrier
	s_barrier
	s_add_u32 s6, s6, 0x100
	s_addc_u32 s7, s7, 0
	s_add_u32 s10, s10, 0x100
	s_addc_u32 s11, s11, 0
	s_cmp_ge_u32 s58, s28
	s_mov_b32 s8, s58
	s_cbranch_scc0 .LBB0_244
	s_and_b64 vcc, exec, s[52:53]
	s_cbranch_vccz .LBB0_247
	s_barrier

; #define PG8_STAGE(bufoff, gbase, voff) do { _Pragma("unroll") for (int _i = 0; _i < 2; ++_i) \
;         __builtin_amdgcn_global_load_lds((const unsigned*)((const char*)(gbase) + (voff)[_i]), (PG8_LAS unsigned*)(lds + (bufoff) + ldsw + _i * 8192), 16, 0, 0); } while (0)
; #define PG8_LDA(dst, b, h) do { _Pragma("unroll") for (int m = 0; m < 4; ++m) _Pragma("unroll") for (int k = 0; k < 2; ++k) dst[m][k] = *(const PG8_LAS bf16x8*)(lds + PG8_SA(b, h) + aoff + m * 2048 + k * 1024); } while (0)
; #define PG8_LDB(dst, b, h) do { _Pragma("unroll") for (int n = 0; n < 2; ++n) _Pragma("unroll") for (int k = 0; k < 2; ++k) dst[n][k] = *(const PG8_LAS bf16x8*)(lds + PG8_SB(b, h) + boff + n * 2048 + k * 1024); } while (0)
; #define PG8_MMA(ai, bj, At, Bt) do { __builtin_amdgcn_s_setprio(1); _Pragma("unroll") for (int m = 0; m < 4; ++m) _Pragma("unroll") for (int n = 0; n < 2; ++n) _Pragma("unroll") for (int k = 0; k < 2; ++k) \
;         acc[ai][bj][m][n] = __builtin_amdgcn_mfma_f32_16x16x32_bf16(Bt[n][k], At[m][k], acc[ai][bj][m][n], 0, 0, 0); __builtin_amdgcn_s_setprio(0); } while (0)
; #define PG8_WAIT_V(n) asm volatile("s_waitcnt vmcnt(" #n ")" ::: "memory")
; #define PG8_WAIT_L(n) asm volatile("s_waitcnt lgkmcnt(" #n ")" ::: "memory")
; #define PG8_BAR __builtin_amdgcn_s_barrier()
; #define PG8_SCHED __builtin_amdgcn_sched_barrier(0)
; template <class Epi, class Sched, bool ALIGN_EPI = false, bool SP2 = false, bool HALFM = false>
; __device__ __forceinline__ void gemm_phase(PG8_LAS unsigned char* lds, const Gemm g, const Sched& S, const Epi& E, const int tid_in) {
;     ...
;             PG8_LDB(B0, 0, 0); PG8_LDB(B1, 0, 1); PG8_SCHED; PG8_LDA(At, 0, 0); PG8_STAGE(PG8_SA(1, 1), a1 + hstep, voffA);
;             PG8_WAIT_V(8); PG8_WAIT_L(0); PG8_BAR; PG8_MMA(0, 0, At, B0); PG8_MMA(0, 1, At, B1); PG8_BAR; PG8_SCHED;
;             PG8_LDA(At, 0, 1); PG8_STAGE(PG8_SB(0, 0), b2, voffB); PG8_STAGE(PG8_SB(0, 1), b2 + hstep, voffB); PG8_STAGE(PG8_SA(0, 0), a2, voffA);
.LBB0_326:
	s_add_u32 s22, s20, 0x100
	s_addc_u32 s23, s21, 0
	s_add_i32 s0, 0, 0x10000
	s_cmp_eq_u32 s48, 40
	s_cselect_b32 s27, s7, s23
	s_cselect_b32 s26, s6, s22
	s_cselect_b32 s25, s19, s47
	s_cselect_b32 s24, s18, s46
	s_add_i32 s49, 0, 0x14000
	v_add_u32_e32 v166, s0, v152
	v_add_u32_e32 v182, s49, v152
	ds_read_b128 v[138:141], v166
	ds_read_b128 v[158:161], v166 offset:1024
	ds_read_b128 v[162:165], v166 offset:2048
	ds_read_b128 v[166:169], v166 offset:3072
	ds_read_b128 v[170:173], v182
	ds_read_b128 v[174:177], v182 offset:1024
	ds_read_b128 v[178:181], v182 offset:2048
	ds_read_b128 v[182:185], v182 offset:3072
	v_lshl_add_u64 v[194:195], s[20:21], 0, v[134:135]
	s_add_i32 m0, s35, 0xc000
	ds_read_b128 v[186:189], v157
	ds_read_b128 v[190:193], v157 offset:1024
	ds_read_b128 v[198:201], v157 offset:2048
	ds_read_b128 v[202:205], v157 offset:3072
	ds_read_b128 v[206:209], v157 offset:4096
	ds_read_b128 v[210:213], v157 offset:5120
	ds_read_b128 v[214:217], v157 offset:6144
	ds_read_b128 v[218:221], v157 offset:7168
	global_load_lds_dwordx4 v[194:195], off
	v_lshl_add_u64 v[194:195], s[20:21], 0, v[136:137]
	s_add_i32 m0, s35, 0xe000
	s_nop 0
	global_load_lds_dwordx4 v[194:195], off
	s_waitcnt vmcnt(8)
	s_waitcnt lgkmcnt(0)
	s_barrier
	s_setprio 1
	s_waitcnt lgkmcnt(0)
	v_mfma_f32_16x16x32_bf16 v[126:129], v[138:141], v[186:189], v[126:129]
	v_mfma_f32_16x16x32_bf16 v[122:125], v[162:165], v[186:189], v[122:125]
	v_mfma_f32_16x16x32_bf16 v[114:117], v[138:141], v[198:201], v[114:117]
	v_mfma_f32_16x16x32_bf16 v[110:113], v[162:165], v[198:201], v[110:113]
	v_mfma_f32_16x16x32_bf16 v[98:101], v[138:141], v[206:209], v[98:101]
	v_mfma_f32_16x16x32_bf16 v[94:97], v[162:165], v[206:209], v[94:97]
	v_mfma_f32_16x16x32_bf16 v[82:85], v[138:141], v[214:217], v[82:85]
	v_mfma_f32_16x16x32_bf16 v[78:81], v[162:165], v[214:217], v[78:81]
	v_mfma_f32_16x16x32_bf16 v[126:129], v[158:161], v[190:193], v[126:129]
	v_mfma_f32_16x16x32_bf16 v[122:125], v[166:169], v[190:193], v[122:125]
	v_mfma_f32_16x16x32_bf16 v[114:117], v[158:161], v[202:205], v[114:117]
	v_mfma_f32_16x16x32_bf16 v[110:113], v[166:169], v[202:205], v[110:113]
	v_mfma_f32_16x16x32_bf16 v[98:101], v[158:161], v[210:213], v[98:101]
	v_mfma_f32_16x16x32_bf16 v[94:97], v[166:169], v[210:213], v[94:97]
	v_mfma_f32_16x16x32_bf16 v[82:85], v[158:161], v[218:221], v[82:85]
	v_mfma_f32_16x16x32_bf16 v[78:81], v[166:169], v[218:221], v[78:81]
	v_mfma_f32_16x16x32_bf16 v[118:121], v[170:173], v[186:189], v[118:121]
	v_mfma_f32_16x16x32_bf16 v[106:109], v[178:181], v[186:189], v[106:109]
	v_mfma_f32_16x16x32_bf16 v[102:105], v[170:173], v[198:201], v[102:105]
	v_mfma_f32_16x16x32_bf16 v[90:93], v[178:181], v[198:201], v[90:93]
	v_mfma_f32_16x16x32_bf16 v[86:89], v[170:173], v[206:209], v[86:89]
	v_mfma_f32_16x16x32_bf16 v[74:77], v[178:181], v[206:209], v[74:77]
	v_mfma_f32_16x16x32_bf16 v[70:73], v[170:173], v[214:217], v[70:73]
	v_mfma_f32_16x16x32_bf16 v[66:69], v[178:181], v[214:217], v[66:69]
	v_mfma_f32_16x16x32_bf16 v[118:121], v[174:177], v[190:193], v[118:121]
	v_mfma_f32_16x16x32_bf16 v[106:109], v[182:185], v[190:193], v[106:109]
	v_mfma_f32_16x16x32_bf16 v[102:105], v[174:177], v[202:205], v[102:105]
	v_mfma_f32_16x16x32_bf16 v[90:93], v[182:185], v[202:205], v[90:93]
	v_mfma_f32_16x16x32_bf16 v[86:89], v[174:177], v[210:213], v[86:89]
	v_mfma_f32_16x16x32_bf16 v[74:77], v[182:185], v[210:213], v[74:77]
	v_mfma_f32_16x16x32_bf16 v[70:73], v[174:177], v[218:221], v[70:73]
	v_mfma_f32_16x16x32_bf16 v[66:69], v[182:185], v[218:221], v[66:69]
	s_setprio 0
	s_barrier
	s_add_i32 s0, s0, s34
	v_lshl_add_u64 v[194:195], s[24:25], 0, v[0:1]
	s_mov_b32 m0, s0
	ds_read_b128 v[186:189], v157 offset:16384
	ds_read_b128 v[190:193], v157 offset:17408
	ds_read_b128 v[198:201], v157 offset:18432
	ds_read_b128 v[202:205], v157 offset:19456
	ds_read_b128 v[206:209], v157 offset:20480
	ds_read_b128 v[210:213], v157 offset:21504
	ds_read_b128 v[214:217], v157 offset:22528
	ds_read_b128 v[218:221], v157 offset:23552
	global_load_lds_dwordx4 v[194:195], off
	s_add_i32 m0, s0, 0x2000
	s_add_u32 s0, s24, 0xb0000
	v_lshl_add_u64 v[222:223], s[24:25], 0, v[132:133]
	s_addc_u32 s1, s25, 0
	s_add_i32 s20, s49, s34
	global_load_lds_dwordx4 v[222:223], off
	v_lshl_add_u64 v[224:225], s[0:1], 0, v[0:1]
	s_mov_b32 m0, s20
	v_lshl_add_u64 v[226:227], s[26:27], 0, v[132:133]
	global_load_lds_dwordx4 v[224:225], off
	v_lshl_add_u64 v[224:225], s[0:1], 0, v[132:133]
	s_add_i32 m0, s20, 0x2000
	s_nop 0
	global_load_lds_dwordx4 v[224:225], off
	v_lshl_add_u64 v[224:225], s[26:27], 0, v[0:1]
	s_mov_b32 m0, s35
	s_nop 0
	global_load_lds_dwordx4 v[224:225], off
	s_mov_b32 m0, s36
	s_nop 0
	global_load_lds_dwordx4 v[226:227], off
	s_waitcnt vmcnt(8)
	s_waitcnt lgkmcnt(0)
	s_barrier
; #define PG8_STAGE(bufoff, gbase, voff) do { _Pragma("unroll") for (int _i = 0; _i < 2; ++_i) \
;         __builtin_amdgcn_global_load_lds((const unsigned*)((const char*)(gbase) + (voff)[_i]), (PG8_LAS unsigned*)(lds + (bufoff) + ldsw + _i * 8192), 16, 0, 0); } while (0)
; #define PG8_LDA(dst, b, h) do { _Pragma("unroll") for (int m = 0; m < 4; ++m) _Pragma("unroll") for (int k = 0; k < 2; ++k) dst[m][k] = *(const PG8_LAS bf16x8*)(lds + PG8_SA(b, h) + aoff + m * 2048 + k * 1024); } while (0)
; #define PG8_LDB(dst, b, h) do { _Pragma("unroll") for (int n = 0; n < 2; ++n) _Pragma("unroll") for (int k = 0; k < 2; ++k) dst[n][k] = *(const PG8_LAS bf16x8*)(lds + PG8_SB(b, h) + boff + n * 2048 + k * 1024); } while (0)
; #define PG8_MMA(ai, bj, At, Bt) do { __builtin_amdgcn_s_setprio(1); _Pragma("unroll") for (int m = 0; m < 4; ++m) _Pragma("unroll") for (int n = 0; n < 2; ++n) _Pragma("unroll") for (int k = 0; k < 2; ++k) \
;         acc[ai][bj][m][n] = __builtin_amdgcn_mfma_f32_16x16x32_bf16(Bt[n][k], At[m][k], acc[ai][bj][m][n], 0, 0, 0); __builtin_amdgcn_s_setprio(0); } while (0)
; #define PG8_WAIT_V(n) asm volatile("s_waitcnt vmcnt(" #n ")" ::: "memory")
; #define PG8_WAIT_L(n) asm volatile("s_waitcnt lgkmcnt(" #n ")" ::: "memory")
; #define PG8_BAR __builtin_amdgcn_s_barrier()
; #define PG8_SCHED __builtin_amdgcn_sched_barrier(0)
; template <class Epi, class Sched, bool ALIGN_EPI = false, bool SP2 = false, bool HALFM = false>
; __device__ __forceinline__ void gemm_phase(PG8_LAS unsigned char* lds, const Gemm g, const Sched& S, const Epi& E, const int tid_in) {
;     ...
;             PG8_WAIT_V(8); PG8_WAIT_L(0); PG8_BAR; if constexpr (!HALFM) { PG8_MMA(1, 0, At, B0); PG8_MMA(1, 1, At, B1); } PG8_BAR; PG8_SCHED;
;             PG8_LDB(B0, 1, 0); PG8_LDB(B1, 1, 1); PG8_SCHED; PG8_LDA(At, 1, 0); PG8_STAGE(PG8_SA(0, 1), a2 + hstep, voffA);
;             PG8_WAIT_V(8); PG8_WAIT_L(0); PG8_BAR; PG8_MMA(0, 0, At, B0); PG8_MMA(0, 1, At, B1); PG8_BAR; PG8_SCHED;
	s_setprio 1
	s_waitcnt lgkmcnt(0)
	v_mfma_f32_16x16x32_bf16 v[62:65], v[138:141], v[186:189], v[62:65]
	v_mfma_f32_16x16x32_bf16 v[58:61], v[162:165], v[186:189], v[58:61]
	v_mfma_f32_16x16x32_bf16 v[50:53], v[138:141], v[198:201], v[50:53]
	v_mfma_f32_16x16x32_bf16 v[46:49], v[162:165], v[198:201], v[46:49]
	v_mfma_f32_16x16x32_bf16 v[34:37], v[138:141], v[206:209], v[34:37]
	v_mfma_f32_16x16x32_bf16 v[30:33], v[162:165], v[206:209], v[30:33]
	v_mfma_f32_16x16x32_bf16 v[18:21], v[138:141], v[214:217], v[18:21]
	v_mfma_f32_16x16x32_bf16 v[14:17], v[162:165], v[214:217], v[14:17]
	v_mfma_f32_16x16x32_bf16 v[62:65], v[158:161], v[190:193], v[62:65]
	v_mfma_f32_16x16x32_bf16 v[58:61], v[166:169], v[190:193], v[58:61]
	v_mfma_f32_16x16x32_bf16 v[50:53], v[158:161], v[202:205], v[50:53]
	v_mfma_f32_16x16x32_bf16 v[46:49], v[166:169], v[202:205], v[46:49]
	v_mfma_f32_16x16x32_bf16 v[34:37], v[158:161], v[210:213], v[34:37]
	v_mfma_f32_16x16x32_bf16 v[30:33], v[166:169], v[210:213], v[30:33]
	v_mfma_f32_16x16x32_bf16 v[18:21], v[158:161], v[218:221], v[18:21]
	v_mfma_f32_16x16x32_bf16 v[14:17], v[166:169], v[218:221], v[14:17]
	v_mfma_f32_16x16x32_bf16 v[54:57], v[170:173], v[186:189], v[54:57]
	v_mfma_f32_16x16x32_bf16 v[42:45], v[178:181], v[186:189], v[42:45]
	v_mfma_f32_16x16x32_bf16 v[38:41], v[170:173], v[198:201], v[38:41]
	v_mfma_f32_16x16x32_bf16 v[26:29], v[178:181], v[198:201], v[26:29]
	v_mfma_f32_16x16x32_bf16 v[22:25], v[170:173], v[206:209], v[22:25]
	v_mfma_f32_16x16x32_bf16 v[10:13], v[178:181], v[206:209], v[10:13]
	v_mfma_f32_16x16x32_bf16 v[6:9], v[170:173], v[214:217], v[6:9]
	v_mfma_f32_16x16x32_bf16 v[2:5], v[178:181], v[214:217], v[2:5]
	v_mfma_f32_16x16x32_bf16 v[54:57], v[174:177], v[190:193], v[54:57]
	v_mfma_f32_16x16x32_bf16 v[42:45], v[182:185], v[190:193], v[42:45]
	v_mfma_f32_16x16x32_bf16 v[38:41], v[174:177], v[202:205], v[38:41]
	v_mfma_f32_16x16x32_bf16 v[26:29], v[182:185], v[202:205], v[26:29]
	v_mfma_f32_16x16x32_bf16 v[22:25], v[174:177], v[210:213], v[22:25]
	v_mfma_f32_16x16x32_bf16 v[10:13], v[182:185], v[210:213], v[10:13]
	v_mfma_f32_16x16x32_bf16 v[6:9], v[174:177], v[218:221], v[6:9]
	v_mfma_f32_16x16x32_bf16 v[2:5], v[182:185], v[218:221], v[2:5]
	s_setprio 0
	s_barrier
	s_add_i32 s20, 0, 0x18000
	s_add_i32 s21, 0, 0x1c000
	v_add_u32_e32 v166, s20, v152
	v_add_u32_e32 v182, s21, v152
	ds_read_b128 v[138:141], v166
	ds_read_b128 v[158:161], v166 offset:1024
	ds_read_b128 v[162:165], v166 offset:2048
	ds_read_b128 v[166:169], v166 offset:3072
	ds_read_b128 v[170:173], v182
	ds_read_b128 v[174:177], v182 offset:1024
	ds_read_b128 v[178:181], v182 offset:2048
	ds_read_b128 v[182:185], v182 offset:3072
	s_add_u32 s0, s26, 0xb0000
	s_addc_u32 s1, s27, 0
	s_mov_b32 m0, s37
	v_lshl_add_u64 v[228:229], s[0:1], 0, v[0:1]
	ds_read_b128 v[186:189], v157 offset:32768
	ds_read_b128 v[190:193], v157 offset:33792
	ds_read_b128 v[198:201], v157 offset:34816
	ds_read_b128 v[202:205], v157 offset:35840
	ds_read_b128 v[206:209], v157 offset:36864
	ds_read_b128 v[210:213], v157 offset:37888
	ds_read_b128 v[214:217], v157 offset:38912
	ds_read_b128 v[218:221], v157 offset:39936
	global_load_lds_dwordx4 v[228:229], off
	v_lshl_add_u64 v[228:229], s[0:1], 0, v[132:133]
	s_mov_b32 m0, s38
	s_nop 0
	global_load_lds_dwordx4 v[228:229], off
	s_waitcnt vmcnt(8)
	s_waitcnt lgkmcnt(0)
	s_barrier
	s_setprio 1
	s_waitcnt lgkmcnt(0)
	v_mfma_f32_16x16x32_bf16 v[126:129], v[138:141], v[186:189], v[126:129]
	v_mfma_f32_16x16x32_bf16 v[122:125], v[162:165], v[186:189], v[122:125]
	v_mfma_f32_16x16x32_bf16 v[114:117], v[138:141], v[198:201], v[114:117]
	v_mfma_f32_16x16x32_bf16 v[110:113], v[162:165], v[198:201], v[110:113]
	v_mfma_f32_16x16x32_bf16 v[98:101], v[138:141], v[206:209], v[98:101]
	v_mfma_f32_16x16x32_bf16 v[94:97], v[162:165], v[206:209], v[94:97]
	v_mfma_f32_16x16x32_bf16 v[82:85], v[138:141], v[214:217], v[82:85]
	v_mfma_f32_16x16x32_bf16 v[78:81], v[162:165], v[214:217], v[78:81]
	v_mfma_f32_16x16x32_bf16 v[126:129], v[158:161], v[190:193], v[126:129]
	v_mfma_f32_16x16x32_bf16 v[122:125], v[166:169], v[190:193], v[122:125]
	v_mfma_f32_16x16x32_bf16 v[114:117], v[158:161], v[202:205], v[114:117]
	v_mfma_f32_16x16x32_bf16 v[110:113], v[166:169], v[202:205], v[110:113]
	v_mfma_f32_16x16x32_bf16 v[98:101], v[158:161], v[210:213], v[98:101]
	v_mfma_f32_16x16x32_bf16 v[94:97], v[166:169], v[210:213], v[94:97]
	v_mfma_f32_16x16x32_bf16 v[82:85], v[158:161], v[218:221], v[82:85]
	v_mfma_f32_16x16x32_bf16 v[78:81], v[166:169], v[218:221], v[78:81]
	v_mfma_f32_16x16x32_bf16 v[118:121], v[170:173], v[186:189], v[118:121]
	v_mfma_f32_16x16x32_bf16 v[106:109], v[178:181], v[186:189], v[106:109]
	v_mfma_f32_16x16x32_bf16 v[102:105], v[170:173], v[198:201], v[102:105]
	v_mfma_f32_16x16x32_bf16 v[90:93], v[178:181], v[198:201], v[90:93]
	v_mfma_f32_16x16x32_bf16 v[86:89], v[170:173], v[206:209], v[86:89]
	v_mfma_f32_16x16x32_bf16 v[74:77], v[178:181], v[206:209], v[74:77]
	v_mfma_f32_16x16x32_bf16 v[70:73], v[170:173], v[214:217], v[70:73]
	v_mfma_f32_16x16x32_bf16 v[66:69], v[178:181], v[214:217], v[66:69]
	v_mfma_f32_16x16x32_bf16 v[118:121], v[174:177], v[190:193], v[118:121]
	v_mfma_f32_16x16x32_bf16 v[106:109], v[182:185], v[190:193], v[106:109]
	v_mfma_f32_16x16x32_bf16 v[102:105], v[174:177], v[202:205], v[102:105]
	v_mfma_f32_16x16x32_bf16 v[90:93], v[182:185], v[202:205], v[90:93]
	v_mfma_f32_16x16x32_bf16 v[86:89], v[174:177], v[210:213], v[86:89]
	v_mfma_f32_16x16x32_bf16 v[74:77], v[182:185], v[210:213], v[74:77]
	v_mfma_f32_16x16x32_bf16 v[70:73], v[174:177], v[218:221], v[70:73]
	v_mfma_f32_16x16x32_bf16 v[66:69], v[182:185], v[218:221], v[66:69]
	s_setprio 0
	s_barrier
; #define PG8_STAGE(bufoff, gbase, voff) do { _Pragma("unroll") for (int _i = 0; _i < 2; ++_i) \
;         __builtin_amdgcn_global_load_lds((const unsigned*)((const char*)(gbase) + (voff)[_i]), (PG8_LAS unsigned*)(lds + (bufoff) + ldsw + _i * 8192), 16, 0, 0); } while (0)
; #define PG8_LDA(dst, b, h) do { _Pragma("unroll") for (int m = 0; m < 4; ++m) _Pragma("unroll") for (int k = 0; k < 2; ++k) dst[m][k] = *(const PG8_LAS bf16x8*)(lds + PG8_SA(b, h) + aoff + m * 2048 + k * 1024); } while (0)
; #define PG8_MMA(ai, bj, At, Bt) do { __builtin_amdgcn_s_setprio(1); _Pragma("unroll") for (int m = 0; m < 4; ++m) _Pragma("unroll") for (int n = 0; n < 2; ++n) _Pragma("unroll") for (int k = 0; k < 2; ++k) \
;         acc[ai][bj][m][n] = __builtin_amdgcn_mfma_f32_16x16x32_bf16(Bt[n][k], At[m][k], acc[ai][bj][m][n], 0, 0, 0); __builtin_amdgcn_s_setprio(0); } while (0)
; #define PG8_WAIT_V(n) asm volatile("s_waitcnt vmcnt(" #n ")" ::: "memory")
; #define PG8_WAIT_L(n) asm volatile("s_waitcnt lgkmcnt(" #n ")" ::: "memory")
; #define PG8_BAR __builtin_amdgcn_s_barrier()
; #define PG8_SCHED __builtin_amdgcn_sched_barrier(0)
; template <class Epi, class Sched, bool ALIGN_EPI = false, bool SP2 = false, bool HALFM = false>
; __device__ __forceinline__ void gemm_phase(PG8_LAS unsigned char* lds, const Gemm g, const Sched& S, const Epi& E, const int tid_in) {
;     ...
;             PG8_LDA(At, 1, 1); PG8_STAGE(PG8_SB(1, 0), b3, voffB); PG8_STAGE(PG8_SB(1, 1), b3 + hstep, voffB); PG8_STAGE(PG8_SA(1, 0), a3, voffA);
;             PG8_WAIT_V(8); PG8_WAIT_L(0); PG8_BAR; if constexpr (!HALFM) { PG8_MMA(1, 0, At, B0); PG8_MMA(1, 1, At, B1); } PG8_BAR; PG8_SCHED;
	s_add_i32 s0, s20, s34
	v_lshl_add_u64 v[194:195], v[194:195], 0, s[86:87]
	s_mov_b32 m0, s0
	ds_read_b128 v[186:189], v157 offset:49152
	ds_read_b128 v[190:193], v157 offset:50176
	ds_read_b128 v[198:201], v157 offset:51200
	ds_read_b128 v[202:205], v157 offset:52224
	ds_read_b128 v[206:209], v157 offset:53248
	ds_read_b128 v[210:213], v157 offset:54272
	ds_read_b128 v[214:217], v157 offset:55296
	ds_read_b128 v[218:221], v157 offset:56320
	global_load_lds_dwordx4 v[194:195], off
	s_add_i32 m0, s0, 0x2000
	s_add_u32 s0, s24, 0xb0080
	v_lshl_add_u64 v[194:195], v[222:223], 0, s[86:87]
	s_addc_u32 s1, s25, 0
	s_add_i32 s20, s21, s34
	global_load_lds_dwordx4 v[194:195], off
	v_lshl_add_u64 v[194:195], s[0:1], 0, v[0:1]
	s_mov_b32 m0, s20
	s_nop 0
	global_load_lds_dwordx4 v[194:195], off
	v_lshl_add_u64 v[194:195], s[0:1], 0, v[132:133]
	s_add_i32 m0, s20, 0x2000
	s_nop 0
	global_load_lds_dwordx4 v[194:195], off
	v_lshl_add_u64 v[194:195], v[224:225], 0, s[86:87]
	s_mov_b32 m0, s39
	s_nop 0
	global_load_lds_dwordx4 v[194:195], off
	v_lshl_add_u64 v[194:195], v[226:227], 0, s[86:87]
	s_mov_b32 m0, s40
	s_nop 0
	global_load_lds_dwordx4 v[194:195], off
	s_waitcnt vmcnt(8)
	s_waitcnt lgkmcnt(0)
	s_barrier
	s_setprio 1
	s_waitcnt lgkmcnt(0)
	v_mfma_f32_16x16x32_bf16 v[62:65], v[138:141], v[186:189], v[62:65]
	v_mfma_f32_16x16x32_bf16 v[58:61], v[162:165], v[186:189], v[58:61]
	v_mfma_f32_16x16x32_bf16 v[50:53], v[138:141], v[198:201], v[50:53]
	v_mfma_f32_16x16x32_bf16 v[46:49], v[162:165], v[198:201], v[46:49]
	v_mfma_f32_16x16x32_bf16 v[34:37], v[138:141], v[206:209], v[34:37]
	v_mfma_f32_16x16x32_bf16 v[30:33], v[162:165], v[206:209], v[30:33]
	v_mfma_f32_16x16x32_bf16 v[18:21], v[138:141], v[214:217], v[18:21]
	v_mfma_f32_16x16x32_bf16 v[14:17], v[162:165], v[214:217], v[14:17]
	v_mfma_f32_16x16x32_bf16 v[62:65], v[158:161], v[190:193], v[62:65]
	v_mfma_f32_16x16x32_bf16 v[58:61], v[166:169], v[190:193], v[58:61]
	v_mfma_f32_16x16x32_bf16 v[50:53], v[158:161], v[202:205], v[50:53]
	v_mfma_f32_16x16x32_bf16 v[46:49], v[166:169], v[202:205], v[46:49]
	v_mfma_f32_16x16x32_bf16 v[34:37], v[158:161], v[210:213], v[34:37]
	v_mfma_f32_16x16x32_bf16 v[30:33], v[166:169], v[210:213], v[30:33]
	v_mfma_f32_16x16x32_bf16 v[18:21], v[158:161], v[218:221], v[18:21]
	v_mfma_f32_16x16x32_bf16 v[14:17], v[166:169], v[218:221], v[14:17]
	v_mfma_f32_16x16x32_bf16 v[54:57], v[170:173], v[186:189], v[54:57]
	v_mfma_f32_16x16x32_bf16 v[42:45], v[178:181], v[186:189], v[42:45]
	v_mfma_f32_16x16x32_bf16 v[38:41], v[170:173], v[198:201], v[38:41]
	v_mfma_f32_16x16x32_bf16 v[26:29], v[178:181], v[198:201], v[26:29]
	v_mfma_f32_16x16x32_bf16 v[22:25], v[170:173], v[206:209], v[22:25]
	v_mfma_f32_16x16x32_bf16 v[10:13], v[178:181], v[206:209], v[10:13]
	v_mfma_f32_16x16x32_bf16 v[6:9], v[170:173], v[214:217], v[6:9]
	v_mfma_f32_16x16x32_bf16 v[2:5], v[178:181], v[214:217], v[2:5]
	v_mfma_f32_16x16x32_bf16 v[54:57], v[174:177], v[190:193], v[54:57]
	v_mfma_f32_16x16x32_bf16 v[42:45], v[182:185], v[190:193], v[42:45]
	v_mfma_f32_16x16x32_bf16 v[38:41], v[174:177], v[202:205], v[38:41]
	v_mfma_f32_16x16x32_bf16 v[26:29], v[182:185], v[202:205], v[26:29]
	v_mfma_f32_16x16x32_bf16 v[22:25], v[174:177], v[210:213], v[22:25]
	v_mfma_f32_16x16x32_bf16 v[10:13], v[182:185], v[210:213], v[10:13]
	v_mfma_f32_16x16x32_bf16 v[6:9], v[174:177], v[218:221], v[6:9]
	v_mfma_f32_16x16x32_bf16 v[2:5], v[182:185], v[218:221], v[2:5]
	s_setprio 0
	s_barrier
	s_add_i32 s48, s48, 2
	s_add_u32 s46, s46, 0x100
	s_addc_u32 s47, s47, 0
	s_cmp_gt_u32 s48, 41
	s_mov_b64 s[20:21], s[22:23]
	s_cbranch_scc0 .LBB0_326
	s_and_b64 vcc, exec, s[16:17]
	s_cbranch_vccz .LBB0_329
	s_barrier

; #define PG8_STAGE(bufoff, gbase, voff) do { _Pragma("unroll") for (int _i = 0; _i < 2; ++_i) \
;         __builtin_amdgcn_global_load_lds((const unsigned*)((const char*)(gbase) + (voff)[_i]), (PG8_LAS unsigned*)(lds + (bufoff) + ldsw + _i * 8192), 16, 0, 0); } while (0)
; #define PG8_LDA(dst, b, h) do { _Pragma("unroll") for (int m = 0; m < 4; ++m) _Pragma("unroll") for (int k = 0; k < 2; ++k) dst[m][k] = *(const PG8_LAS bf16x8*)(lds + PG8_SA(b, h) + aoff + m * 2048 + k * 1024); } while (0)
; #define PG8_LDB(dst, b, h) do { _Pragma("unroll") for (int n = 0; n < 2; ++n) _Pragma("unroll") for (int k = 0; k < 2; ++k) dst[n][k] = *(const PG8_LAS bf16x8*)(lds + PG8_SB(b, h) + boff + n * 2048 + k * 1024); } while (0)
; #define PG8_MMA(ai, bj, At, Bt) do { __builtin_amdgcn_s_setprio(1); _Pragma("unroll") for (int m = 0; m < 4; ++m) _Pragma("unroll") for (int n = 0; n < 2; ++n) _Pragma("unroll") for (int k = 0; k < 2; ++k) \
;         acc[ai][bj][m][n] = __builtin_amdgcn_mfma_f32_16x16x32_bf16(Bt[n][k], At[m][k], acc[ai][bj][m][n], 0, 0, 0); __builtin_amdgcn_s_setprio(0); } while (0)
; #define PG8_WAIT_V(n) asm volatile("s_waitcnt vmcnt(" #n ")" ::: "memory")
; #define PG8_WAIT_L(n) asm volatile("s_waitcnt lgkmcnt(" #n ")" ::: "memory")
; #define PG8_BAR __builtin_amdgcn_s_barrier()
; #define PG8_SCHED __builtin_amdgcn_sched_barrier(0)
; template <class Epi, class Sched, bool ALIGN_EPI = false, bool SP2 = false, bool HALFM = false>
; __device__ __forceinline__ void gemm_phase(PG8_LAS unsigned char* lds, const Gemm g, const Sched& S, const Epi& E, const int tid_in) {
;     ...
;             PG8_LDB(B0, 0, 0); PG8_LDB(B1, 0, 1); PG8_SCHED; PG8_LDA(At, 0, 0); PG8_STAGE(PG8_SA(1, 1), a1 + hstep, voffA);
;             PG8_WAIT_V(8); PG8_WAIT_L(0); PG8_BAR; PG8_MMA(0, 0, At, B0); PG8_MMA(0, 1, At, B1); PG8_BAR; PG8_SCHED;
;             PG8_LDA(At, 0, 1); PG8_STAGE(PG8_SB(0, 0), b2, voffB); PG8_STAGE(PG8_SB(0, 1), b2 + hstep, voffB); PG8_STAGE(PG8_SA(0, 0), a2, voffA);
;             PG8_WAIT_V(8); PG8_WAIT_L(0); PG8_BAR; if constexpr (!HALFM) { PG8_MMA(1, 0, At, B0); PG8_MMA(1, 1, At, B1); } PG8_BAR; PG8_SCHED;
.LBB0_352:
	s_add_u32 s0, s24, 0xfffc0080
	s_addc_u32 s1, s25, -1
	s_add_i32 s49, 0, 0x10000
	s_cmp_eq_u32 s48, 12
	s_cselect_b32 s29, s17, s1
	s_cselect_b32 s28, s44, s0
	v_add_u32_e32 v70, s49, v73
	s_cselect_b32 s27, s15, s47
	s_cselect_b32 s26, s45, s46
	s_add_i32 s50, 0, 0x14000
	ds_read_b128 v[80:83], v70
	ds_read_b128 v[84:87], v70 offset:1024
	ds_read_b128 v[88:91], v70 offset:2048
	ds_read_b128 v[92:95], v70 offset:3072
	v_add_u32_e32 v70, s50, v73
	ds_read_b128 v[96:99], v70
	ds_read_b128 v[100:103], v70 offset:1024
	ds_read_b128 v[104:107], v70 offset:2048
	ds_read_b128 v[108:111], v70 offset:3072
	v_lshl_add_u64 v[70:71], s[24:25], 0, v[68:69]
	s_add_i32 m0, s37, 0xc000
	ds_read_b128 v[112:115], v78
	ds_read_b128 v[116:119], v78 offset:1024
	ds_read_b128 v[120:123], v78 offset:2048
	ds_read_b128 v[124:127], v78 offset:3072
	ds_read_b128 v[132:135], v78 offset:4096
	ds_read_b128 v[136:139], v78 offset:5120
	ds_read_b128 v[140:143], v78 offset:6144
	ds_read_b128 v[144:147], v78 offset:7168
	global_load_lds_dwordx4 v[70:71], off
	v_lshl_add_u64 v[70:71], s[24:25], 0, v[66:67]
	s_add_i32 m0, s37, 0xe000
	s_nop 0
	global_load_lds_dwordx4 v[70:71], off
	s_waitcnt vmcnt(8)
	s_waitcnt lgkmcnt(0)
	s_barrier
	s_setprio 1
	s_waitcnt lgkmcnt(0)
	v_mfma_f32_16x16x32_bf16 v[62:65], v[80:83], v[112:115], v[62:65]
	v_mfma_f32_16x16x32_bf16 v[58:61], v[88:91], v[112:115], v[58:61]
	v_mfma_f32_16x16x32_bf16 v[46:49], v[80:83], v[120:123], v[46:49]
	v_mfma_f32_16x16x32_bf16 v[42:45], v[88:91], v[120:123], v[42:45]
	v_mfma_f32_16x16x32_bf16 v[30:33], v[80:83], v[132:135], v[30:33]
	v_mfma_f32_16x16x32_bf16 v[26:29], v[88:91], v[132:135], v[26:29]
	v_mfma_f32_16x16x32_bf16 v[14:17], v[80:83], v[140:143], v[14:17]
	v_mfma_f32_16x16x32_bf16 v[10:13], v[88:91], v[140:143], v[10:13]
	v_mfma_f32_16x16x32_bf16 v[62:65], v[84:87], v[116:119], v[62:65]
	v_mfma_f32_16x16x32_bf16 v[58:61], v[92:95], v[116:119], v[58:61]
	v_mfma_f32_16x16x32_bf16 v[46:49], v[84:87], v[124:127], v[46:49]
	v_mfma_f32_16x16x32_bf16 v[42:45], v[92:95], v[124:127], v[42:45]
	v_mfma_f32_16x16x32_bf16 v[30:33], v[84:87], v[136:139], v[30:33]
	v_mfma_f32_16x16x32_bf16 v[26:29], v[92:95], v[136:139], v[26:29]
	v_mfma_f32_16x16x32_bf16 v[14:17], v[84:87], v[144:147], v[14:17]
	v_mfma_f32_16x16x32_bf16 v[10:13], v[92:95], v[144:147], v[10:13]
	v_mfma_f32_16x16x32_bf16 v[54:57], v[96:99], v[112:115], v[54:57]
	v_mfma_f32_16x16x32_bf16 v[50:53], v[104:107], v[112:115], v[50:53]
	v_mfma_f32_16x16x32_bf16 v[38:41], v[96:99], v[120:123], v[38:41]
	v_mfma_f32_16x16x32_bf16 v[34:37], v[104:107], v[120:123], v[34:37]
	v_mfma_f32_16x16x32_bf16 v[22:25], v[96:99], v[132:135], v[22:25]
	v_mfma_f32_16x16x32_bf16 v[18:21], v[104:107], v[132:135], v[18:21]
	v_mfma_f32_16x16x32_bf16 v[6:9], v[96:99], v[140:143], v[6:9]
	v_mfma_f32_16x16x32_bf16 v[2:5], v[104:107], v[140:143], v[2:5]
	v_mfma_f32_16x16x32_bf16 v[54:57], v[100:103], v[116:119], v[54:57]
	v_mfma_f32_16x16x32_bf16 v[50:53], v[108:111], v[116:119], v[50:53]
	v_mfma_f32_16x16x32_bf16 v[38:41], v[100:103], v[124:127], v[38:41]
	v_mfma_f32_16x16x32_bf16 v[34:37], v[108:111], v[124:127], v[34:37]
	v_mfma_f32_16x16x32_bf16 v[22:25], v[100:103], v[136:139], v[22:25]
	v_mfma_f32_16x16x32_bf16 v[18:21], v[108:111], v[136:139], v[18:21]
	v_mfma_f32_16x16x32_bf16 v[6:9], v[100:103], v[144:147], v[6:9]
	v_mfma_f32_16x16x32_bf16 v[2:5], v[108:111], v[144:147], v[2:5]
	s_setprio 0
	s_barrier
	s_add_i32 s0, s49, s36
	v_lshl_add_u64 v[70:71], s[26:27], 0, v[0:1]
	s_mov_b32 m0, s0
	v_lshl_add_u64 v[128:129], s[26:27], 0, v[66:67]
	global_load_lds_dwordx4 v[70:71], off
	s_add_i32 m0, s0, 0x2000
	s_add_u32 s0, s26, 0x40000
	s_addc_u32 s1, s27, 0
	s_add_i32 s49, s50, s36
	global_load_lds_dwordx4 v[128:129], off
	v_lshl_add_u64 v[80:81], s[0:1], 0, v[0:1]
	s_mov_b32 m0, s49
	v_lshl_add_u64 v[148:149], s[28:29], 0, v[0:1]
	global_load_lds_dwordx4 v[80:81], off
	v_lshl_add_u64 v[80:81], s[0:1], 0, v[66:67]
	s_add_i32 m0, s49, 0x2000
	v_lshl_add_u64 v[150:151], s[28:29], 0, v[66:67]
	global_load_lds_dwordx4 v[80:81], off
	s_mov_b32 m0, s37
	s_nop 0
	global_load_lds_dwordx4 v[148:149], off
	s_mov_b32 m0, s38
	s_nop 0
	global_load_lds_dwordx4 v[150:151], off
	s_waitcnt vmcnt(8)
	s_waitcnt lgkmcnt(0)
	s_barrier
	s_barrier
; #define PG8_STAGE(bufoff, gbase, voff) do { _Pragma("unroll") for (int _i = 0; _i < 2; ++_i) \
;         __builtin_amdgcn_global_load_lds((const unsigned*)((const char*)(gbase) + (voff)[_i]), (PG8_LAS unsigned*)(lds + (bufoff) + ldsw + _i * 8192), 16, 0, 0); } while (0)
; #define PG8_LDA(dst, b, h) do { _Pragma("unroll") for (int m = 0; m < 4; ++m) _Pragma("unroll") for (int k = 0; k < 2; ++k) dst[m][k] = *(const PG8_LAS bf16x8*)(lds + PG8_SA(b, h) + aoff + m * 2048 + k * 1024); } while (0)
; #define PG8_LDB(dst, b, h) do { _Pragma("unroll") for (int n = 0; n < 2; ++n) _Pragma("unroll") for (int k = 0; k < 2; ++k) dst[n][k] = *(const PG8_LAS bf16x8*)(lds + PG8_SB(b, h) + boff + n * 2048 + k * 1024); } while (0)
; #define PG8_MMA(ai, bj, At, Bt) do { __builtin_amdgcn_s_setprio(1); _Pragma("unroll") for (int m = 0; m < 4; ++m) _Pragma("unroll") for (int n = 0; n < 2; ++n) _Pragma("unroll") for (int k = 0; k < 2; ++k) \
;         acc[ai][bj][m][n] = __builtin_amdgcn_mfma_f32_16x16x32_bf16(Bt[n][k], At[m][k], acc[ai][bj][m][n], 0, 0, 0); __builtin_amdgcn_s_setprio(0); } while (0)
; #define PG8_WAIT_V(n) asm volatile("s_waitcnt vmcnt(" #n ")" ::: "memory")
; #define PG8_WAIT_L(n) asm volatile("s_waitcnt lgkmcnt(" #n ")" ::: "memory")
; #define PG8_BAR __builtin_amdgcn_s_barrier()
; #define PG8_SCHED __builtin_amdgcn_sched_barrier(0)
; template <class Epi, class Sched, bool ALIGN_EPI = false, bool SP2 = false, bool HALFM = false>
; __device__ __forceinline__ void gemm_phase(PG8_LAS unsigned char* lds, const Gemm g, const Sched& S, const Epi& E, const int tid_in) {
;     ...
;             PG8_LDB(B0, 1, 0); PG8_LDB(B1, 1, 1); PG8_SCHED; PG8_LDA(At, 1, 0); PG8_STAGE(PG8_SA(0, 1), a2 + hstep, voffA);
;             PG8_WAIT_V(8); PG8_WAIT_L(0); PG8_BAR; PG8_MMA(0, 0, At, B0); PG8_MMA(0, 1, At, B1); PG8_BAR; PG8_SCHED;
;             PG8_LDA(At, 1, 1); PG8_STAGE(PG8_SB(1, 0), b3, voffB); PG8_STAGE(PG8_SB(1, 1), b3 + hstep, voffB); PG8_STAGE(PG8_SA(1, 0), a3, voffA);
;             PG8_WAIT_V(8); PG8_WAIT_L(0); PG8_BAR; if constexpr (!HALFM) { PG8_MMA(1, 0, At, B0); PG8_MMA(1, 1, At, B1); } PG8_BAR; PG8_SCHED;
	s_add_i32 s49, 0, 0x18000
	v_add_u32_e32 v79, s49, v73
	s_add_i32 s50, 0, 0x1c000
	ds_read_b128 v[80:83], v79
	ds_read_b128 v[84:87], v79 offset:1024
	ds_read_b128 v[88:91], v79 offset:2048
	ds_read_b128 v[92:95], v79 offset:3072
	v_add_u32_e32 v79, s50, v73
	ds_read_b128 v[96:99], v79
	ds_read_b128 v[100:103], v79 offset:1024
	ds_read_b128 v[104:107], v79 offset:2048
	ds_read_b128 v[108:111], v79 offset:3072
	s_add_u32 s0, s28, 0x40000
	s_addc_u32 s1, s29, 0
	s_mov_b32 m0, s39
	v_lshl_add_u64 v[152:153], s[0:1], 0, v[0:1]
	ds_read_b128 v[112:115], v78 offset:32768
	ds_read_b128 v[116:119], v78 offset:33792
	ds_read_b128 v[120:123], v78 offset:34816
	ds_read_b128 v[124:127], v78 offset:35840
	ds_read_b128 v[132:135], v78 offset:36864
	ds_read_b128 v[136:139], v78 offset:37888
	ds_read_b128 v[140:143], v78 offset:38912
	ds_read_b128 v[144:147], v78 offset:39936
	global_load_lds_dwordx4 v[152:153], off
	v_lshl_add_u64 v[152:153], s[0:1], 0, v[66:67]
	s_mov_b32 m0, s40
	s_nop 0
	global_load_lds_dwordx4 v[152:153], off
	s_waitcnt vmcnt(8)
	s_waitcnt lgkmcnt(0)
	s_barrier
	s_setprio 1
	s_waitcnt lgkmcnt(0)
	v_mfma_f32_16x16x32_bf16 v[62:65], v[80:83], v[112:115], v[62:65]
	v_mfma_f32_16x16x32_bf16 v[58:61], v[88:91], v[112:115], v[58:61]
	v_mfma_f32_16x16x32_bf16 v[46:49], v[80:83], v[120:123], v[46:49]
	v_mfma_f32_16x16x32_bf16 v[42:45], v[88:91], v[120:123], v[42:45]
	v_mfma_f32_16x16x32_bf16 v[30:33], v[80:83], v[132:135], v[30:33]
	v_mfma_f32_16x16x32_bf16 v[26:29], v[88:91], v[132:135], v[26:29]
	v_mfma_f32_16x16x32_bf16 v[14:17], v[80:83], v[140:143], v[14:17]
	v_mfma_f32_16x16x32_bf16 v[10:13], v[88:91], v[140:143], v[10:13]
	v_mfma_f32_16x16x32_bf16 v[62:65], v[84:87], v[116:119], v[62:65]
	v_mfma_f32_16x16x32_bf16 v[58:61], v[92:95], v[116:119], v[58:61]
	v_mfma_f32_16x16x32_bf16 v[46:49], v[84:87], v[124:127], v[46:49]
	v_mfma_f32_16x16x32_bf16 v[42:45], v[92:95], v[124:127], v[42:45]
	v_mfma_f32_16x16x32_bf16 v[30:33], v[84:87], v[136:139], v[30:33]
	v_mfma_f32_16x16x32_bf16 v[26:29], v[92:95], v[136:139], v[26:29]
	v_mfma_f32_16x16x32_bf16 v[14:17], v[84:87], v[144:147], v[14:17]
	v_mfma_f32_16x16x32_bf16 v[10:13], v[92:95], v[144:147], v[10:13]
	v_mfma_f32_16x16x32_bf16 v[54:57], v[96:99], v[112:115], v[54:57]
	v_mfma_f32_16x16x32_bf16 v[50:53], v[104:107], v[112:115], v[50:53]
	v_mfma_f32_16x16x32_bf16 v[38:41], v[96:99], v[120:123], v[38:41]
	v_mfma_f32_16x16x32_bf16 v[34:37], v[104:107], v[120:123], v[34:37]
	v_mfma_f32_16x16x32_bf16 v[22:25], v[96:99], v[132:135], v[22:25]
	v_mfma_f32_16x16x32_bf16 v[18:21], v[104:107], v[132:135], v[18:21]
	v_mfma_f32_16x16x32_bf16 v[6:9], v[96:99], v[140:143], v[6:9]
	v_mfma_f32_16x16x32_bf16 v[2:5], v[104:107], v[140:143], v[2:5]
	v_mfma_f32_16x16x32_bf16 v[54:57], v[100:103], v[116:119], v[54:57]
	v_mfma_f32_16x16x32_bf16 v[50:53], v[108:111], v[116:119], v[50:53]
	v_mfma_f32_16x16x32_bf16 v[38:41], v[100:103], v[124:127], v[38:41]
	v_mfma_f32_16x16x32_bf16 v[34:37], v[108:111], v[124:127], v[34:37]
	v_mfma_f32_16x16x32_bf16 v[22:25], v[100:103], v[136:139], v[22:25]
	v_mfma_f32_16x16x32_bf16 v[18:21], v[108:111], v[136:139], v[18:21]
	v_mfma_f32_16x16x32_bf16 v[6:9], v[100:103], v[144:147], v[6:9]
	v_mfma_f32_16x16x32_bf16 v[2:5], v[108:111], v[144:147], v[2:5]
	s_setprio 0
	s_barrier
	s_add_i32 s0, s49, s36
	v_lshl_add_u64 v[70:71], v[70:71], 0, s[86:87]
	s_mov_b32 m0, s0
	s_nop 0
	global_load_lds_dwordx4 v[70:71], off
	s_add_i32 m0, s0, 0x2000
	s_add_u32 s0, s26, 0x40080
	v_lshl_add_u64 v[70:71], v[128:129], 0, s[86:87]
	s_addc_u32 s1, s27, 0
	s_add_i32 s26, s50, s36
	global_load_lds_dwordx4 v[70:71], off
	v_lshl_add_u64 v[70:71], s[0:1], 0, v[0:1]
	s_mov_b32 m0, s26
	s_nop 0
	global_load_lds_dwordx4 v[70:71], off
	v_lshl_add_u64 v[70:71], s[0:1], 0, v[66:67]
	s_add_i32 m0, s26, 0x2000
	s_nop 0
	global_load_lds_dwordx4 v[70:71], off
	v_lshl_add_u64 v[70:71], v[148:149], 0, s[86:87]
	s_mov_b32 m0, s41
	s_nop 0
	global_load_lds_dwordx4 v[70:71], off
	v_lshl_add_u64 v[70:71], v[150:151], 0, s[86:87]
	s_mov_b32 m0, s42
	s_nop 0
	global_load_lds_dwordx4 v[70:71], off
	s_waitcnt vmcnt(8)
	s_waitcnt lgkmcnt(0)
	s_barrier
	s_barrier
	s_add_i32 s48, s48, 2
	s_add_u32 s24, s24, 0x100
	s_addc_u32 s25, s25, 0
	s_add_u32 s46, s46, 0x100
	s_addc_u32 s47, s47, 0
	s_cmp_gt_u32 s48, 13
	s_cbranch_scc0 .LBB0_352
	s_and_b64 vcc, exec, s[10:11]
	s_cbranch_vccz .LBB0_355
	s_barrier

; #define PG8_STAGE(bufoff, gbase, voff) do { _Pragma("unroll") for (int _i = 0; _i < 2; ++_i) \
;         __builtin_amdgcn_global_load_lds((const unsigned*)((const char*)(gbase) + (voff)[_i]), (PG8_LAS unsigned*)(lds + (bufoff) + ldsw + _i * 8192), 16, 0, 0); } while (0)
; #define PG8_LDA(dst, b, h) do { _Pragma("unroll") for (int m = 0; m < 4; ++m) _Pragma("unroll") for (int k = 0; k < 2; ++k) dst[m][k] = *(const PG8_LAS bf16x8*)(lds + PG8_SA(b, h) + aoff + m * 2048 + k * 1024); } while (0)
; #define PG8_LDB(dst, b, h) do { _Pragma("unroll") for (int n = 0; n < 2; ++n) _Pragma("unroll") for (int k = 0; k < 2; ++k) dst[n][k] = *(const PG8_LAS bf16x8*)(lds + PG8_SB(b, h) + boff + n * 2048 + k * 1024); } while (0)
; #define PG8_MMA(ai, bj, At, Bt) do { __builtin_amdgcn_s_setprio(1); _Pragma("unroll") for (int m = 0; m < 4; ++m) _Pragma("unroll") for (int n = 0; n < 2; ++n) _Pragma("unroll") for (int k = 0; k < 2; ++k) \
;         acc[ai][bj][m][n] = __builtin_amdgcn_mfma_f32_16x16x32_bf16(Bt[n][k], At[m][k], acc[ai][bj][m][n], 0, 0, 0); __builtin_amdgcn_s_setprio(0); } while (0)
; #define PG8_WAIT_V(n) asm volatile("s_waitcnt vmcnt(" #n ")" ::: "memory")
; #define PG8_WAIT_L(n) asm volatile("s_waitcnt lgkmcnt(" #n ")" ::: "memory")
; #define PG8_BAR __builtin_amdgcn_s_barrier()
; #define PG8_SCHED __builtin_amdgcn_sched_barrier(0)
; template <class Epi, class Sched, bool ALIGN_EPI = false, bool SP2 = false, bool HALFM = false>
; __device__ __forceinline__ void gemm_phase(PG8_LAS unsigned char* lds, const Gemm g, const Sched& S, const Epi& E, const int tid_in) {
;     ...
;             PG8_LDB(B0, 0, 0); PG8_LDB(B1, 0, 1); PG8_SCHED; PG8_LDA(At, 0, 0); PG8_STAGE(PG8_SA(1, 1), a1 + hstep, voffA);
;             PG8_WAIT_V(8); PG8_WAIT_L(0); PG8_BAR; PG8_MMA(0, 0, At, B0); PG8_MMA(0, 1, At, B1); PG8_BAR; PG8_SCHED;
;             PG8_LDA(At, 0, 1); PG8_STAGE(PG8_SB(0, 0), b2, voffB); PG8_STAGE(PG8_SB(0, 1), b2 + hstep, voffB); PG8_STAGE(PG8_SA(0, 0), a2, voffA);
.LBB0_395:
	s_add_u32 s0, s22, 0xfffc0080
	s_addc_u32 s1, s23, -1
	s_add_i32 s47, 0, 0x10000
	s_cmp_eq_u32 s46, 12
	s_cselect_b32 s27, s15, s1
	s_cselect_b32 s26, s42, s0
	v_add_u32_e32 v140, s47, v155
	s_cselect_b32 s25, s13, s45
	s_cselect_b32 s24, s43, s44
	s_add_i32 s48, 0, 0x14000
	ds_read_b128 v[158:161], v140
	ds_read_b128 v[162:165], v140 offset:1024
	ds_read_b128 v[166:169], v140 offset:2048
	ds_read_b128 v[170:173], v140 offset:3072
	v_add_u32_e32 v140, s48, v155
	ds_read_b128 v[174:177], v140
	ds_read_b128 v[178:181], v140 offset:1024
	ds_read_b128 v[182:185], v140 offset:2048
	ds_read_b128 v[186:189], v140 offset:3072
	v_lshl_add_u64 v[140:141], s[22:23], 0, v[136:137]
	s_add_i32 m0, s35, 0xc000
	ds_read_b128 v[190:193], v157
	ds_read_b128 v[198:201], v157 offset:1024
	ds_read_b128 v[202:205], v157 offset:2048
	ds_read_b128 v[206:209], v157 offset:3072
	ds_read_b128 v[210:213], v157 offset:4096
	ds_read_b128 v[214:217], v157 offset:5120
	ds_read_b128 v[218:221], v157 offset:6144
	ds_read_b128 v[222:225], v157 offset:7168
	global_load_lds_dwordx4 v[140:141], off
	v_lshl_add_u64 v[140:141], s[22:23], 0, v[138:139]
	s_add_i32 m0, s35, 0xe000
	s_nop 0
	global_load_lds_dwordx4 v[140:141], off
	s_waitcnt vmcnt(8)
	s_waitcnt lgkmcnt(0)
	s_barrier
	s_setprio 1
	s_waitcnt lgkmcnt(0)
	v_mfma_f32_16x16x32_bf16 v[126:129], v[158:161], v[190:193], v[126:129]
	v_mfma_f32_16x16x32_bf16 v[118:121], v[166:169], v[190:193], v[118:121]
	v_mfma_f32_16x16x32_bf16 v[110:113], v[158:161], v[202:205], v[110:113]
	v_mfma_f32_16x16x32_bf16 v[102:105], v[166:169], v[202:205], v[102:105]
	v_mfma_f32_16x16x32_bf16 v[94:97], v[158:161], v[210:213], v[94:97]
	v_mfma_f32_16x16x32_bf16 v[86:89], v[166:169], v[210:213], v[86:89]
	v_mfma_f32_16x16x32_bf16 v[78:81], v[158:161], v[218:221], v[78:81]
	v_mfma_f32_16x16x32_bf16 v[70:73], v[166:169], v[218:221], v[70:73]
	v_mfma_f32_16x16x32_bf16 v[126:129], v[162:165], v[198:201], v[126:129]
	v_mfma_f32_16x16x32_bf16 v[118:121], v[170:173], v[198:201], v[118:121]
	v_mfma_f32_16x16x32_bf16 v[110:113], v[162:165], v[206:209], v[110:113]
	v_mfma_f32_16x16x32_bf16 v[102:105], v[170:173], v[206:209], v[102:105]
	v_mfma_f32_16x16x32_bf16 v[94:97], v[162:165], v[214:217], v[94:97]
	v_mfma_f32_16x16x32_bf16 v[86:89], v[170:173], v[214:217], v[86:89]
	v_mfma_f32_16x16x32_bf16 v[78:81], v[162:165], v[222:225], v[78:81]
	v_mfma_f32_16x16x32_bf16 v[70:73], v[170:173], v[222:225], v[70:73]
	v_mfma_f32_16x16x32_bf16 v[122:125], v[174:177], v[190:193], v[122:125]
	v_mfma_f32_16x16x32_bf16 v[114:117], v[182:185], v[190:193], v[114:117]
	v_mfma_f32_16x16x32_bf16 v[106:109], v[174:177], v[202:205], v[106:109]
	v_mfma_f32_16x16x32_bf16 v[98:101], v[182:185], v[202:205], v[98:101]
	v_mfma_f32_16x16x32_bf16 v[90:93], v[174:177], v[210:213], v[90:93]
	v_mfma_f32_16x16x32_bf16 v[82:85], v[182:185], v[210:213], v[82:85]
	v_mfma_f32_16x16x32_bf16 v[74:77], v[174:177], v[218:221], v[74:77]
	v_mfma_f32_16x16x32_bf16 v[66:69], v[182:185], v[218:221], v[66:69]
	v_mfma_f32_16x16x32_bf16 v[122:125], v[178:181], v[198:201], v[122:125]
	v_mfma_f32_16x16x32_bf16 v[114:117], v[186:189], v[198:201], v[114:117]
	v_mfma_f32_16x16x32_bf16 v[106:109], v[178:181], v[206:209], v[106:109]
	v_mfma_f32_16x16x32_bf16 v[98:101], v[186:189], v[206:209], v[98:101]
	v_mfma_f32_16x16x32_bf16 v[90:93], v[178:181], v[214:217], v[90:93]
	v_mfma_f32_16x16x32_bf16 v[82:85], v[186:189], v[214:217], v[82:85]
	v_mfma_f32_16x16x32_bf16 v[74:77], v[178:181], v[222:225], v[74:77]
	v_mfma_f32_16x16x32_bf16 v[66:69], v[186:189], v[222:225], v[66:69]
	s_setprio 0
	s_barrier
	s_add_i32 s0, s47, s31
	v_lshl_add_u64 v[140:141], s[24:25], 0, v[0:1]
	s_mov_b32 m0, s0
	ds_read_b128 v[190:193], v157 offset:16384
	ds_read_b128 v[198:201], v157 offset:17408
	ds_read_b128 v[202:205], v157 offset:18432
	ds_read_b128 v[206:209], v157 offset:19456
	ds_read_b128 v[210:213], v157 offset:20480
	ds_read_b128 v[214:217], v157 offset:21504
	ds_read_b128 v[218:221], v157 offset:22528
	ds_read_b128 v[222:225], v157 offset:23552
	global_load_lds_dwordx4 v[140:141], off
	s_add_i32 m0, s0, 0x2000
	s_add_u32 s0, s24, 0x40000
	v_lshl_add_u64 v[194:195], s[24:25], 0, v[134:135]
	s_addc_u32 s1, s25, 0
	s_add_i32 s47, s48, s31
	global_load_lds_dwordx4 v[194:195], off
	v_lshl_add_u64 v[226:227], s[0:1], 0, v[0:1]
	s_mov_b32 m0, s47
	v_lshl_add_u64 v[228:229], s[26:27], 0, v[132:133]
	global_load_lds_dwordx4 v[226:227], off
	v_lshl_add_u64 v[226:227], s[0:1], 0, v[134:135]
	s_add_i32 m0, s47, 0x2000
	s_nop 0
	global_load_lds_dwordx4 v[226:227], off
	v_lshl_add_u64 v[226:227], s[26:27], 0, v[130:131]
	s_mov_b32 m0, s35
	s_nop 0
	global_load_lds_dwordx4 v[226:227], off
	s_mov_b32 m0, s36
	s_nop 0
	global_load_lds_dwordx4 v[228:229], off
	s_waitcnt vmcnt(8)
	s_waitcnt lgkmcnt(0)
	s_barrier
; #define PG8_STAGE(bufoff, gbase, voff) do { _Pragma("unroll") for (int _i = 0; _i < 2; ++_i) \
;         __builtin_amdgcn_global_load_lds((const unsigned*)((const char*)(gbase) + (voff)[_i]), (PG8_LAS unsigned*)(lds + (bufoff) + ldsw + _i * 8192), 16, 0, 0); } while (0)
; #define PG8_LDA(dst, b, h) do { _Pragma("unroll") for (int m = 0; m < 4; ++m) _Pragma("unroll") for (int k = 0; k < 2; ++k) dst[m][k] = *(const PG8_LAS bf16x8*)(lds + PG8_SA(b, h) + aoff + m * 2048 + k * 1024); } while (0)
; #define PG8_LDB(dst, b, h) do { _Pragma("unroll") for (int n = 0; n < 2; ++n) _Pragma("unroll") for (int k = 0; k < 2; ++k) dst[n][k] = *(const PG8_LAS bf16x8*)(lds + PG8_SB(b, h) + boff + n * 2048 + k * 1024); } while (0)
; #define PG8_MMA(ai, bj, At, Bt) do { __builtin_amdgcn_s_setprio(1); _Pragma("unroll") for (int m = 0; m < 4; ++m) _Pragma("unroll") for (int n = 0; n < 2; ++n) _Pragma("unroll") for (int k = 0; k < 2; ++k) \
;         acc[ai][bj][m][n] = __builtin_amdgcn_mfma_f32_16x16x32_bf16(Bt[n][k], At[m][k], acc[ai][bj][m][n], 0, 0, 0); __builtin_amdgcn_s_setprio(0); } while (0)
; #define PG8_WAIT_V(n) asm volatile("s_waitcnt vmcnt(" #n ")" ::: "memory")
; #define PG8_WAIT_L(n) asm volatile("s_waitcnt lgkmcnt(" #n ")" ::: "memory")
; #define PG8_BAR __builtin_amdgcn_s_barrier()
; #define PG8_SCHED __builtin_amdgcn_sched_barrier(0)
; template <class Epi, class Sched, bool ALIGN_EPI = false, bool SP2 = false, bool HALFM = false>
; __device__ __forceinline__ void gemm_phase(PG8_LAS unsigned char* lds, const Gemm g, const Sched& S, const Epi& E, const int tid_in) {
;     ...
;             PG8_WAIT_V(8); PG8_WAIT_L(0); PG8_BAR; if constexpr (!HALFM) { PG8_MMA(1, 0, At, B0); PG8_MMA(1, 1, At, B1); } PG8_BAR; PG8_SCHED;
;             PG8_LDB(B0, 1, 0); PG8_LDB(B1, 1, 1); PG8_SCHED; PG8_LDA(At, 1, 0); PG8_STAGE(PG8_SA(0, 1), a2 + hstep, voffA);
;             PG8_WAIT_V(8); PG8_WAIT_L(0); PG8_BAR; PG8_MMA(0, 0, At, B0); PG8_MMA(0, 1, At, B1); PG8_BAR; PG8_SCHED;
	s_setprio 1
	s_waitcnt lgkmcnt(0)
	v_mfma_f32_16x16x32_bf16 v[62:65], v[158:161], v[190:193], v[62:65]
	v_mfma_f32_16x16x32_bf16 v[54:57], v[166:169], v[190:193], v[54:57]
	v_mfma_f32_16x16x32_bf16 v[46:49], v[158:161], v[202:205], v[46:49]
	v_mfma_f32_16x16x32_bf16 v[38:41], v[166:169], v[202:205], v[38:41]
	v_mfma_f32_16x16x32_bf16 v[30:33], v[158:161], v[210:213], v[30:33]
	v_mfma_f32_16x16x32_bf16 v[22:25], v[166:169], v[210:213], v[22:25]
	v_mfma_f32_16x16x32_bf16 v[14:17], v[158:161], v[218:221], v[14:17]
	v_mfma_f32_16x16x32_bf16 v[6:9], v[166:169], v[218:221], v[6:9]
	v_mfma_f32_16x16x32_bf16 v[62:65], v[162:165], v[198:201], v[62:65]
	v_mfma_f32_16x16x32_bf16 v[54:57], v[170:173], v[198:201], v[54:57]
	v_mfma_f32_16x16x32_bf16 v[46:49], v[162:165], v[206:209], v[46:49]
	v_mfma_f32_16x16x32_bf16 v[38:41], v[170:173], v[206:209], v[38:41]
	v_mfma_f32_16x16x32_bf16 v[30:33], v[162:165], v[214:217], v[30:33]
	v_mfma_f32_16x16x32_bf16 v[22:25], v[170:173], v[214:217], v[22:25]
	v_mfma_f32_16x16x32_bf16 v[14:17], v[162:165], v[222:225], v[14:17]
	v_mfma_f32_16x16x32_bf16 v[6:9], v[170:173], v[222:225], v[6:9]
	v_mfma_f32_16x16x32_bf16 v[58:61], v[174:177], v[190:193], v[58:61]
	v_mfma_f32_16x16x32_bf16 v[50:53], v[182:185], v[190:193], v[50:53]
	v_mfma_f32_16x16x32_bf16 v[42:45], v[174:177], v[202:205], v[42:45]
	v_mfma_f32_16x16x32_bf16 v[34:37], v[182:185], v[202:205], v[34:37]
	v_mfma_f32_16x16x32_bf16 v[26:29], v[174:177], v[210:213], v[26:29]
	v_mfma_f32_16x16x32_bf16 v[18:21], v[182:185], v[210:213], v[18:21]
	v_mfma_f32_16x16x32_bf16 v[10:13], v[174:177], v[218:221], v[10:13]
	v_mfma_f32_16x16x32_bf16 v[2:5], v[182:185], v[218:221], v[2:5]
	v_mfma_f32_16x16x32_bf16 v[58:61], v[178:181], v[198:201], v[58:61]
	v_mfma_f32_16x16x32_bf16 v[50:53], v[186:189], v[198:201], v[50:53]
	v_mfma_f32_16x16x32_bf16 v[42:45], v[178:181], v[206:209], v[42:45]
	v_mfma_f32_16x16x32_bf16 v[34:37], v[186:189], v[206:209], v[34:37]
	v_mfma_f32_16x16x32_bf16 v[26:29], v[178:181], v[214:217], v[26:29]
	v_mfma_f32_16x16x32_bf16 v[18:21], v[186:189], v[214:217], v[18:21]
	v_mfma_f32_16x16x32_bf16 v[10:13], v[178:181], v[222:225], v[10:13]
	v_mfma_f32_16x16x32_bf16 v[2:5], v[186:189], v[222:225], v[2:5]
	s_setprio 0
	s_barrier
	s_add_i32 s47, 0, 0x18000
	s_add_i32 s48, 0, 0x1c000
	v_add_u32_e32 v170, s47, v155
	v_add_u32_e32 v186, s48, v155
	ds_read_b128 v[158:161], v170
	ds_read_b128 v[162:165], v170 offset:1024
	ds_read_b128 v[166:169], v170 offset:2048
	ds_read_b128 v[170:173], v170 offset:3072
	ds_read_b128 v[174:177], v186
	ds_read_b128 v[178:181], v186 offset:1024
	ds_read_b128 v[182:185], v186 offset:2048
	ds_read_b128 v[186:189], v186 offset:3072
	s_add_u32 s0, s26, 0x40000
	s_addc_u32 s1, s27, 0
	s_mov_b32 m0, s37
	v_lshl_add_u64 v[230:231], s[0:1], 0, v[130:131]
	ds_read_b128 v[190:193], v157 offset:32768
	ds_read_b128 v[198:201], v157 offset:33792
	ds_read_b128 v[202:205], v157 offset:34816
	ds_read_b128 v[206:209], v157 offset:35840
	ds_read_b128 v[210:213], v157 offset:36864
	ds_read_b128 v[214:217], v157 offset:37888
	ds_read_b128 v[218:221], v157 offset:38912
	ds_read_b128 v[222:225], v157 offset:39936
	global_load_lds_dwordx4 v[230:231], off
	v_lshl_add_u64 v[230:231], s[0:1], 0, v[132:133]
	s_mov_b32 m0, s38
	s_nop 0
	global_load_lds_dwordx4 v[230:231], off
	s_waitcnt vmcnt(8)
	s_waitcnt lgkmcnt(0)
	s_barrier
	s_setprio 1
	s_waitcnt lgkmcnt(0)
	v_mfma_f32_16x16x32_bf16 v[126:129], v[158:161], v[190:193], v[126:129]
	v_mfma_f32_16x16x32_bf16 v[118:121], v[166:169], v[190:193], v[118:121]
	v_mfma_f32_16x16x32_bf16 v[110:113], v[158:161], v[202:205], v[110:113]
	v_mfma_f32_16x16x32_bf16 v[102:105], v[166:169], v[202:205], v[102:105]
	v_mfma_f32_16x16x32_bf16 v[94:97], v[158:161], v[210:213], v[94:97]
	v_mfma_f32_16x16x32_bf16 v[86:89], v[166:169], v[210:213], v[86:89]
	v_mfma_f32_16x16x32_bf16 v[78:81], v[158:161], v[218:221], v[78:81]
	v_mfma_f32_16x16x32_bf16 v[70:73], v[166:169], v[218:221], v[70:73]
	v_mfma_f32_16x16x32_bf16 v[126:129], v[162:165], v[198:201], v[126:129]
	v_mfma_f32_16x16x32_bf16 v[118:121], v[170:173], v[198:201], v[118:121]
	v_mfma_f32_16x16x32_bf16 v[110:113], v[162:165], v[206:209], v[110:113]
	v_mfma_f32_16x16x32_bf16 v[102:105], v[170:173], v[206:209], v[102:105]
	v_mfma_f32_16x16x32_bf16 v[94:97], v[162:165], v[214:217], v[94:97]
	v_mfma_f32_16x16x32_bf16 v[86:89], v[170:173], v[214:217], v[86:89]
	v_mfma_f32_16x16x32_bf16 v[78:81], v[162:165], v[222:225], v[78:81]
	v_mfma_f32_16x16x32_bf16 v[70:73], v[170:173], v[222:225], v[70:73]
	v_mfma_f32_16x16x32_bf16 v[122:125], v[174:177], v[190:193], v[122:125]
	v_mfma_f32_16x16x32_bf16 v[114:117], v[182:185], v[190:193], v[114:117]
	v_mfma_f32_16x16x32_bf16 v[106:109], v[174:177], v[202:205], v[106:109]
	v_mfma_f32_16x16x32_bf16 v[98:101], v[182:185], v[202:205], v[98:101]
	v_mfma_f32_16x16x32_bf16 v[90:93], v[174:177], v[210:213], v[90:93]
	v_mfma_f32_16x16x32_bf16 v[82:85], v[182:185], v[210:213], v[82:85]
	v_mfma_f32_16x16x32_bf16 v[74:77], v[174:177], v[218:221], v[74:77]
	v_mfma_f32_16x16x32_bf16 v[66:69], v[182:185], v[218:221], v[66:69]
	v_mfma_f32_16x16x32_bf16 v[122:125], v[178:181], v[198:201], v[122:125]
	v_mfma_f32_16x16x32_bf16 v[114:117], v[186:189], v[198:201], v[114:117]
	v_mfma_f32_16x16x32_bf16 v[106:109], v[178:181], v[206:209], v[106:109]
	v_mfma_f32_16x16x32_bf16 v[98:101], v[186:189], v[206:209], v[98:101]
	v_mfma_f32_16x16x32_bf16 v[90:93], v[178:181], v[214:217], v[90:93]
	v_mfma_f32_16x16x32_bf16 v[82:85], v[186:189], v[214:217], v[82:85]
	v_mfma_f32_16x16x32_bf16 v[74:77], v[178:181], v[222:225], v[74:77]
	v_mfma_f32_16x16x32_bf16 v[66:69], v[186:189], v[222:225], v[66:69]
	s_setprio 0
	s_barrier
; #define PG8_STAGE(bufoff, gbase, voff) do { _Pragma("unroll") for (int _i = 0; _i < 2; ++_i) \
;         __builtin_amdgcn_global_load_lds((const unsigned*)((const char*)(gbase) + (voff)[_i]), (PG8_LAS unsigned*)(lds + (bufoff) + ldsw + _i * 8192), 16, 0, 0); } while (0)
; #define PG8_LDA(dst, b, h) do { _Pragma("unroll") for (int m = 0; m < 4; ++m) _Pragma("unroll") for (int k = 0; k < 2; ++k) dst[m][k] = *(const PG8_LAS bf16x8*)(lds + PG8_SA(b, h) + aoff + m * 2048 + k * 1024); } while (0)
; #define PG8_MMA(ai, bj, At, Bt) do { __builtin_amdgcn_s_setprio(1); _Pragma("unroll") for (int m = 0; m < 4; ++m) _Pragma("unroll") for (int n = 0; n < 2; ++n) _Pragma("unroll") for (int k = 0; k < 2; ++k) \
;         acc[ai][bj][m][n] = __builtin_amdgcn_mfma_f32_16x16x32_bf16(Bt[n][k], At[m][k], acc[ai][bj][m][n], 0, 0, 0); __builtin_amdgcn_s_setprio(0); } while (0)
; #define PG8_WAIT_V(n) asm volatile("s_waitcnt vmcnt(" #n ")" ::: "memory")
; #define PG8_WAIT_L(n) asm volatile("s_waitcnt lgkmcnt(" #n ")" ::: "memory")
; #define PG8_BAR __builtin_amdgcn_s_barrier()
; #define PG8_SCHED __builtin_amdgcn_sched_barrier(0)
; template <class Epi, class Sched, bool ALIGN_EPI = false, bool SP2 = false, bool HALFM = false>
; __device__ __forceinline__ void gemm_phase(PG8_LAS unsigned char* lds, const Gemm g, const Sched& S, const Epi& E, const int tid_in) {
;     ...
;             PG8_LDA(At, 1, 1); PG8_STAGE(PG8_SB(1, 0), b3, voffB); PG8_STAGE(PG8_SB(1, 1), b3 + hstep, voffB); PG8_STAGE(PG8_SA(1, 0), a3, voffA);
;             PG8_WAIT_V(8); PG8_WAIT_L(0); PG8_BAR; if constexpr (!HALFM) { PG8_MMA(1, 0, At, B0); PG8_MMA(1, 1, At, B1); } PG8_BAR; PG8_SCHED;
	s_add_i32 s0, s47, s31
	v_lshl_add_u64 v[140:141], v[140:141], 0, s[86:87]
	s_mov_b32 m0, s0
	ds_read_b128 v[190:193], v157 offset:49152
	ds_read_b128 v[198:201], v157 offset:50176
	ds_read_b128 v[202:205], v157 offset:51200
	ds_read_b128 v[206:209], v157 offset:52224
	ds_read_b128 v[210:213], v157 offset:53248
	ds_read_b128 v[214:217], v157 offset:54272
	ds_read_b128 v[218:221], v157 offset:55296
	ds_read_b128 v[222:225], v157 offset:56320
	global_load_lds_dwordx4 v[140:141], off
	s_add_i32 m0, s0, 0x2000
	s_add_u32 s0, s24, 0x40080
	v_lshl_add_u64 v[140:141], v[194:195], 0, s[86:87]
	s_addc_u32 s1, s25, 0
	s_add_i32 s24, s48, s31
	global_load_lds_dwordx4 v[140:141], off
	v_lshl_add_u64 v[140:141], s[0:1], 0, v[0:1]
	s_mov_b32 m0, s24
	s_nop 0
	global_load_lds_dwordx4 v[140:141], off
	v_lshl_add_u64 v[140:141], s[0:1], 0, v[134:135]
	s_add_i32 m0, s24, 0x2000
	s_nop 0
	global_load_lds_dwordx4 v[140:141], off
	v_lshl_add_u64 v[140:141], v[226:227], 0, s[86:87]
	s_mov_b32 m0, s39
	s_nop 0
	global_load_lds_dwordx4 v[140:141], off
	v_lshl_add_u64 v[140:141], v[228:229], 0, s[86:87]
	s_mov_b32 m0, s40
	s_nop 0
	global_load_lds_dwordx4 v[140:141], off
	s_waitcnt vmcnt(8)
	s_waitcnt lgkmcnt(0)
	s_barrier
	s_setprio 1
	s_waitcnt lgkmcnt(0)
	v_mfma_f32_16x16x32_bf16 v[62:65], v[158:161], v[190:193], v[62:65]
	v_mfma_f32_16x16x32_bf16 v[54:57], v[166:169], v[190:193], v[54:57]
	v_mfma_f32_16x16x32_bf16 v[46:49], v[158:161], v[202:205], v[46:49]
	v_mfma_f32_16x16x32_bf16 v[38:41], v[166:169], v[202:205], v[38:41]
	v_mfma_f32_16x16x32_bf16 v[30:33], v[158:161], v[210:213], v[30:33]
	v_mfma_f32_16x16x32_bf16 v[22:25], v[166:169], v[210:213], v[22:25]
	v_mfma_f32_16x16x32_bf16 v[14:17], v[158:161], v[218:221], v[14:17]
	v_mfma_f32_16x16x32_bf16 v[6:9], v[166:169], v[218:221], v[6:9]
	v_mfma_f32_16x16x32_bf16 v[62:65], v[162:165], v[198:201], v[62:65]
	v_mfma_f32_16x16x32_bf16 v[54:57], v[170:173], v[198:201], v[54:57]
	v_mfma_f32_16x16x32_bf16 v[46:49], v[162:165], v[206:209], v[46:49]
	v_mfma_f32_16x16x32_bf16 v[38:41], v[170:173], v[206:209], v[38:41]
	v_mfma_f32_16x16x32_bf16 v[30:33], v[162:165], v[214:217], v[30:33]
	v_mfma_f32_16x16x32_bf16 v[22:25], v[170:173], v[214:217], v[22:25]
	v_mfma_f32_16x16x32_bf16 v[14:17], v[162:165], v[222:225], v[14:17]
	v_mfma_f32_16x16x32_bf16 v[6:9], v[170:173], v[222:225], v[6:9]
	v_mfma_f32_16x16x32_bf16 v[58:61], v[174:177], v[190:193], v[58:61]
	v_mfma_f32_16x16x32_bf16 v[50:53], v[182:185], v[190:193], v[50:53]
	v_mfma_f32_16x16x32_bf16 v[42:45], v[174:177], v[202:205], v[42:45]
	v_mfma_f32_16x16x32_bf16 v[34:37], v[182:185], v[202:205], v[34:37]
	v_mfma_f32_16x16x32_bf16 v[26:29], v[174:177], v[210:213], v[26:29]
	v_mfma_f32_16x16x32_bf16 v[18:21], v[182:185], v[210:213], v[18:21]
	v_mfma_f32_16x16x32_bf16 v[10:13], v[174:177], v[218:221], v[10:13]
	v_mfma_f32_16x16x32_bf16 v[2:5], v[182:185], v[218:221], v[2:5]
	v_mfma_f32_16x16x32_bf16 v[58:61], v[178:181], v[198:201], v[58:61]
	v_mfma_f32_16x16x32_bf16 v[50:53], v[186:189], v[198:201], v[50:53]
	v_mfma_f32_16x16x32_bf16 v[42:45], v[178:181], v[206:209], v[42:45]
	v_mfma_f32_16x16x32_bf16 v[34:37], v[186:189], v[206:209], v[34:37]
	v_mfma_f32_16x16x32_bf16 v[26:29], v[178:181], v[214:217], v[26:29]
	v_mfma_f32_16x16x32_bf16 v[18:21], v[186:189], v[214:217], v[18:21]
	v_mfma_f32_16x16x32_bf16 v[10:13], v[178:181], v[222:225], v[10:13]
	v_mfma_f32_16x16x32_bf16 v[2:5], v[186:189], v[222:225], v[2:5]
	s_setprio 0
	s_barrier
	s_add_i32 s46, s46, 2
	s_add_u32 s22, s22, 0x100
	s_addc_u32 s23, s23, 0
	s_add_u32 s44, s44, 0x100
	s_addc_u32 s45, s45, 0
	s_cmp_gt_u32 s46, 13
	s_cbranch_scc0 .LBB0_395
	s_and_b64 vcc, exec, s[10:11]
	s_cbranch_vccz .LBB0_398
	s_barrier

; #define PG8_STAGE(bufoff, gbase, voff) do { _Pragma("unroll") for (int _i = 0; _i < 2; ++_i) \
;         __builtin_amdgcn_global_load_lds((const unsigned*)((const char*)(gbase) + (voff)[_i]), (PG8_LAS unsigned*)(lds + (bufoff) + ldsw + _i * 8192), 16, 0, 0); } while (0)
; #define PG8_LDA(dst, b, h) do { _Pragma("unroll") for (int m = 0; m < 4; ++m) _Pragma("unroll") for (int k = 0; k < 2; ++k) dst[m][k] = *(const PG8_LAS bf16x8*)(lds + PG8_SA(b, h) + aoff + m * 2048 + k * 1024); } while (0)
; #define PG8_LDB(dst, b, h) do { _Pragma("unroll") for (int n = 0; n < 2; ++n) _Pragma("unroll") for (int k = 0; k < 2; ++k) dst[n][k] = *(const PG8_LAS bf16x8*)(lds + PG8_SB(b, h) + boff + n * 2048 + k * 1024); } while (0)
; #define PG8_MMA(ai, bj, At, Bt) do { __builtin_amdgcn_s_setprio(1); _Pragma("unroll") for (int m = 0; m < 4; ++m) _Pragma("unroll") for (int n = 0; n < 2; ++n) _Pragma("unroll") for (int k = 0; k < 2; ++k) \
;         acc[ai][bj][m][n] = __builtin_amdgcn_mfma_f32_16x16x32_bf16(Bt[n][k], At[m][k], acc[ai][bj][m][n], 0, 0, 0); __builtin_amdgcn_s_setprio(0); } while (0)
; #define PG8_WAIT_V(n) asm volatile("s_waitcnt vmcnt(" #n ")" ::: "memory")
; #define PG8_WAIT_L(n) asm volatile("s_waitcnt lgkmcnt(" #n ")" ::: "memory")
; #define PG8_BAR __builtin_amdgcn_s_barrier()
; #define PG8_SCHED __builtin_amdgcn_sched_barrier(0)
; template <class Epi, class Sched, bool ALIGN_EPI = false, bool SP2 = false, bool HALFM = false>
; __device__ __forceinline__ void gemm_phase(PG8_LAS unsigned char* lds, const Gemm g, const Sched& S, const Epi& E, const int tid_in) {
;     ...
;             PG8_LDB(B0, 0, 0); PG8_LDB(B1, 0, 1); PG8_SCHED; PG8_LDA(At, 0, 0); PG8_STAGE(PG8_SA(1, 1), a1 + hstep, voffA);
;             PG8_WAIT_V(8); PG8_WAIT_L(0); PG8_BAR; PG8_MMA(0, 0, At, B0); PG8_MMA(0, 1, At, B1); PG8_BAR; PG8_SCHED;
;             PG8_LDA(At, 0, 1); PG8_STAGE(PG8_SB(0, 0), b2, voffB); PG8_STAGE(PG8_SB(0, 1), b2 + hstep, voffB); PG8_STAGE(PG8_SA(0, 0), a2, voffA);
;             PG8_WAIT_V(8); PG8_WAIT_L(0); PG8_BAR; if constexpr (!HALFM) { PG8_MMA(1, 0, At, B0); PG8_MMA(1, 1, At, B1); } PG8_BAR; PG8_SCHED;
.LBB0_419:
	s_add_u32 s0, s22, 0xfffc0080
	s_addc_u32 s1, s23, -1
	s_add_i32 s47, 0, 0x10000
	s_cmp_eq_u32 s46, 12
	s_cselect_b32 s27, s15, s1
	s_cselect_b32 s26, s42, s0
	v_add_u32_e32 v70, s47, v73
	s_cselect_b32 s25, s13, s45
	s_cselect_b32 s24, s43, s44
	s_add_i32 s48, 0, 0x14000
	ds_read_b128 v[76:79], v70
	ds_read_b128 v[80:83], v70 offset:1024
	ds_read_b128 v[84:87], v70 offset:2048
	ds_read_b128 v[88:91], v70 offset:3072
	v_add_u32_e32 v70, s48, v73
	ds_read_b128 v[92:95], v70
	ds_read_b128 v[96:99], v70 offset:1024
	ds_read_b128 v[100:103], v70 offset:2048
	ds_read_b128 v[104:107], v70 offset:3072
	v_lshl_add_u64 v[70:71], s[22:23], 0, v[66:67]
	s_add_i32 m0, s35, 0xc000
	ds_read_b128 v[108:111], v75
	ds_read_b128 v[112:115], v75 offset:1024
	ds_read_b128 v[116:119], v75 offset:2048
	ds_read_b128 v[120:123], v75 offset:3072
	ds_read_b128 v[124:127], v75 offset:4096
	ds_read_b128 v[136:139], v75 offset:5120
	ds_read_b128 v[144:147], v75 offset:6144
	ds_read_b128 v[148:151], v75 offset:7168
	global_load_lds_dwordx4 v[70:71], off
	v_lshl_add_u64 v[70:71], s[22:23], 0, v[68:69]
	s_add_i32 m0, s35, 0xe000
	s_nop 0
	global_load_lds_dwordx4 v[70:71], off
	s_waitcnt vmcnt(8)
	s_waitcnt lgkmcnt(0)
	s_barrier
	s_setprio 1
	s_waitcnt lgkmcnt(0)
	v_mfma_f32_16x16x32_bf16 v[62:65], v[76:79], v[108:111], v[62:65]
	v_mfma_f32_16x16x32_bf16 v[54:57], v[84:87], v[108:111], v[54:57]
	v_mfma_f32_16x16x32_bf16 v[46:49], v[76:79], v[116:119], v[46:49]
	v_mfma_f32_16x16x32_bf16 v[38:41], v[84:87], v[116:119], v[38:41]
	v_mfma_f32_16x16x32_bf16 v[30:33], v[76:79], v[124:127], v[30:33]
	v_mfma_f32_16x16x32_bf16 v[22:25], v[84:87], v[124:127], v[22:25]
	v_mfma_f32_16x16x32_bf16 v[14:17], v[76:79], v[144:147], v[14:17]
	v_mfma_f32_16x16x32_bf16 v[6:9], v[84:87], v[144:147], v[6:9]
	v_mfma_f32_16x16x32_bf16 v[62:65], v[80:83], v[112:115], v[62:65]
	v_mfma_f32_16x16x32_bf16 v[54:57], v[88:91], v[112:115], v[54:57]
	v_mfma_f32_16x16x32_bf16 v[46:49], v[80:83], v[120:123], v[46:49]
	v_mfma_f32_16x16x32_bf16 v[38:41], v[88:91], v[120:123], v[38:41]
	v_mfma_f32_16x16x32_bf16 v[30:33], v[80:83], v[136:139], v[30:33]
	v_mfma_f32_16x16x32_bf16 v[22:25], v[88:91], v[136:139], v[22:25]
	v_mfma_f32_16x16x32_bf16 v[14:17], v[80:83], v[148:151], v[14:17]
	v_mfma_f32_16x16x32_bf16 v[6:9], v[88:91], v[148:151], v[6:9]
	v_mfma_f32_16x16x32_bf16 v[58:61], v[92:95], v[108:111], v[58:61]
	v_mfma_f32_16x16x32_bf16 v[50:53], v[100:103], v[108:111], v[50:53]
	v_mfma_f32_16x16x32_bf16 v[42:45], v[92:95], v[116:119], v[42:45]
	v_mfma_f32_16x16x32_bf16 v[34:37], v[100:103], v[116:119], v[34:37]
	v_mfma_f32_16x16x32_bf16 v[26:29], v[92:95], v[124:127], v[26:29]
	v_mfma_f32_16x16x32_bf16 v[18:21], v[100:103], v[124:127], v[18:21]
	v_mfma_f32_16x16x32_bf16 v[10:13], v[92:95], v[144:147], v[10:13]
	v_mfma_f32_16x16x32_bf16 v[2:5], v[100:103], v[144:147], v[2:5]
	v_mfma_f32_16x16x32_bf16 v[58:61], v[96:99], v[112:115], v[58:61]
	v_mfma_f32_16x16x32_bf16 v[50:53], v[104:107], v[112:115], v[50:53]
	v_mfma_f32_16x16x32_bf16 v[42:45], v[96:99], v[120:123], v[42:45]
	v_mfma_f32_16x16x32_bf16 v[34:37], v[104:107], v[120:123], v[34:37]
	v_mfma_f32_16x16x32_bf16 v[26:29], v[96:99], v[136:139], v[26:29]
	v_mfma_f32_16x16x32_bf16 v[18:21], v[104:107], v[136:139], v[18:21]
	v_mfma_f32_16x16x32_bf16 v[10:13], v[96:99], v[148:151], v[10:13]
	v_mfma_f32_16x16x32_bf16 v[2:5], v[104:107], v[148:151], v[2:5]
	s_setprio 0
	s_barrier
	s_add_i32 s0, s47, s34
	v_lshl_add_u64 v[70:71], s[24:25], 0, v[0:1]
	s_mov_b32 m0, s0
	v_lshl_add_u64 v[128:129], s[24:25], 0, v[134:135]
	global_load_lds_dwordx4 v[70:71], off
	s_add_i32 m0, s0, 0x2000
	s_add_u32 s0, s24, 0x40000
	s_addc_u32 s1, s25, 0
	s_add_i32 s47, s48, s34
	global_load_lds_dwordx4 v[128:129], off
	v_lshl_add_u64 v[76:77], s[0:1], 0, v[0:1]
	s_mov_b32 m0, s47
	v_lshl_add_u64 v[140:141], s[26:27], 0, v[130:131]
	global_load_lds_dwordx4 v[76:77], off
	v_lshl_add_u64 v[76:77], s[0:1], 0, v[134:135]
	s_add_i32 m0, s47, 0x2000
	v_lshl_add_u64 v[152:153], s[26:27], 0, v[132:133]
	global_load_lds_dwordx4 v[76:77], off
	s_mov_b32 m0, s35
	s_nop 0
	global_load_lds_dwordx4 v[140:141], off
	s_mov_b32 m0, s36
	s_nop 0
	global_load_lds_dwordx4 v[152:153], off
	s_waitcnt vmcnt(8)
	s_waitcnt lgkmcnt(0)
	s_barrier
	s_barrier
; #define PG8_STAGE(bufoff, gbase, voff) do { _Pragma("unroll") for (int _i = 0; _i < 2; ++_i) \
;         __builtin_amdgcn_global_load_lds((const unsigned*)((const char*)(gbase) + (voff)[_i]), (PG8_LAS unsigned*)(lds + (bufoff) + ldsw + _i * 8192), 16, 0, 0); } while (0)
; #define PG8_LDA(dst, b, h) do { _Pragma("unroll") for (int m = 0; m < 4; ++m) _Pragma("unroll") for (int k = 0; k < 2; ++k) dst[m][k] = *(const PG8_LAS bf16x8*)(lds + PG8_SA(b, h) + aoff + m * 2048 + k * 1024); } while (0)
; #define PG8_LDB(dst, b, h) do { _Pragma("unroll") for (int n = 0; n < 2; ++n) _Pragma("unroll") for (int k = 0; k < 2; ++k) dst[n][k] = *(const PG8_LAS bf16x8*)(lds + PG8_SB(b, h) + boff + n * 2048 + k * 1024); } while (0)
; #define PG8_MMA(ai, bj, At, Bt) do { __builtin_amdgcn_s_setprio(1); _Pragma("unroll") for (int m = 0; m < 4; ++m) _Pragma("unroll") for (int n = 0; n < 2; ++n) _Pragma("unroll") for (int k = 0; k < 2; ++k) \
;         acc[ai][bj][m][n] = __builtin_amdgcn_mfma_f32_16x16x32_bf16(Bt[n][k], At[m][k], acc[ai][bj][m][n], 0, 0, 0); __builtin_amdgcn_s_setprio(0); } while (0)
; #define PG8_WAIT_V(n) asm volatile("s_waitcnt vmcnt(" #n ")" ::: "memory")
; #define PG8_WAIT_L(n) asm volatile("s_waitcnt lgkmcnt(" #n ")" ::: "memory")
; #define PG8_BAR __builtin_amdgcn_s_barrier()
; #define PG8_SCHED __builtin_amdgcn_sched_barrier(0)
; template <class Epi, class Sched, bool ALIGN_EPI = false, bool SP2 = false, bool HALFM = false>
; __device__ __forceinline__ void gemm_phase(PG8_LAS unsigned char* lds, const Gemm g, const Sched& S, const Epi& E, const int tid_in) {
;     ...
;             PG8_LDB(B0, 1, 0); PG8_LDB(B1, 1, 1); PG8_SCHED; PG8_LDA(At, 1, 0); PG8_STAGE(PG8_SA(0, 1), a2 + hstep, voffA);
;             PG8_WAIT_V(8); PG8_WAIT_L(0); PG8_BAR; PG8_MMA(0, 0, At, B0); PG8_MMA(0, 1, At, B1); PG8_BAR; PG8_SCHED;
;             PG8_LDA(At, 1, 1); PG8_STAGE(PG8_SB(1, 0), b3, voffB); PG8_STAGE(PG8_SB(1, 1), b3 + hstep, voffB); PG8_STAGE(PG8_SA(1, 0), a3, voffA);
;             PG8_WAIT_V(8); PG8_WAIT_L(0); PG8_BAR; if constexpr (!HALFM) { PG8_MMA(1, 0, At, B0); PG8_MMA(1, 1, At, B1); } PG8_BAR; PG8_SCHED;
	s_add_i32 s47, 0, 0x18000
	s_add_i32 s48, 0, 0x1c000
	v_add_u32_e32 v88, s47, v73
	v_add_u32_e32 v104, s48, v73
	ds_read_b128 v[76:79], v88
	ds_read_b128 v[80:83], v88 offset:1024
	ds_read_b128 v[84:87], v88 offset:2048
	ds_read_b128 v[88:91], v88 offset:3072
	ds_read_b128 v[92:95], v104
	ds_read_b128 v[96:99], v104 offset:1024
	ds_read_b128 v[100:103], v104 offset:2048
	ds_read_b128 v[104:107], v104 offset:3072
	s_add_u32 s0, s26, 0x40000
	s_addc_u32 s1, s27, 0
	s_mov_b32 m0, s37
	v_lshl_add_u64 v[154:155], s[0:1], 0, v[130:131]
	ds_read_b128 v[108:111], v75 offset:32768
	ds_read_b128 v[112:115], v75 offset:33792
	ds_read_b128 v[116:119], v75 offset:34816
	ds_read_b128 v[120:123], v75 offset:35840
	ds_read_b128 v[124:127], v75 offset:36864
	ds_read_b128 v[136:139], v75 offset:37888
	ds_read_b128 v[144:147], v75 offset:38912
	ds_read_b128 v[148:151], v75 offset:39936
	global_load_lds_dwordx4 v[154:155], off
	v_lshl_add_u64 v[154:155], s[0:1], 0, v[132:133]
	s_mov_b32 m0, s38
	s_nop 0
	global_load_lds_dwordx4 v[154:155], off
	s_waitcnt vmcnt(8)
	s_waitcnt lgkmcnt(0)
	s_barrier
	s_setprio 1
	s_waitcnt lgkmcnt(0)
	v_mfma_f32_16x16x32_bf16 v[62:65], v[76:79], v[108:111], v[62:65]
	v_mfma_f32_16x16x32_bf16 v[54:57], v[84:87], v[108:111], v[54:57]
	v_mfma_f32_16x16x32_bf16 v[46:49], v[76:79], v[116:119], v[46:49]
	v_mfma_f32_16x16x32_bf16 v[38:41], v[84:87], v[116:119], v[38:41]
	v_mfma_f32_16x16x32_bf16 v[30:33], v[76:79], v[124:127], v[30:33]
	v_mfma_f32_16x16x32_bf16 v[22:25], v[84:87], v[124:127], v[22:25]
	v_mfma_f32_16x16x32_bf16 v[14:17], v[76:79], v[144:147], v[14:17]
	v_mfma_f32_16x16x32_bf16 v[6:9], v[84:87], v[144:147], v[6:9]
	v_mfma_f32_16x16x32_bf16 v[62:65], v[80:83], v[112:115], v[62:65]
	v_mfma_f32_16x16x32_bf16 v[54:57], v[88:91], v[112:115], v[54:57]
	v_mfma_f32_16x16x32_bf16 v[46:49], v[80:83], v[120:123], v[46:49]
	v_mfma_f32_16x16x32_bf16 v[38:41], v[88:91], v[120:123], v[38:41]
	v_mfma_f32_16x16x32_bf16 v[30:33], v[80:83], v[136:139], v[30:33]
	v_mfma_f32_16x16x32_bf16 v[22:25], v[88:91], v[136:139], v[22:25]
	v_mfma_f32_16x16x32_bf16 v[14:17], v[80:83], v[148:151], v[14:17]
	v_mfma_f32_16x16x32_bf16 v[6:9], v[88:91], v[148:151], v[6:9]
	v_mfma_f32_16x16x32_bf16 v[58:61], v[92:95], v[108:111], v[58:61]
	v_mfma_f32_16x16x32_bf16 v[50:53], v[100:103], v[108:111], v[50:53]
	v_mfma_f32_16x16x32_bf16 v[42:45], v[92:95], v[116:119], v[42:45]
	v_mfma_f32_16x16x32_bf16 v[34:37], v[100:103], v[116:119], v[34:37]
	v_mfma_f32_16x16x32_bf16 v[26:29], v[92:95], v[124:127], v[26:29]
	v_mfma_f32_16x16x32_bf16 v[18:21], v[100:103], v[124:127], v[18:21]
	v_mfma_f32_16x16x32_bf16 v[10:13], v[92:95], v[144:147], v[10:13]
	v_mfma_f32_16x16x32_bf16 v[2:5], v[100:103], v[144:147], v[2:5]
	v_mfma_f32_16x16x32_bf16 v[58:61], v[96:99], v[112:115], v[58:61]
	v_mfma_f32_16x16x32_bf16 v[50:53], v[104:107], v[112:115], v[50:53]
	v_mfma_f32_16x16x32_bf16 v[42:45], v[96:99], v[120:123], v[42:45]
	v_mfma_f32_16x16x32_bf16 v[34:37], v[104:107], v[120:123], v[34:37]
	v_mfma_f32_16x16x32_bf16 v[26:29], v[96:99], v[136:139], v[26:29]
	v_mfma_f32_16x16x32_bf16 v[18:21], v[104:107], v[136:139], v[18:21]
	v_mfma_f32_16x16x32_bf16 v[10:13], v[96:99], v[148:151], v[10:13]
	v_mfma_f32_16x16x32_bf16 v[2:5], v[104:107], v[148:151], v[2:5]
	s_setprio 0
	s_barrier
	s_add_i32 s0, s47, s34
	v_lshl_add_u64 v[70:71], v[70:71], 0, s[86:87]
	s_mov_b32 m0, s0
	s_nop 0
	global_load_lds_dwordx4 v[70:71], off
	s_add_i32 m0, s0, 0x2000
	s_add_u32 s0, s24, 0x40080
	v_lshl_add_u64 v[70:71], v[128:129], 0, s[86:87]
	s_addc_u32 s1, s25, 0
	s_add_i32 s24, s48, s34
	global_load_lds_dwordx4 v[70:71], off
	v_lshl_add_u64 v[70:71], s[0:1], 0, v[0:1]
	s_mov_b32 m0, s24
	s_nop 0
	global_load_lds_dwordx4 v[70:71], off
	v_lshl_add_u64 v[70:71], s[0:1], 0, v[134:135]
	s_add_i32 m0, s24, 0x2000
	s_nop 0
	global_load_lds_dwordx4 v[70:71], off
	v_lshl_add_u64 v[70:71], v[140:141], 0, s[86:87]
	s_mov_b32 m0, s39
	s_nop 0
	global_load_lds_dwordx4 v[70:71], off
	v_lshl_add_u64 v[70:71], v[152:153], 0, s[86:87]
	s_mov_b32 m0, s40
	s_nop 0
	global_load_lds_dwordx4 v[70:71], off
	s_waitcnt vmcnt(8)
	s_waitcnt lgkmcnt(0)
	s_barrier
	s_barrier
	s_add_i32 s46, s46, 2
	s_add_u32 s22, s22, 0x100
	s_addc_u32 s23, s23, 0
	s_add_u32 s44, s44, 0x100
	s_addc_u32 s45, s45, 0
	s_cmp_gt_u32 s46, 13
	s_cbranch_scc0 .LBB0_419
	s_and_b64 vcc, exec, s[10:11]
	s_cbranch_vccz .LBB0_422
	s_barrier

; #define LAS __attribute__((address_space(3)))
; __device__ __forceinline__ float xh_max(float v) { auto rr = __builtin_amdgcn_permlane32_swap(__float_as_uint(v), __float_as_uint(v), false, false); return fmaxf(__uint_as_float(rr[0]), __uint_as_float(rr[1])); }
; #define SCHED_BAR() __builtin_amdgcn_sched_barrier(0)
; __device__ __forceinline__ void sm_fast2(f32x16& s, f32x16& t, float c, float& m, float& l, f32x16 (&O)[2]) {
;     float a0 = fmaxf(fmaxf(s[0], s[1]), fmaxf(s[2], s[3])), a1 = fmaxf(fmaxf(s[4], s[5]), fmaxf(s[6], s[7]));
;     float a2 = fmaxf(fmaxf(s[8], s[9]), fmaxf(s[10], s[11])), a3 = fmaxf(fmaxf(s[12], s[13]), fmaxf(s[14], s[15]));
;     float b0 = fmaxf(fmaxf(t[0], t[1]), fmaxf(t[2], t[3])), b1 = fmaxf(fmaxf(t[4], t[5]), fmaxf(t[6], t[7]));
;     float b2 = fmaxf(fmaxf(t[8], t[9]), fmaxf(t[10], t[11])), b3 = fmaxf(fmaxf(t[12], t[13]), fmaxf(t[14], t[15]));
;     const float tmax = xh_max(fmaxf(fmaxf(fmaxf(a0, a1), fmaxf(a2, a3)), fmaxf(fmaxf(b0, b1), fmaxf(b2, b3))));
;     const float cand = tmax * c; const float mn = (cand > m + 8.0f) ? cand : m;
; template <int NKS, int KP, class MaskA, class MaskB>
; __device__ __forceinline__ void pair_tiles(LAS const unsigned char* ia, LAS const unsigned char* ib, int c, int h, const bf16x8 (&qf)[NKS], float cc, float& m, float& l, f32x16 (&O)[2], MaskA maskA, MaskB maskB) {
;     LAS const unsigned char* ka = ia + c * KP + 16 * h; LAS const unsigned char* va = ia + 64 * KP + c * KV_VP + 8 * h;
;     LAS const unsigned char* kb = ib + c * KP + 16 * h; LAS const unsigned char* vb = ib + 64 * KP + c * KV_VP + 8 * h;
;     bf16x8 kf[NKS], kg[NKS];
;     load_k<NKS>(ka, kf); load_k<NKS>(ka + 32 * KP, kg); SCHED_BAR();
;     f32x16 sa = mma_qk<NKS>(kf, qf), ta = mma_qk<NKS>(kg, qf);
;     load_k<NKS>(kb, kf); load_k<NKS>(kb + 32 * KP, kg); SCHED_BAR();
;     f32x16 sb = mma_qk<NKS>(kf, qf), tb = mma_qk<NKS>(kg, qf);
;     bf16x8 vf[2][2], vg[2][2]; load_v(va, vf); load_v(va + 64, vg); SCHED_BAR();
;     maskA(sa, ta); sm_fast2(sa, ta, cc, m, l, O);
.LBB0_803:
	s_add_i32 s0, s24, 64
	s_cmp_gt_i32 s0, s21
	s_cselect_b64 s[14:15], -1, 0
	s_or_b64 s[14:15], s[12:13], s[14:15]
	v_add_u32_e32 v2, v15, v208
	s_and_b64 vcc, exec, s[14:15]
	v_add_u32_e32 v14, v2, v184
	s_cbranch_vccnz .LBB0_811
	v_add3_u32 v176, v15, v206, v207
	ds_read_b128 v[2:5], v176
	ds_read_b128 v[6:9], v176 offset:32
	ds_read_b128 v[10:13], v176 offset:64
	ds_read_b128 v[64:67], v176 offset:96
	ds_read_b128 v[68:71], v176 offset:128
	ds_read_b128 v[72:75], v176 offset:160
	ds_read_b128 v[76:79], v176 offset:6656
	ds_read_b128 v[80:83], v176 offset:6688
	ds_read_b128 v[84:87], v176 offset:6720
	ds_read_b128 v[88:91], v176 offset:6752
	ds_read_b128 v[92:95], v176 offset:6784
	ds_read_b128 v[160:163], v176 offset:6816
	s_setprio 1
	s_waitcnt lgkmcnt(11)
	v_mfma_f32_32x32x16_bf16 v[48:63], v[2:5], v[112:115], 0
	s_waitcnt lgkmcnt(10)
	v_mfma_f32_32x32x16_bf16 v[48:63], v[6:9], v[116:119], v[48:63]
	s_waitcnt lgkmcnt(9)
	v_mfma_f32_32x32x16_bf16 v[48:63], v[10:13], v[120:123], v[48:63]
	s_waitcnt lgkmcnt(8)
	v_mfma_f32_32x32x16_bf16 v[48:63], v[64:67], v[124:127], v[48:63]
	s_waitcnt lgkmcnt(7)
	v_mfma_f32_32x32x16_bf16 v[48:63], v[68:71], v[128:131], v[48:63]
	s_waitcnt lgkmcnt(6)
	v_mfma_f32_32x32x16_bf16 v[48:63], v[72:75], v[132:135], v[48:63]
	s_waitcnt lgkmcnt(5)
	v_mfma_f32_32x32x16_bf16 v[96:111], v[76:79], v[112:115], 0
	s_waitcnt lgkmcnt(4)
	v_mfma_f32_32x32x16_bf16 v[96:111], v[80:83], v[116:119], v[96:111]
	s_waitcnt lgkmcnt(3)
	v_mfma_f32_32x32x16_bf16 v[96:111], v[84:87], v[120:123], v[96:111]
	s_waitcnt lgkmcnt(2)
	v_mfma_f32_32x32x16_bf16 v[96:111], v[88:91], v[124:127], v[96:111]
	s_waitcnt lgkmcnt(1)
	v_mfma_f32_32x32x16_bf16 v[96:111], v[92:95], v[128:131], v[96:111]
	s_waitcnt lgkmcnt(0)
	v_mfma_f32_32x32x16_bf16 v[96:111], v[160:163], v[132:135], v[96:111]
	s_setprio 0
	ds_read_b128 v[2:5], v176 offset:22016
	ds_read_b128 v[6:9], v176 offset:22048
	ds_read_b128 v[10:13], v176 offset:22080
	ds_read_b128 v[80:83], v176 offset:22112
	ds_read_b128 v[84:87], v176 offset:22144
	ds_read_b128 v[88:91], v176 offset:22176
	ds_read_b128 v[92:95], v176 offset:28672
	ds_read_b128 v[160:163], v176 offset:28704
	ds_read_b128 v[164:167], v176 offset:28736
	ds_read_b128 v[168:171], v176 offset:28768
	ds_read_b128 v[172:175], v176 offset:28800
	ds_read_b128 v[176:179], v176 offset:28832
	s_setprio 1
	s_waitcnt lgkmcnt(11)
	v_mfma_f32_32x32x16_bf16 v[64:79], v[2:5], v[112:115], 0
	s_waitcnt lgkmcnt(10)
	v_mfma_f32_32x32x16_bf16 v[64:79], v[6:9], v[116:119], v[64:79]
	s_waitcnt lgkmcnt(9)
	v_mfma_f32_32x32x16_bf16 v[64:79], v[10:13], v[120:123], v[64:79]
	s_waitcnt lgkmcnt(8)
	v_mfma_f32_32x32x16_bf16 v[64:79], v[80:83], v[124:127], v[64:79]
	s_waitcnt lgkmcnt(7)
	v_mfma_f32_32x32x16_bf16 v[64:79], v[84:87], v[128:131], v[64:79]
	s_waitcnt lgkmcnt(6)
	v_mfma_f32_32x32x16_bf16 v[64:79], v[88:91], v[132:135], v[64:79]
	s_waitcnt lgkmcnt(5)
	v_mfma_f32_32x32x16_bf16 v[80:95], v[92:95], v[112:115], 0
	s_waitcnt lgkmcnt(4)
	v_mfma_f32_32x32x16_bf16 v[80:95], v[160:163], v[116:119], v[80:95]
	s_waitcnt lgkmcnt(3)
	v_mfma_f32_32x32x16_bf16 v[80:95], v[164:167], v[120:123], v[80:95]
	s_waitcnt lgkmcnt(2)
	v_mfma_f32_32x32x16_bf16 v[80:95], v[168:171], v[124:127], v[80:95]
	s_waitcnt lgkmcnt(1)
	v_mfma_f32_32x32x16_bf16 v[80:95], v[172:175], v[128:131], v[80:95]
	s_waitcnt lgkmcnt(0)
	v_mfma_f32_32x32x16_bf16 v[80:95], v[176:179], v[132:135], v[80:95]
	s_setprio 0
	v_add_u32_e32 v2, 0x3000, v14
	v_add_u32_e32 v3, 0x4000, v14
	ds_read2_b64 v[176:179], v2 offset0:128 offset1:130
	ds_read2_b64 v[172:175], v2 offset0:132 offset1:134
	ds_read2_b64 v[168:171], v3 offset0:160 offset1:162
	ds_read2_b64 v[164:167], v3 offset0:164 offset1:166
	ds_read2_b64 v[160:163], v2 offset0:136 offset1:138
	ds_read2_b64 v[10:13], v2 offset0:140 offset1:142
	ds_read2_b64 v[6:9], v3 offset0:168 offset1:170
	ds_read2_b64 v[2:5], v3 offset0:172 offset1:174
	v_max_f32_e32 v180, v49, v49
	v_max_f32_e32 v181, v48, v48
	v_max_f32_e32 v180, v181, v180
	v_max_f32_e32 v181, v51, v51
	v_max_f32_e32 v182, v50, v50
	v_max_f32_e32 v181, v182, v181
	v_max_f32_e32 v182, v55, v55
	v_max_f32_e32 v183, v54, v54
	v_max_f32_e32 v182, v183, v182
	v_max_f32_e32 v183, v57, v57
	v_max_f32_e32 v194, v56, v56
	v_max_f32_e32 v183, v194, v183
	v_max_f32_e32 v194, v59, v59
	v_max_f32_e32 v195, v58, v58
	v_max_f32_e32 v194, v195, v194
	v_max_f32_e32 v195, v63, v63
	v_max_f32_e32 v196, v62, v62
	v_max_f32_e32 v195, v196, v195
	v_max_f32_e32 v196, v99, v99
	v_max_f32_e32 v198, v98, v98
	v_max_f32_e32 v196, v198, v196
	v_max_f32_e32 v198, v103, v103
	v_max_f32_e32 v199, v102, v102
	v_max_f32_e32 v198, v199, v198
	v_max_f32_e32 v199, v105, v105
	v_max_f32_e32 v200, v104, v104
	v_max_f32_e32 v199, v200, v199
	v_max_f32_e32 v200, v107, v107
	v_max_f32_e32 v201, v106, v106
	v_max_f32_e32 v200, v201, v200
	v_max_f32_e32 v201, v111, v111
	v_max_f32_e32 v202, v110, v110
	v_max_f32_e32 v201, v202, v201
	v_max3_f32 v182, v52, v53, v182
	v_max3_f32 v201, v108, v109, v201
	v_max3_f32 v195, v60, v61, v195
	v_max3_f32 v196, v96, v97, v196
	v_max3_f32 v198, v100, v101, v198
	v_max3_f32 v180, v180, v181, v182
	v_max3_f32 v182, v199, v200, v201
	v_max3_f32 v181, v183, v194, v195
	v_max3_f32 v182, v196, v198, v182
	v_max3_f32 v180, v180, v181, v182
	v_mov_b32_e32 v181, v180
	s_nop 1
	v_permlane32_swap_b32_e32 v180, v181
	v_max_f32_e32 v181, v181, v181
	v_max_f32_e32 v180, v180, v180
	v_max_f32_e32 v180, v180, v181
	v_mul_f32_e32 v180, 0x3e16c740, v180
	v_add_f32_e32 v181, 0x41000000, v243
	v_cmp_gt_f32_e32 vcc, v180, v181
	v_mov_b32_e32 v242, v235
	s_nop 0
	v_cndmask_b32_e32 v244, v243, v180, vcc
; __device__ __forceinline__ float xh_sum(float v) { auto rr = __builtin_amdgcn_permlane32_swap(__float_as_uint(v), __float_as_uint(v), false, false); return __uint_as_float(rr[0]) + __uint_as_float(rr[1]); }
; __device__ __forceinline__ void sm_fast2(f32x16& s, f32x16& t, float c, float& m, float& l, f32x16 (&O)[2]) {
;     ...
;     float p0 = 0.f, p1 = 0.f, p2 = 0.f, p3 = 0.f;
; #pragma unroll
;     for (int r = 0; r < 16; r += 2) {
;         const float e0 = __builtin_amdgcn_exp2f(fmaf(s[r], c, -mn)), e1 = __builtin_amdgcn_exp2f(fmaf(s[r + 1], c, -mn));
;         const float e2 = __builtin_amdgcn_exp2f(fmaf(t[r], c, -mn)), e3 = __builtin_amdgcn_exp2f(fmaf(t[r + 1], c, -mn));
;         s[r] = e0; s[r + 1] = e1; t[r] = e2; t[r + 1] = e3; p0 += e0; p1 += e1; p2 += e2; p3 += e3; }
;     const float ps = xh_sum((p0 + p1) + (p2 + p3));
;     if (__ballot(mn > m) != 0ull) { const float alpha = __builtin_amdgcn_exp2f(m - mn); l *= alpha; O[0] = O[0] * alpha; O[1] = O[1] * alpha; }
;     l += ps; m = mn;
	v_fma_f32 v52, v52, s96, -v244
	v_exp_f32_e32 v204, v52
	v_fma_f32 v52, v53, s96, -v244
	v_exp_f32_e32 v205, v52
	v_fma_f32 v52, v100, s96, -v244
	v_exp_f32_e32 v250, v52
	v_fma_f32 v52, v101, s96, -v244
	v_exp_f32_e32 v251, v52
	v_fma_f32 v52, v54, s96, -v244
	v_exp_f32_e32 v180, v52
	v_fma_f32 v52, v55, s96, -v244
	v_exp_f32_e32 v181, v52
	v_fma_f32 v52, v102, s96, -v244
	v_exp_f32_e32 v196, v52
	v_fma_f32 v52, v103, s96, -v244
	v_exp_f32_e32 v199, v52
	v_fma_f32 v52, v56, s96, -v244
	v_exp_f32_e32 v198, v52
	v_fma_f32 v52, v57, s96, -v244
	v_exp_f32_e32 v225, v52
	v_fma_f32 v52, v104, s96, -v244
	v_exp_f32_e32 v202, v52
	v_fma_f32 v52, v105, s96, -v244
	v_exp_f32_e32 v203, v52
	v_fma_f32 v52, v58, s96, -v244
	v_fma_f32 v48, v48, s96, -v244
	v_exp_f32_e32 v228, v52
	v_fma_f32 v52, v59, s96, -v244
	v_exp_f32_e32 v252, v48
	v_fma_f32 v48, v49, s96, -v244
	v_fma_f32 v50, v50, s96, -v244
	v_exp_f32_e32 v229, v52
	v_fma_f32 v52, v106, s96, -v244
	v_exp_f32_e32 v253, v48
	v_fma_f32 v48, v96, s96, -v244
	v_exp_f32_e32 v200, v50
	v_fma_f32 v50, v51, s96, -v244
	v_exp_f32_e32 v194, v52
	v_fma_f32 v52, v107, s96, -v244
	v_exp_f32_e32 v246, v48
	v_fma_f32 v48, v97, s96, -v244
	v_exp_f32_e32 v201, v50
	v_fma_f32 v50, v98, s96, -v244
	v_exp_f32_e32 v195, v52
	v_fma_f32 v52, v60, s96, -v244
	v_exp_f32_e32 v247, v48
	v_exp_f32_e32 v248, v50
	v_fma_f32 v50, v99, s96, -v244
	v_exp_f32_e32 v230, v52
	v_fma_f32 v52, v61, s96, -v244
	v_exp_f32_e32 v249, v50
	v_exp_f32_e32 v231, v52
	v_fma_f32 v52, v108, s96, -v244
	v_exp_f32_e32 v182, v52
	v_fma_f32 v52, v109, s96, -v244
	v_exp_f32_e32 v183, v52
	v_fma_f32 v52, v62, s96, -v244
	v_add_f32_e32 v48, 0, v252
	v_add_f32_e32 v49, 0, v253
	v_add_f32_e32 v96, 0, v246
	v_add_f32_e32 v97, 0, v247
	v_exp_f32_e32 v232, v52
	v_fma_f32 v52, v63, s96, -v244
	v_add_f32_e32 v48, v200, v48
	v_add_f32_e32 v49, v201, v49
	v_add_f32_e32 v50, v248, v96
	v_add_f32_e32 v51, v249, v97
	v_exp_f32_e32 v233, v52
	v_fma_f32 v52, v110, s96, -v244
	v_add_f32_e32 v48, v204, v48
	v_add_f32_e32 v49, v205, v49
	v_add_f32_e32 v50, v250, v50
	v_add_f32_e32 v51, v251, v51
	v_exp_f32_e32 v226, v52
	v_fma_f32 v52, v111, s96, -v244
	v_add_f32_e32 v48, v180, v48
	v_add_f32_e32 v49, v181, v49
	v_add_f32_e32 v50, v196, v50
	v_add_f32_e32 v51, v199, v51
	v_exp_f32_e32 v227, v52
	v_add_f32_e32 v48, v198, v48
	v_add_f32_e32 v49, v225, v49
	v_add_f32_e32 v50, v202, v50
	v_add_f32_e32 v51, v203, v51
	v_add_f32_e32 v48, v228, v48
	v_add_f32_e32 v49, v229, v49
	v_add_f32_e32 v50, v194, v50
	v_add_f32_e32 v51, v195, v51
	v_add_f32_e32 v48, v230, v48
	v_add_f32_e32 v49, v231, v49
	v_add_f32_e32 v50, v182, v50
	v_add_f32_e32 v51, v183, v51
	v_add_f32_e32 v48, v232, v48
	v_add_f32_e32 v49, v233, v49
	v_add_f32_e32 v50, v226, v50
	v_add_f32_e32 v51, v227, v51
	v_add_f32_e32 v48, v49, v48
	v_add_f32_e32 v49, v51, v50
	v_add_f32_e32 v245, v49, v48
	v_mov_b32_e32 v234, v245
	v_mov_b64_e32 v[110:111], v[30:31]
	v_mov_b64_e32 v[62:63], v[46:47]
	v_permlane32_swap_b32_e32 v245, v234
	v_cmp_gt_f32_e32 vcc, v244, v243
	v_mov_b64_e32 v[108:109], v[28:29]
	v_mov_b64_e32 v[106:107], v[26:27]
	v_mov_b64_e32 v[104:105], v[24:25]
	v_mov_b64_e32 v[102:103], v[22:23]
	v_mov_b64_e32 v[100:101], v[20:21]
	v_mov_b64_e32 v[98:99], v[18:19]
	v_mov_b64_e32 v[96:97], v[16:17]
	v_mov_b64_e32 v[60:61], v[44:45]
	v_mov_b64_e32 v[58:59], v[42:43]
	v_mov_b64_e32 v[56:57], v[40:41]
	v_mov_b64_e32 v[54:55], v[38:39]
	v_mov_b64_e32 v[52:53], v[36:37]
	v_mov_b64_e32 v[50:51], v[34:35]
	v_mov_b64_e32 v[48:49], v[32:33]
	s_cbranch_vccz .LBB0_806
	v_sub_f32_e32 v48, v243, v244
	v_exp_f32_e32 v96, v48
	s_nop 0
	v_mul_f32_e32 v242, v235, v96
	v_pk_mul_f32 v[62:63], v[46:47], v[96:97] op_sel_hi:[1,0]
	v_pk_mul_f32 v[60:61], v[44:45], v[96:97] op_sel_hi:[1,0]
	v_pk_mul_f32 v[58:59], v[42:43], v[96:97] op_sel_hi:[1,0]
	v_pk_mul_f32 v[56:57], v[40:41], v[96:97] op_sel_hi:[1,0]
	v_pk_mul_f32 v[54:55], v[38:39], v[96:97] op_sel_hi:[1,0]
	v_pk_mul_f32 v[52:53], v[36:37], v[96:97] op_sel_hi:[1,0]
	v_pk_mul_f32 v[50:51], v[34:35], v[96:97] op_sel_hi:[1,0]
	v_pk_mul_f32 v[48:49], v[32:33], v[96:97] op_sel_hi:[1,0]
	v_pk_mul_f32 v[110:111], v[30:31], v[96:97] op_sel_hi:[1,0]
	v_pk_mul_f32 v[108:109], v[28:29], v[96:97] op_sel_hi:[1,0]
	v_pk_mul_f32 v[106:107], v[26:27], v[96:97] op_sel_hi:[1,0]
	v_pk_mul_f32 v[104:105], v[24:25], v[96:97] op_sel_hi:[1,0]
	v_pk_mul_f32 v[102:103], v[22:23], v[96:97] op_sel_hi:[1,0]
	v_pk_mul_f32 v[100:101], v[20:21], v[96:97] op_sel_hi:[1,0]
	v_pk_mul_f32 v[98:99], v[18:19], v[96:97] op_sel_hi:[1,0]
	v_pk_mul_f32 v[96:97], v[16:17], v[96:97] op_sel_hi:[1,0]
; __device__ __forceinline__ float xh_sum(float v) { auto rr = __builtin_amdgcn_permlane32_swap(__float_as_uint(v), __float_as_uint(v), false, false); return __uint_as_float(rr[0]) + __uint_as_float(rr[1]); }
; __device__ __forceinline__ float xh_max(float v) { auto rr = __builtin_amdgcn_permlane32_swap(__float_as_uint(v), __float_as_uint(v), false, false); return fmaxf(__uint_as_float(rr[0]), __uint_as_float(rr[1])); }
; __device__ __forceinline__ void sm_fast2(f32x16& s, f32x16& t, float c, float& m, float& l, f32x16 (&O)[2]) {
;     float a0 = fmaxf(fmaxf(s[0], s[1]), fmaxf(s[2], s[3])), a1 = fmaxf(fmaxf(s[4], s[5]), fmaxf(s[6], s[7]));
;     float a2 = fmaxf(fmaxf(s[8], s[9]), fmaxf(s[10], s[11])), a3 = fmaxf(fmaxf(s[12], s[13]), fmaxf(s[14], s[15]));
;     float b0 = fmaxf(fmaxf(t[0], t[1]), fmaxf(t[2], t[3])), b1 = fmaxf(fmaxf(t[4], t[5]), fmaxf(t[6], t[7]));
;     float b2 = fmaxf(fmaxf(t[8], t[9]), fmaxf(t[10], t[11])), b3 = fmaxf(fmaxf(t[12], t[13]), fmaxf(t[14], t[15]));
;     const float tmax = xh_max(fmaxf(fmaxf(fmaxf(a0, a1), fmaxf(a2, a3)), fmaxf(fmaxf(b0, b1), fmaxf(b2, b3))));
;     const float cand = tmax * c; const float mn = (cand > m + 8.0f) ? cand : m;
;     float p0 = 0.f, p1 = 0.f, p2 = 0.f, p3 = 0.f;
; #pragma unroll
;     for (int r = 0; r < 16; r += 2) {
;         const float e0 = __builtin_amdgcn_exp2f(fmaf(s[r], c, -mn)), e1 = __builtin_amdgcn_exp2f(fmaf(s[r + 1], c, -mn));
;         const float e2 = __builtin_amdgcn_exp2f(fmaf(t[r], c, -mn)), e3 = __builtin_amdgcn_exp2f(fmaf(t[r + 1], c, -mn));
;         s[r] = e0; s[r + 1] = e1; t[r] = e2; t[r + 1] = e3; p0 += e0; p1 += e1; p2 += e2; p3 += e3; }
;     const float ps = xh_sum((p0 + p1) + (p2 + p3));
;     if (__ballot(mn > m) != 0ull) { const float alpha = __builtin_amdgcn_exp2f(m - mn); l *= alpha; O[0] = O[0] * alpha; O[1] = O[1] * alpha; }
;     l += ps; m = mn;
; template <int NKS, int KP, class MaskA, class MaskB>
; __device__ __forceinline__ void pair_tiles(LAS const unsigned char* ia, LAS const unsigned char* ib, int c, int h, const bf16x8 (&qf)[NKS], float cc, float& m, float& l, f32x16 (&O)[2], MaskA maskA, MaskB maskB) {
;     ...
;     SCHED_BAR();
;     mma_pv(vf, sa, O); mma_pv(vg, ta, O);
;     load_v(vb, vf); load_v(vb + 64, vg); SCHED_BAR();
;     maskB(sb, tb); sm_fast2(sb, tb, cc, m, l, O);
;     SCHED_BAR();
;     mma_pv(vf, sb, O); mma_pv(vg, tb, O);
.LBB0_806:
	v_add_f32_e32 v210, v245, v234
	v_add_f32_e32 v245, v210, v242
	v_cvt_pk_bf16_f32 v236, v252, v253
	v_cvt_pk_bf16_f32 v237, v200, v201
	v_cvt_pk_bf16_f32 v238, v204, v205
	v_cvt_pk_bf16_f32 v239, v180, v181
	v_cvt_pk_bf16_f32 v210, v198, v225
	v_cvt_pk_bf16_f32 v211, v228, v229
	v_cvt_pk_bf16_f32 v212, v230, v231
	v_cvt_pk_bf16_f32 v213, v232, v233
	s_setprio 1
	s_waitcnt lgkmcnt(7)
	v_mfma_f32_32x32x16_bf16 v[48:63], v[176:179], v[236:239], v[48:63]
	s_waitcnt lgkmcnt(6)
	v_mfma_f32_32x32x16_bf16 v[48:63], v[172:175], v[210:213], v[48:63]
	s_waitcnt lgkmcnt(5)
	v_mfma_f32_32x32x16_bf16 v[96:111], v[168:171], v[236:239], v[96:111]
	s_waitcnt lgkmcnt(4)
	v_mfma_f32_32x32x16_bf16 v[96:111], v[164:167], v[210:213], v[96:111]
	s_setprio 0
	v_cvt_pk_bf16_f32 v164, v246, v247
	v_cvt_pk_bf16_f32 v165, v248, v249
	v_cvt_pk_bf16_f32 v166, v250, v251
	v_cvt_pk_bf16_f32 v167, v196, v199
	v_cvt_pk_bf16_f32 v168, v202, v203
	v_cvt_pk_bf16_f32 v169, v194, v195
	v_cvt_pk_bf16_f32 v170, v182, v183
	v_cvt_pk_bf16_f32 v171, v226, v227
	s_setprio 1
	s_waitcnt lgkmcnt(3)
	v_mfma_f32_32x32x16_bf16 v[48:63], v[160:163], v[164:167], v[48:63]
	s_waitcnt lgkmcnt(2)
	v_mfma_f32_32x32x16_bf16 v[48:63], v[10:13], v[168:171], v[48:63]
	s_waitcnt lgkmcnt(1)
	v_mfma_f32_32x32x16_bf16 v[96:111], v[6:9], v[164:167], v[96:111]
	s_waitcnt lgkmcnt(0)
	v_mfma_f32_32x32x16_bf16 v[96:111], v[2:5], v[168:171], v[96:111]
	s_setprio 0
	v_add_u32_e32 v2, 0x8800, v14
	v_add_u32_e32 v3, 0x9800, v14
	ds_read2_b64 v[176:179], v2 offset0:64 offset1:66
	ds_read2_b64 v[168:171], v2 offset0:68 offset1:70
	ds_read2_b64 v[172:175], v3 offset0:96 offset1:98
	ds_read2_b64 v[164:167], v3 offset0:100 offset1:102
	ds_read2_b64 v[160:163], v2 offset0:72 offset1:74
	ds_read2_b64 v[10:13], v2 offset0:76 offset1:78
	ds_read2_b64 v[6:9], v3 offset0:104 offset1:106
	ds_read2_b64 v[2:5], v3 offset0:108 offset1:110
	v_max_f32_e32 v180, v65, v65
	v_max_f32_e32 v181, v64, v64
	v_max_f32_e32 v180, v181, v180
	v_max_f32_e32 v181, v67, v67
	v_max_f32_e32 v182, v66, v66
	v_max_f32_e32 v181, v182, v181
	v_max_f32_e32 v182, v71, v71
	v_max_f32_e32 v183, v70, v70
	v_max_f32_e32 v182, v183, v182
	v_max_f32_e32 v183, v73, v73
	v_max_f32_e32 v194, v72, v72
	v_max_f32_e32 v183, v194, v183
	v_max_f32_e32 v194, v75, v75
	v_max_f32_e32 v195, v74, v74
	v_max_f32_e32 v194, v195, v194
	v_max_f32_e32 v195, v79, v79
	v_max_f32_e32 v196, v78, v78
	v_max_f32_e32 v195, v196, v195
	v_max_f32_e32 v196, v83, v83
	v_max_f32_e32 v198, v82, v82
	v_max_f32_e32 v196, v198, v196
	v_max_f32_e32 v198, v87, v87
	v_max_f32_e32 v199, v86, v86
	v_max_f32_e32 v198, v199, v198
	v_max_f32_e32 v199, v89, v89
	v_max_f32_e32 v200, v88, v88
	v_max_f32_e32 v199, v200, v199
	v_max_f32_e32 v200, v91, v91
	v_max_f32_e32 v201, v90, v90
	v_max_f32_e32 v200, v201, v200
	v_max_f32_e32 v201, v95, v95
	v_max_f32_e32 v202, v94, v94
	v_max_f32_e32 v201, v202, v201
	v_max3_f32 v182, v68, v69, v182
	v_max3_f32 v201, v92, v93, v201
	v_max3_f32 v195, v76, v77, v195
	v_max3_f32 v196, v80, v81, v196
	v_max3_f32 v198, v84, v85, v198
	v_max3_f32 v180, v180, v181, v182
	v_max3_f32 v182, v199, v200, v201
	v_max3_f32 v181, v183, v194, v195
	v_max3_f32 v182, v196, v198, v182
	v_max3_f32 v180, v180, v181, v182
	v_mov_b32_e32 v181, v180
	s_nop 1
	v_permlane32_swap_b32_e32 v180, v181
	v_max_f32_e32 v181, v181, v181
	v_max_f32_e32 v180, v180, v180
	v_max_f32_e32 v180, v180, v181
	v_mul_f32_e32 v180, 0x3e16c740, v180
	v_add_f32_e32 v181, 0x41000000, v244
	v_cmp_gt_f32_e32 vcc, v180, v181
	s_nop 1
	v_cndmask_b32_e32 v246, v244, v180, vcc
	v_fma_f32 v64, v64, s96, -v246
	v_exp_f32_e32 v247, v64
	v_fma_f32 v64, v65, s96, -v246
	v_fma_f32 v66, v66, s96, -v246
	v_exp_f32_e32 v248, v64
	v_fma_f32 v64, v80, s96, -v246
	v_fma_f32 v65, v81, s96, -v246
	v_exp_f32_e32 v80, v66
	v_fma_f32 v66, v67, s96, -v246
	v_fma_f32 v68, v68, s96, -v246
	v_exp_f32_e32 v64, v64
	v_exp_f32_e32 v65, v65
	v_exp_f32_e32 v81, v66
	v_fma_f32 v66, v82, s96, -v246
	v_fma_f32 v67, v83, s96, -v246
	v_exp_f32_e32 v82, v68
	v_fma_f32 v68, v69, s96, -v246
	v_fma_f32 v70, v70, s96, -v246
	v_exp_f32_e32 v66, v66
	v_exp_f32_e32 v67, v67
	v_exp_f32_e32 v83, v68
	v_fma_f32 v68, v84, s96, -v246
	v_fma_f32 v69, v85, s96, -v246
	v_exp_f32_e32 v84, v70
	v_fma_f32 v70, v71, s96, -v246
	v_fma_f32 v72, v72, s96, -v246
	v_exp_f32_e32 v68, v68
	v_exp_f32_e32 v69, v69
	v_exp_f32_e32 v85, v70
	v_fma_f32 v70, v86, s96, -v246
	v_fma_f32 v71, v87, s96, -v246
	v_exp_f32_e32 v86, v72
	v_fma_f32 v72, v73, s96, -v246
	v_fma_f32 v74, v74, s96, -v246
	v_exp_f32_e32 v70, v70
	v_exp_f32_e32 v71, v71
	v_exp_f32_e32 v87, v72
	v_fma_f32 v72, v88, s96, -v246
	v_fma_f32 v73, v89, s96, -v246
	v_exp_f32_e32 v88, v74
	v_fma_f32 v74, v75, s96, -v246
	v_fma_f32 v76, v76, s96, -v246
	v_add_f32_e32 v180, 0, v247
	v_add_f32_e32 v181, 0, v248
	v_add_f32_e32 v182, 0, v64
	v_add_f32_e32 v183, 0, v65
	v_exp_f32_e32 v72, v72
	v_exp_f32_e32 v73, v73
	v_exp_f32_e32 v89, v74
	v_fma_f32 v74, v90, s96, -v246
	v_fma_f32 v75, v91, s96, -v246
	v_exp_f32_e32 v90, v76
	v_fma_f32 v76, v77, s96, -v246
	v_fma_f32 v78, v78, s96, -v246
	v_add_f32_e32 v180, v80, v180
	v_add_f32_e32 v181, v81, v181
	v_add_f32_e32 v182, v66, v182
	v_add_f32_e32 v183, v67, v183
	v_exp_f32_e32 v74, v74
	v_exp_f32_e32 v75, v75
	v_exp_f32_e32 v91, v76
	v_fma_f32 v76, v92, s96, -v246
	v_fma_f32 v77, v93, s96, -v246
	v_exp_f32_e32 v92, v78
	v_fma_f32 v78, v79, s96, -v246
	v_add_f32_e32 v180, v82, v180
	v_add_f32_e32 v181, v83, v181
	v_add_f32_e32 v182, v68, v182
	v_add_f32_e32 v183, v69, v183
	v_exp_f32_e32 v76, v76
	v_exp_f32_e32 v77, v77
	v_exp_f32_e32 v93, v78
	v_fma_f32 v78, v94, s96, -v246
	v_fma_f32 v79, v95, s96, -v246
	v_add_f32_e32 v180, v84, v180
	v_add_f32_e32 v181, v85, v181
	v_add_f32_e32 v182, v70, v182
	v_add_f32_e32 v183, v71, v183
	v_exp_f32_e32 v78, v78
	v_exp_f32_e32 v79, v79
	v_add_f32_e32 v180, v86, v180
	v_add_f32_e32 v181, v87, v181
	v_add_f32_e32 v182, v72, v182
	v_add_f32_e32 v183, v73, v183
	v_add_f32_e32 v180, v88, v180
	v_add_f32_e32 v181, v89, v181
	v_add_f32_e32 v182, v74, v182
	v_add_f32_e32 v183, v75, v183
	v_add_f32_e32 v180, v90, v180
	v_add_f32_e32 v181, v91, v181
	v_add_f32_e32 v182, v76, v182
	v_add_f32_e32 v183, v77, v183
	v_add_f32_e32 v94, v92, v180
	v_add_f32_e32 v95, v93, v181
	v_add_f32_e32 v180, v78, v182
	v_add_f32_e32 v181, v79, v183
	v_add_f32_e32 v94, v95, v94
	v_add_f32_e32 v95, v181, v180
	v_add_f32_e32 v94, v95, v94
	v_mov_b32_e32 v95, v94
	s_nop 1
	v_permlane32_swap_b32_e32 v94, v95
	v_cmp_gt_f32_e32 vcc, v246, v244
	s_cbranch_vccz .LBB0_808
; __device__ __forceinline__ unsigned pk2(float lo, float hi) { f32x2_t v = {lo, hi}; bf16x2_t b = __builtin_convertvector(v, bf16x2_t); return __builtin_bit_cast(unsigned, b); }
; #define SCHED_BAR() __builtin_amdgcn_sched_barrier(0)
; __device__ __forceinline__ void mma_pv(const bf16x8 (&vf)[2][2], const f32x16& p, f32x16 (&O)[2]) {
;     bf16x8 pf[2];
; #pragma unroll
;     for (int s = 0; s < 2; ++s) { u32x4 w; w.x = pk2(p[8 * s], p[8 * s + 1]); w.y = pk2(p[8 * s + 2], p[8 * s + 3]); w.z = pk2(p[8 * s + 4], p[8 * s + 5]); w.w = pk2(p[8 * s + 6], p[8 * s + 7]); pf[s] = __builtin_bit_cast(bf16x8, w); }
; #pragma unroll
;     for (int d = 0; d < 2; ++d)
; #pragma unroll
;         for (int s = 0; s < 2; ++s) { __builtin_amdgcn_s_setprio(1); O[d] = __builtin_amdgcn_mfma_f32_32x32x16_bf16(vf[d][s], pf[s], O[d], 0, 0, 0); __builtin_amdgcn_s_setprio(0); }
; }
; template <int NKS, int KP, class MaskA, class MaskB>
; __device__ __forceinline__ void pair_tiles(LAS const unsigned char* ia, LAS const unsigned char* ib, int c, int h, const bf16x8 (&qf)[NKS], float cc, float& m, float& l, f32x16 (&O)[2], MaskA maskA, MaskB maskB) {
;     ...
;     maskB(sb, tb); sm_fast2(sb, tb, cc, m, l, O);
;     SCHED_BAR();
;     mma_pv(vf, sb, O); mma_pv(vg, tb, O);
	v_sub_f32_e32 v180, v244, v246
	v_exp_f32_e32 v180, v180
	s_nop 0
	v_mul_f32_e32 v245, v245, v180
	v_pk_mul_f32 v[62:63], v[62:63], v[180:181] op_sel_hi:[1,0]
	v_pk_mul_f32 v[60:61], v[60:61], v[180:181] op_sel_hi:[1,0]
	v_pk_mul_f32 v[58:59], v[58:59], v[180:181] op_sel_hi:[1,0]
	v_pk_mul_f32 v[56:57], v[56:57], v[180:181] op_sel_hi:[1,0]
	v_pk_mul_f32 v[54:55], v[54:55], v[180:181] op_sel_hi:[1,0]
	v_pk_mul_f32 v[52:53], v[52:53], v[180:181] op_sel_hi:[1,0]
	v_pk_mul_f32 v[50:51], v[50:51], v[180:181] op_sel_hi:[1,0]
	v_pk_mul_f32 v[48:49], v[48:49], v[180:181] op_sel_hi:[1,0]
	v_pk_mul_f32 v[110:111], v[110:111], v[180:181] op_sel_hi:[1,0]
	v_pk_mul_f32 v[108:109], v[108:109], v[180:181] op_sel_hi:[1,0]
	v_pk_mul_f32 v[106:107], v[106:107], v[180:181] op_sel_hi:[1,0]
	v_pk_mul_f32 v[104:105], v[104:105], v[180:181] op_sel_hi:[1,0]
	v_pk_mul_f32 v[102:103], v[102:103], v[180:181] op_sel_hi:[1,0]
	v_pk_mul_f32 v[100:101], v[100:101], v[180:181] op_sel_hi:[1,0]
	v_pk_mul_f32 v[98:99], v[98:99], v[180:181] op_sel_hi:[1,0]
	v_pk_mul_f32 v[96:97], v[96:97], v[180:181] op_sel_hi:[1,0]
.LBB0_808:
	v_add_f32_e32 v94, v94, v95
	v_add_f32_e32 v94, v94, v245
	v_cvt_pk_bf16_f32 v180, v247, v248
	v_cvt_pk_bf16_f32 v181, v80, v81
	v_cvt_pk_bf16_f32 v182, v82, v83
	v_cvt_pk_bf16_f32 v183, v84, v85
	v_cvt_pk_bf16_f32 v80, v86, v87
	v_cvt_pk_bf16_f32 v81, v88, v89
	v_cvt_pk_bf16_f32 v82, v90, v91
	v_cvt_pk_bf16_f32 v83, v92, v93
	s_setprio 1
	s_waitcnt lgkmcnt(7)
	v_mfma_f32_32x32x16_bf16 v[48:63], v[176:179], v[180:183], v[48:63]
	s_waitcnt lgkmcnt(6)
	v_mfma_f32_32x32x16_bf16 v[48:63], v[168:171], v[80:83], v[48:63]
	s_waitcnt lgkmcnt(5)
	v_mfma_f32_32x32x16_bf16 v[96:111], v[172:175], v[180:183], v[96:111]
	s_waitcnt lgkmcnt(4)
	v_mfma_f32_32x32x16_bf16 v[96:111], v[164:167], v[80:83], v[96:111]
	s_setprio 0
	v_cvt_pk_bf16_f32 v64, v64, v65
	v_cvt_pk_bf16_f32 v65, v66, v67
	v_cvt_pk_bf16_f32 v66, v68, v69
	v_cvt_pk_bf16_f32 v67, v70, v71
	v_cvt_pk_bf16_f32 v68, v72, v73
	v_cvt_pk_bf16_f32 v69, v74, v75
	v_cvt_pk_bf16_f32 v70, v76, v77
	v_cvt_pk_bf16_f32 v71, v78, v79
	s_setprio 1
	s_waitcnt lgkmcnt(3)
	v_mfma_f32_32x32x16_bf16 v[48:63], v[160:163], v[64:67], v[48:63]
	s_waitcnt lgkmcnt(2)
	v_mfma_f32_32x32x16_bf16 v[48:63], v[10:13], v[68:71], v[48:63]
	s_waitcnt lgkmcnt(1)
	v_mfma_f32_32x32x16_bf16 v[96:111], v[6:9], v[64:67], v[96:111]
	s_mov_b64 s[14:15], -1
	s_waitcnt lgkmcnt(0)
	v_mfma_f32_32x32x16_bf16 v[96:111], v[2:5], v[68:71], v[96:111]

; __device__ __forceinline__ unsigned pk2(float lo, float hi) { f32x2_t v = {lo, hi}; bf16x2_t b = __builtin_convertvector(v, bf16x2_t); return __builtin_bit_cast(unsigned, b); }
; __device__ __forceinline__ int kr16(int r, int h) { return (r & 3) + 8 * (r >> 2) + 4 * h; }
; #define SCHED_BAR() __builtin_amdgcn_sched_barrier(0)
; __device__ __forceinline__ void mma_pv(const bf16x8 (&vf)[2][2], const f32x16& p, f32x16 (&O)[2]) {
;     bf16x8 pf[2];
; #pragma unroll
;     for (int s = 0; s < 2; ++s) { u32x4 w; w.x = pk2(p[8 * s], p[8 * s + 1]); w.y = pk2(p[8 * s + 2], p[8 * s + 3]); w.z = pk2(p[8 * s + 4], p[8 * s + 5]); w.w = pk2(p[8 * s + 6], p[8 * s + 7]); pf[s] = __builtin_bit_cast(bf16x8, w); }
; #pragma unroll
;     for (int d = 0; d < 2; ++d)
; #pragma unroll
;         for (int s = 0; s < 2; ++s) { __builtin_amdgcn_s_setprio(1); O[d] = __builtin_amdgcn_mfma_f32_32x32x16_bf16(vf[d][s], pf[s], O[d], 0, 0, 0); __builtin_amdgcn_s_setprio(0); }
; }
; __device__ __forceinline__ void mla_unit(unsigned char* ws, LAS unsigned char* kvb, int bl, int hd, int qt, int tid, int wave, int lane) {
;     ...
;             if (k0 + 32 > q0w) {
;                 bf16x8 kf[6], vf[2][2]; load_k<6>(kb, kf); load_v(vb, vf); SCHED_BAR();
;                 f32x16 s = mma_qk<6>(kf, qf);
;                 unsigned valid = 0u;
; #pragma unroll
;                 for (int r = 0; r < 16; ++r) valid |= (k0 + kr16(r, h) <= qpos ? 1u : 0u) << r;
;                 mask_apply(s, valid);
;                 sm_fast(s, C_MLA, m, l, O); mma_pv(vf, s, O); return; }
;             bf16x8 kf[6], kg[6]; load_k<6>(kb, kf); load_k<6>(kb + 32 * 208, kg); SCHED_BAR();
;             f32x16 s = mma_qk<6>(kf, qf), t = mma_qk<6>(kg, qf);
;             bf16x8 vf[2][2]; load_v(vb, vf); SCHED_BAR();
;             if (k0 + 32 == q0w) { unsigned valid = 0u;
; #pragma unroll
;                 for (int r = 0; r < 16; ++r) valid |= (k0 + 32 + kr16(r, h) <= qpos ? 1u : 0u) << r;
;                 mask_apply(t, valid); }
.LBB0_816:
	v_add_f32_e32 v160, v160, v177
	v_add_f32_e32 v160, v160, v178
	v_cvt_pk_bf16_f32 v162, v161, v162
	v_cvt_pk_bf16_f32 v163, v163, v164
	v_cvt_pk_bf16_f32 v164, v165, v166
	v_cvt_pk_bf16_f32 v165, v167, v168
	v_cvt_pk_bf16_f32 v166, v169, v170
	v_cvt_pk_bf16_f32 v167, v171, v172
	v_cvt_pk_bf16_f32 v168, v173, v174
	v_cvt_pk_bf16_f32 v169, v175, v176
	s_setprio 1
	s_waitcnt lgkmcnt(3)
	v_mfma_f32_32x32x16_bf16 v[48:63], v[104:107], v[162:165], v[48:63]
	s_waitcnt lgkmcnt(2)
	v_mfma_f32_32x32x16_bf16 v[48:63], v[100:103], v[166:169], v[48:63]
	s_waitcnt lgkmcnt(1)
	v_mfma_f32_32x32x16_bf16 v[64:79], v[96:99], v[162:165], v[64:79]
	s_waitcnt lgkmcnt(0)
	v_mfma_f32_32x32x16_bf16 v[64:79], v[92:95], v[166:169], v[64:79]
	s_mov_b64 s[16:17], 0
.LBB0_817:
	s_and_b64 vcc, exec, s[16:17]
	s_cbranch_vccz .LBB0_823
	s_nop 8
	ds_read_b128 v[64:67], v15 offset:6656
	ds_read_b128 v[92:95], v15 offset:6688
	ds_read_b128 v[96:99], v15 offset:6720
	ds_read_b128 v[100:103], v15 offset:6752
	ds_read_b128 v[104:107], v15 offset:6784
	ds_read_b128 v[160:163], v15 offset:6816
	s_or_b32 s0, s25, 32
	s_setprio 1
	s_waitcnt lgkmcnt(11)
	v_mfma_f32_32x32x16_bf16 v[48:63], v[88:91], v[112:115], 0
	s_waitcnt lgkmcnt(10)
	v_mfma_f32_32x32x16_bf16 v[48:63], v[84:87], v[116:119], v[48:63]
	s_waitcnt lgkmcnt(9)
	v_mfma_f32_32x32x16_bf16 v[48:63], v[80:83], v[120:123], v[48:63]
	s_waitcnt lgkmcnt(8)
	v_mfma_f32_32x32x16_bf16 v[48:63], v[10:13], v[124:127], v[48:63]
	s_waitcnt lgkmcnt(7)
	v_mfma_f32_32x32x16_bf16 v[48:63], v[6:9], v[128:131], v[48:63]
	s_waitcnt lgkmcnt(6)
	v_mfma_f32_32x32x16_bf16 v[48:63], v[2:5], v[132:135], v[48:63]
	s_waitcnt lgkmcnt(5)
	v_mfma_f32_32x32x16_bf16 v[64:79], v[64:67], v[112:115], 0
	s_waitcnt lgkmcnt(4)
	v_mfma_f32_32x32x16_bf16 v[64:79], v[92:95], v[116:119], v[64:79]
	s_waitcnt lgkmcnt(3)
	v_mfma_f32_32x32x16_bf16 v[64:79], v[96:99], v[120:123], v[64:79]
	s_waitcnt lgkmcnt(2)
	v_mfma_f32_32x32x16_bf16 v[64:79], v[100:103], v[124:127], v[64:79]
	s_waitcnt lgkmcnt(1)
	v_mfma_f32_32x32x16_bf16 v[64:79], v[104:107], v[128:131], v[64:79]
	s_waitcnt lgkmcnt(0)
	v_mfma_f32_32x32x16_bf16 v[64:79], v[160:163], v[132:135], v[64:79]
	s_setprio 0
	ds_read2_b64 v[80:83], v109 offset0:128 offset1:130
	ds_read2_b64 v[10:13], v109 offset0:132 offset1:134
	ds_read2_b64 v[6:9], v108 offset0:160 offset1:162
	ds_read2_b64 v[2:5], v108 offset0:164 offset1:166
	s_cmp_lg_u32 s0, s21
	s_cbranch_scc1 .LBB0_820
	v_add_u32_e32 v84, 33, v209
	v_add_u32_e32 v84, s25, v84
	v_add_u32_e32 v85, 34, v209
	v_add_u32_e32 v85, s25, v85
	v_add_u32_e32 v86, 35, v209
	v_mov_b32_e32 v99, 0xff61b1e6
	v_cmp_gt_i32_e32 vcc, v84, v186
	v_add_u32_e32 v86, s25, v86
	v_add_u32_e32 v87, 40, v209
	v_add_u32_e32 v87, s25, v87
	v_cndmask_b32_e32 v65, v65, v99, vcc
	v_cmp_gt_i32_e32 vcc, v85, v186
	v_add_u32_e32 v88, 41, v209
	v_add_u32_e32 v88, s25, v88
	v_cndmask_b32_e32 v66, v66, v99, vcc
	v_cmp_gt_i32_e32 vcc, v86, v186
	v_add_u32_e32 v89, 42, v209
	v_add_u32_e32 v89, s25, v89
	v_cndmask_b32_e32 v67, v67, v99, vcc
	v_cmp_gt_i32_e32 vcc, v87, v186
	v_add_u32_e32 v90, 43, v209
	v_add_u32_e32 v90, s25, v90
	v_cndmask_b32_e32 v68, v68, v99, vcc
	v_cmp_gt_i32_e32 vcc, v88, v186
	v_add_u32_e32 v91, 48, v209
	v_add_u32_e32 v91, s25, v91
	v_cndmask_b32_e32 v69, v69, v99, vcc
	v_cmp_gt_i32_e32 vcc, v89, v186
	v_add_u32_e32 v92, 49, v209
	v_add_u32_e32 v92, s25, v92
	v_cndmask_b32_e32 v70, v70, v99, vcc
	v_cmp_gt_i32_e32 vcc, v90, v186
	v_add_u32_e32 v93, 50, v209
	v_add_u32_e32 v93, s25, v93
	v_cndmask_b32_e32 v71, v71, v99, vcc
	v_cmp_gt_i32_e32 vcc, v91, v186
	v_add_u32_e32 v94, 51, v209
	v_add_u32_e32 v94, s25, v94
	v_cndmask_b32_e32 v72, v72, v99, vcc
	v_cmp_gt_i32_e32 vcc, v92, v186
	v_add_u32_e32 v95, 56, v209
	v_add_u32_e32 v95, s25, v95
	v_cndmask_b32_e32 v73, v73, v99, vcc
	v_cmp_gt_i32_e32 vcc, v93, v186
	v_add_u32_e32 v96, 57, v209
	v_add_u32_e32 v96, s25, v96
	v_cndmask_b32_e32 v74, v74, v99, vcc
	v_cmp_gt_i32_e32 vcc, v94, v186
	v_add_u32_e32 v97, 58, v209
	v_add_u32_e32 v97, s25, v97
	v_cndmask_b32_e32 v75, v75, v99, vcc
	v_cmp_gt_i32_e32 vcc, v95, v186
	v_add_u32_e32 v98, 59, v209
	v_add_u32_e32 v98, s25, v98
	v_cndmask_b32_e32 v76, v76, v99, vcc
	v_cmp_gt_i32_e32 vcc, v96, v186
	v_cndmask_b32_e64 v64, v64, v99, s[6:7]
	s_nop 0
	v_cndmask_b32_e32 v77, v77, v99, vcc
	v_cmp_gt_i32_e32 vcc, v97, v186
	s_nop 1
	v_cndmask_b32_e32 v78, v78, v99, vcc
	v_cmp_gt_i32_e32 vcc, v98, v186
	s_nop 1
	v_cndmask_b32_e32 v79, v79, v99, vcc

; __device__ __forceinline__ unsigned pk2(float lo, float hi) { f32x2_t v = {lo, hi}; bf16x2_t b = __builtin_convertvector(v, bf16x2_t); return __builtin_bit_cast(unsigned, b); }
; #define SCHED_BAR() __builtin_amdgcn_sched_barrier(0)
; __device__ __forceinline__ void mma_pv(const bf16x8 (&vf)[2][2], const f32x16& p, f32x16 (&O)[2]) {
;     bf16x8 pf[2];
; #pragma unroll
;     for (int s = 0; s < 2; ++s) { u32x4 w; w.x = pk2(p[8 * s], p[8 * s + 1]); w.y = pk2(p[8 * s + 2], p[8 * s + 3]); w.z = pk2(p[8 * s + 4], p[8 * s + 5]); w.w = pk2(p[8 * s + 6], p[8 * s + 7]); pf[s] = __builtin_bit_cast(bf16x8, w); }
; #pragma unroll
;     for (int d = 0; d < 2; ++d)
; #pragma unroll
;         for (int s = 0; s < 2; ++s) { __builtin_amdgcn_s_setprio(1); O[d] = __builtin_amdgcn_mfma_f32_32x32x16_bf16(vf[d][s], pf[s], O[d], 0, 0, 0); __builtin_amdgcn_s_setprio(0); }
; }
; __device__ __forceinline__ void mla_unit(unsigned char* ws, LAS unsigned char* kvb, int bl, int hd, int qt, int tid, int wave, int lane) {
;     ...
;             sm_fast2(s, t, C_MLA, m, l, O);
;             bf16x8 vg[2][2]; load_v(vb + 64, vg); SCHED_BAR();
;             mma_pv(vf, s, O); mma_pv(vg, t, O); },
.LBB0_822:
	ds_read2_b64 v[86:89], v109 offset0:136 offset1:138
	ds_read2_b64 v[90:93], v109 offset0:140 offset1:142
	ds_read2_b64 v[94:97], v108 offset0:168 offset1:170
	ds_read2_b64 v[98:101], v108 offset0:172 offset1:174
	v_add_f32_e32 v78, v78, v79
	v_add_f32_e32 v160, v78, v235
	v_cvt_pk_bf16_f32 v103, v64, v65
	v_cvt_pk_bf16_f32 v104, v66, v67
	v_cvt_pk_bf16_f32 v64, v70, v71
	v_cvt_pk_bf16_f32 v65, v72, v73
	v_cvt_pk_bf16_f32 v66, v74, v75
	v_cvt_pk_bf16_f32 v67, v76, v77
	v_cvt_pk_bf16_f32 v102, v84, v85
	v_cvt_pk_bf16_f32 v105, v68, v69
	s_setprio 1
	s_waitcnt lgkmcnt(7)
	v_mfma_f32_32x32x16_bf16 v[32:47], v[80:83], v[102:105], v[32:47]
	s_waitcnt lgkmcnt(6)
	v_mfma_f32_32x32x16_bf16 v[32:47], v[10:13], v[64:67], v[32:47]
	s_waitcnt lgkmcnt(5)
	v_mfma_f32_32x32x16_bf16 v[16:31], v[6:9], v[102:105], v[16:31]
	s_waitcnt lgkmcnt(4)
	v_mfma_f32_32x32x16_bf16 v[16:31], v[2:5], v[64:67], v[16:31]
	s_setprio 0
	v_cvt_pk_bf16_f32 v2, v48, v49
	v_cvt_pk_bf16_f32 v3, v50, v51
	v_cvt_pk_bf16_f32 v4, v52, v53
	v_cvt_pk_bf16_f32 v5, v54, v55
	v_cvt_pk_bf16_f32 v6, v56, v57
	v_cvt_pk_bf16_f32 v7, v58, v59
	v_cvt_pk_bf16_f32 v8, v60, v61
	v_cvt_pk_bf16_f32 v9, v62, v63
	s_setprio 1
	s_waitcnt lgkmcnt(3)
	v_mfma_f32_32x32x16_bf16 v[32:47], v[86:89], v[2:5], v[32:47]
	s_waitcnt lgkmcnt(2)
	v_mfma_f32_32x32x16_bf16 v[32:47], v[90:93], v[6:9], v[32:47]
	s_waitcnt lgkmcnt(1)
	v_mfma_f32_32x32x16_bf16 v[16:31], v[94:97], v[2:5], v[16:31]
	s_waitcnt lgkmcnt(0)
	v_mfma_f32_32x32x16_bf16 v[16:31], v[98:101], v[6:9], v[16:31]
	s_nop 3
	v_mov_b64_e32 v[62:63], v[46:47]
	v_mov_b64_e32 v[60:61], v[44:45]
	v_mov_b64_e32 v[58:59], v[42:43]
	v_mov_b64_e32 v[56:57], v[40:41]
	v_mov_b64_e32 v[54:55], v[38:39]
	v_mov_b64_e32 v[52:53], v[36:37]
	v_mov_b64_e32 v[50:51], v[34:35]
	s_nop 0
	v_mov_b64_e32 v[78:79], v[30:31]
	v_mov_b64_e32 v[76:77], v[28:29]
	v_mov_b64_e32 v[74:75], v[26:27]
	v_mov_b64_e32 v[72:73], v[24:25]
	v_mov_b64_e32 v[70:71], v[22:23]
	v_mov_b64_e32 v[68:69], v[20:21]
	v_mov_b64_e32 v[66:67], v[18:19]
	v_mov_b64_e32 v[64:65], v[16:17]
	v_mov_b64_e32 v[48:49], v[32:33]

; #define LAS __attribute__((address_space(3)))
; __device__ __forceinline__ int kr16(int r, int h) { return (r & 3) + 8 * (r >> 2) + 4 * h; }
; #define SCHED_BAR() __builtin_amdgcn_sched_barrier(0)
; __device__ __forceinline__ void mla_unit(unsigned char* ws, LAS unsigned char* kvb, int bl, int hd, int qt, int tid, int wave, int lane) {
;     ...
;         [&](int k0, LAS const unsigned char* buf) {
;             if (k0 > q0w) return;
;             LAS const unsigned char* kb = buf + c * 208 + 16 * h; LAS const unsigned char* vb = buf + 64 * 208 + c * KV_VP + 8 * h;
;             if (k0 + 32 > q0w) {
;                 bf16x8 kf[6], vf[2][2]; load_k<6>(kb, kf); load_v(vb, vf); SCHED_BAR();
;                 f32x16 s = mma_qk<6>(kf, qf);
;                 unsigned valid = 0u;
; #pragma unroll
;                 for (int r = 0; r < 16; ++r) valid |= (k0 + kr16(r, h) <= qpos ? 1u : 0u) << r;
;                 mask_apply(s, valid);
;                 sm_fast(s, C_MLA, m, l, O); mma_pv(vf, s, O); return; }
;             bf16x8 kf[6], kg[6]; load_k<6>(kb, kf); load_k<6>(kb + 32 * 208, kg); SCHED_BAR();
;             f32x16 s = mma_qk<6>(kf, qf), t = mma_qk<6>(kg, qf);
;             bf16x8 vf[2][2]; load_v(vb, vf); SCHED_BAR();
;             if (k0 + 32 == q0w) { unsigned valid = 0u;
; #pragma unroll
;                 for (int r = 0; r < 16; ++r) valid |= (k0 + 32 + kr16(r, h) <= qpos ? 1u : 0u) << r;
;                 mask_apply(t, valid); }
.LBB0_824:
	s_cmp_gt_i32 s24, s21
	s_cselect_b64 s[16:17], -1, 0
	s_or_b64 s[12:13], s[12:13], s[16:17]
	s_and_b64 vcc, exec, s[12:13]
	s_cbranch_vccnz .LBB0_836
	s_waitcnt lgkmcnt(3)
	ds_read_b128 v[80:83], v15 offset:22016
	ds_read_b128 v[84:87], v15 offset:22048
	ds_read_b128 v[88:91], v15 offset:22080
	s_waitcnt lgkmcnt(5)
	ds_read_b128 v[10:13], v15 offset:22112
	s_waitcnt lgkmcnt(5)
	ds_read_b128 v[6:9], v15 offset:22144
	s_waitcnt lgkmcnt(5)
	ds_read_b128 v[2:5], v15 offset:22176
	s_add_i32 s9, s24, 32
	s_cmp_le_u32 s9, s21
	s_mov_b64 s[12:13], -1
	v_add_u32_e32 v109, 0x8800, v14
	v_add_u32_e32 v108, 0x9800, v14
	s_cbranch_scc0 .LBB0_831
	ds_read_b128 v[64:67], v15 offset:28672
	ds_read_b128 v[92:95], v15 offset:28704
	ds_read_b128 v[96:99], v15 offset:28736
	ds_read_b128 v[100:103], v15 offset:28768
	ds_read_b128 v[104:107], v15 offset:28800
	ds_read_b128 v[160:163], v15 offset:28832
	s_setprio 1
	s_waitcnt lgkmcnt(11)
	v_mfma_f32_32x32x16_bf16 v[48:63], v[80:83], v[112:115], 0
	s_waitcnt lgkmcnt(10)
	v_mfma_f32_32x32x16_bf16 v[48:63], v[84:87], v[116:119], v[48:63]
	s_waitcnt lgkmcnt(9)
	v_mfma_f32_32x32x16_bf16 v[48:63], v[88:91], v[120:123], v[48:63]
	s_waitcnt lgkmcnt(8)
	v_mfma_f32_32x32x16_bf16 v[48:63], v[10:13], v[124:127], v[48:63]
	s_waitcnt lgkmcnt(7)
	v_mfma_f32_32x32x16_bf16 v[48:63], v[6:9], v[128:131], v[48:63]
	s_waitcnt lgkmcnt(6)
	v_mfma_f32_32x32x16_bf16 v[48:63], v[2:5], v[132:135], v[48:63]
	s_waitcnt lgkmcnt(5)
	v_mfma_f32_32x32x16_bf16 v[64:79], v[64:67], v[112:115], 0
	s_waitcnt lgkmcnt(4)
	v_mfma_f32_32x32x16_bf16 v[64:79], v[92:95], v[116:119], v[64:79]
	s_waitcnt lgkmcnt(3)
	v_mfma_f32_32x32x16_bf16 v[64:79], v[96:99], v[120:123], v[64:79]
	s_waitcnt lgkmcnt(2)
	v_mfma_f32_32x32x16_bf16 v[64:79], v[100:103], v[124:127], v[64:79]
	s_waitcnt lgkmcnt(1)
	v_mfma_f32_32x32x16_bf16 v[64:79], v[104:107], v[128:131], v[64:79]
	s_waitcnt lgkmcnt(0)
	v_mfma_f32_32x32x16_bf16 v[64:79], v[160:163], v[132:135], v[64:79]
	s_setprio 0
	ds_read2_b64 v[104:107], v109 offset0:64 offset1:66
	ds_read2_b64 v[100:103], v109 offset0:68 offset1:70
	ds_read2_b64 v[96:99], v108 offset0:96 offset1:98
	ds_read2_b64 v[92:95], v108 offset0:100 offset1:102
	s_cmp_lg_u32 s9, s21
	s_cbranch_scc1 .LBB0_828
	v_add_u32_e32 v14, 33, v209
	v_add_u32_e32 v14, s24, v14
	v_add_u32_e32 v15, 34, v209
	v_add_u32_e32 v15, s24, v15
	v_add_u32_e32 v110, 35, v209
	v_mov_b32_e32 v171, 0xff61b1e6
	v_cmp_gt_i32_e32 vcc, v14, v186
	v_add_u32_e32 v110, s24, v110
	v_add_u32_e32 v111, 40, v209
	v_add_u32_e32 v111, s24, v111
	v_cndmask_b32_e32 v65, v65, v171, vcc
	v_cmp_gt_i32_e32 vcc, v15, v186
	v_add_u32_e32 v160, 41, v209
	v_add_u32_e32 v160, s24, v160
	v_cndmask_b32_e32 v66, v66, v171, vcc
	v_cmp_gt_i32_e32 vcc, v110, v186
	v_add_u32_e32 v161, 42, v209
	v_add_u32_e32 v161, s24, v161
	v_cndmask_b32_e32 v67, v67, v171, vcc
	v_cmp_gt_i32_e32 vcc, v111, v186
	v_add_u32_e32 v162, 43, v209
	v_add_u32_e32 v162, s24, v162
	v_cndmask_b32_e32 v68, v68, v171, vcc
	v_cmp_gt_i32_e32 vcc, v160, v186
	v_add_u32_e32 v163, 48, v209
	v_add_u32_e32 v163, s24, v163
	v_cndmask_b32_e32 v69, v69, v171, vcc
	v_cmp_gt_i32_e32 vcc, v161, v186
	v_add_u32_e32 v164, 49, v209
	v_add_u32_e32 v164, s24, v164
	v_cndmask_b32_e32 v70, v70, v171, vcc
	v_cmp_gt_i32_e32 vcc, v162, v186
	v_add_u32_e32 v165, 50, v209
	v_add_u32_e32 v165, s24, v165
	v_cndmask_b32_e32 v71, v71, v171, vcc
	v_cmp_gt_i32_e32 vcc, v163, v186
	v_add_u32_e32 v166, 51, v209
	v_add_u32_e32 v166, s24, v166
	v_cndmask_b32_e32 v72, v72, v171, vcc
	v_cmp_gt_i32_e32 vcc, v164, v186
	v_add_u32_e32 v167, 56, v209
	v_add_u32_e32 v167, s24, v167
	v_cndmask_b32_e32 v73, v73, v171, vcc
	v_cmp_gt_i32_e32 vcc, v165, v186
	v_add_u32_e32 v168, 57, v209
	v_add_u32_e32 v168, s24, v168
	v_cndmask_b32_e32 v74, v74, v171, vcc
	v_cmp_gt_i32_e32 vcc, v166, v186
	v_add_u32_e32 v169, 58, v209
	v_add_u32_e32 v169, s24, v169
	v_cndmask_b32_e32 v75, v75, v171, vcc
	v_cmp_gt_i32_e32 vcc, v167, v186
	v_add_u32_e32 v170, 59, v209
	v_add_u32_e32 v170, s24, v170
	v_cndmask_b32_e32 v76, v76, v171, vcc
	v_cmp_gt_i32_e32 vcc, v168, v186
	v_cndmask_b32_e64 v64, v64, v171, s[6:7]
	s_nop 0
	v_cndmask_b32_e32 v77, v77, v171, vcc
	v_cmp_gt_i32_e32 vcc, v169, v186
	s_nop 1
	v_cndmask_b32_e32 v78, v78, v171, vcc
	v_cmp_gt_i32_e32 vcc, v170, v186
	s_nop 1
	v_cndmask_b32_e32 v79, v79, v171, vcc

; __device__ __forceinline__ unsigned pk2(float lo, float hi) { f32x2_t v = {lo, hi}; bf16x2_t b = __builtin_convertvector(v, bf16x2_t); return __builtin_bit_cast(unsigned, b); }
; #define SCHED_BAR() __builtin_amdgcn_sched_barrier(0)
; __device__ __forceinline__ void mma_pv(const bf16x8 (&vf)[2][2], const f32x16& p, f32x16 (&O)[2]) {
;     bf16x8 pf[2];
; #pragma unroll
;     for (int s = 0; s < 2; ++s) { u32x4 w; w.x = pk2(p[8 * s], p[8 * s + 1]); w.y = pk2(p[8 * s + 2], p[8 * s + 3]); w.z = pk2(p[8 * s + 4], p[8 * s + 5]); w.w = pk2(p[8 * s + 6], p[8 * s + 7]); pf[s] = __builtin_bit_cast(bf16x8, w); }
; #pragma unroll
;     for (int d = 0; d < 2; ++d)
; #pragma unroll
;         for (int s = 0; s < 2; ++s) { __builtin_amdgcn_s_setprio(1); O[d] = __builtin_amdgcn_mfma_f32_32x32x16_bf16(vf[d][s], pf[s], O[d], 0, 0, 0); __builtin_amdgcn_s_setprio(0); }
; }
; __device__ __forceinline__ void mla_unit(unsigned char* ws, LAS unsigned char* kvb, int bl, int hd, int qt, int tid, int wave, int lane) {
;     ...
;             sm_fast2(s, t, C_MLA, m, l, O);
;             bf16x8 vg[2][2]; load_v(vb + 64, vg); SCHED_BAR();
;             mma_pv(vf, s, O); mma_pv(vg, t, O); },
.LBB0_830:
	v_add_f32_e32 v180, v180, v201
	v_add_f32_e32 v180, v180, v202
	ds_read2_b64 v[202:205], v109 offset0:72 offset1:74
	ds_read2_b64 v[210:213], v109 offset0:76 offset1:78
	ds_read2_b64 v[226:229], v108 offset0:104 offset1:106
	ds_read2_b64 v[230:233], v108 offset0:108 offset1:110
	v_cvt_pk_bf16_f32 v236, v163, v164
	v_cvt_pk_bf16_f32 v237, v167, v168
	v_cvt_pk_bf16_f32 v238, v171, v172
	v_cvt_pk_bf16_f32 v239, v175, v176
	v_cvt_pk_bf16_f32 v244, v179, v196
	v_cvt_pk_bf16_f32 v245, v194, v195
	v_cvt_pk_bf16_f32 v246, v181, v182
	v_cvt_pk_bf16_f32 v247, v183, v198
	s_setprio 1
	s_waitcnt lgkmcnt(7)
	v_mfma_f32_32x32x16_bf16 v[48:63], v[104:107], v[236:239], v[48:63]
	s_waitcnt lgkmcnt(6)
	v_mfma_f32_32x32x16_bf16 v[48:63], v[100:103], v[244:247], v[48:63]
	s_waitcnt lgkmcnt(5)
	v_mfma_f32_32x32x16_bf16 v[64:79], v[96:99], v[236:239], v[64:79]
	s_waitcnt lgkmcnt(4)
	v_mfma_f32_32x32x16_bf16 v[64:79], v[92:95], v[244:247], v[64:79]
	s_setprio 0
	v_cvt_pk_bf16_f32 v92, v15, v110
	v_cvt_pk_bf16_f32 v93, v111, v160
	v_cvt_pk_bf16_f32 v94, v161, v162
	v_cvt_pk_bf16_f32 v95, v165, v166
	v_cvt_pk_bf16_f32 v96, v169, v170
	v_cvt_pk_bf16_f32 v97, v173, v174
	v_cvt_pk_bf16_f32 v98, v177, v178
	v_cvt_pk_bf16_f32 v99, v199, v200
	s_setprio 1
	s_waitcnt lgkmcnt(3)
	v_mfma_f32_32x32x16_bf16 v[48:63], v[202:205], v[92:95], v[48:63]
	s_waitcnt lgkmcnt(2)
	v_mfma_f32_32x32x16_bf16 v[48:63], v[210:213], v[96:99], v[48:63]
	s_waitcnt lgkmcnt(1)
	v_mfma_f32_32x32x16_bf16 v[64:79], v[226:229], v[92:95], v[64:79]
	s_waitcnt lgkmcnt(0)
	v_mfma_f32_32x32x16_bf16 v[64:79], v[230:233], v[96:99], v[64:79]
	s_mov_b64 s[12:13], 0

; __device__ __forceinline__ unsigned pk2(float lo, float hi) { f32x2_t v = {lo, hi}; bf16x2_t b = __builtin_convertvector(v, bf16x2_t); return __builtin_bit_cast(unsigned, b); }
; __device__ __forceinline__ int kr16(int r, int h) { return (r & 3) + 8 * (r >> 2) + 4 * h; }
; #define SCHED_BAR() __builtin_amdgcn_sched_barrier(0)
; __device__ __forceinline__ void mma_pv(const bf16x8 (&vf)[2][2], const f32x16& p, f32x16 (&O)[2]) {
;     bf16x8 pf[2];
; #pragma unroll
;     for (int s = 0; s < 2; ++s) { u32x4 w; w.x = pk2(p[8 * s], p[8 * s + 1]); w.y = pk2(p[8 * s + 2], p[8 * s + 3]); w.z = pk2(p[8 * s + 4], p[8 * s + 5]); w.w = pk2(p[8 * s + 6], p[8 * s + 7]); pf[s] = __builtin_bit_cast(bf16x8, w); }
; #pragma unroll
;     for (int d = 0; d < 2; ++d)
; #pragma unroll
;         for (int s = 0; s < 2; ++s) { __builtin_amdgcn_s_setprio(1); O[d] = __builtin_amdgcn_mfma_f32_32x32x16_bf16(vf[d][s], pf[s], O[d], 0, 0, 0); __builtin_amdgcn_s_setprio(0); }
; }
; __device__ __forceinline__ void mla_unit(unsigned char* ws, LAS unsigned char* kvb, int bl, int hd, int qt, int tid, int wave, int lane) {
;     ...
;                 bf16x8 kf[6], vf[2][2]; load_k<6>(kb, kf); load_v(vb, vf); SCHED_BAR();
;                 f32x16 s = mma_qk<6>(kf, qf);
;                 unsigned valid = 0u;
; #pragma unroll
;                 for (int r = 0; r < 16; ++r) valid |= (k0 + kr16(r, h) <= qpos ? 1u : 0u) << r;
;                 mask_apply(s, valid);
;                 sm_fast(s, C_MLA, m, l, O); mma_pv(vf, s, O); return; }
.LBB0_834:
	v_add_f32_e32 v51, v51, v52
	v_add_f32_e32 v180, v51, v235
	v_cvt_pk_bf16_f32 v2, v2, v3
	v_cvt_pk_bf16_f32 v3, v4, v5
	v_cvt_pk_bf16_f32 v4, v6, v7
	v_cvt_pk_bf16_f32 v5, v8, v9
	v_cvt_pk_bf16_f32 v6, v10, v11
	v_cvt_pk_bf16_f32 v7, v12, v13
	v_cvt_pk_bf16_f32 v8, v15, v48
	v_cvt_pk_bf16_f32 v9, v49, v50
	s_setprio 1
	s_waitcnt lgkmcnt(3)
	v_mfma_f32_32x32x16_bf16 v[32:47], v[76:79], v[2:5], v[32:47]
	s_waitcnt lgkmcnt(2)
	v_mfma_f32_32x32x16_bf16 v[32:47], v[72:75], v[6:9], v[32:47]
	s_waitcnt lgkmcnt(1)
	v_mfma_f32_32x32x16_bf16 v[16:31], v[68:71], v[2:5], v[16:31]
	s_waitcnt lgkmcnt(0)
	v_mfma_f32_32x32x16_bf16 v[16:31], v[64:67], v[6:9], v[16:31]
	s_nop 3
	v_mov_b64_e32 v[62:63], v[46:47]
	v_mov_b64_e32 v[60:61], v[44:45]
	v_mov_b64_e32 v[58:59], v[42:43]
	v_mov_b64_e32 v[56:57], v[40:41]
	v_mov_b64_e32 v[54:55], v[38:39]
	v_mov_b64_e32 v[52:53], v[36:37]
	v_mov_b64_e32 v[50:51], v[34:35]
	s_nop 0
	v_mov_b64_e32 v[78:79], v[30:31]
	v_mov_b64_e32 v[48:49], v[32:33]
	v_mov_b64_e32 v[76:77], v[28:29]
	v_mov_b64_e32 v[74:75], v[26:27]
	v_mov_b64_e32 v[72:73], v[24:25]
	v_mov_b64_e32 v[70:71], v[22:23]
	v_mov_b64_e32 v[68:69], v[20:21]
	v_mov_b64_e32 v[66:67], v[18:19]
	v_mov_b64_e32 v[64:65], v[16:17]

; #define LAS __attribute__((address_space(3)))
; __device__ __forceinline__ unsigned pk2(float lo, float hi) { f32x2_t v = {lo, hi}; bf16x2_t b = __builtin_convertvector(v, bf16x2_t); return __builtin_bit_cast(unsigned, b); }
; __device__ __forceinline__ void mma_pv(const bf16x8 (&vf)[2][2], const f32x16& p, f32x16 (&O)[2]) {
;     bf16x8 pf[2];
; #pragma unroll
;     for (int s = 0; s < 2; ++s) { u32x4 w; w.x = pk2(p[8 * s], p[8 * s + 1]); w.y = pk2(p[8 * s + 2], p[8 * s + 3]); w.z = pk2(p[8 * s + 4], p[8 * s + 5]); w.w = pk2(p[8 * s + 6], p[8 * s + 7]); pf[s] = __builtin_bit_cast(bf16x8, w); }
; #pragma unroll
;     for (int d = 0; d < 2; ++d)
; #pragma unroll
;         for (int s = 0; s < 2; ++s) { __builtin_amdgcn_s_setprio(1); O[d] = __builtin_amdgcn_mfma_f32_32x32x16_bf16(vf[d][s], pf[s], O[d], 0, 0, 0); __builtin_amdgcn_s_setprio(0); }
; }
; __device__ __forceinline__ void nsa_unit(unsigned char* ws, LAS unsigned char* kvb, int bl, int g, int qt, int tid, int wave, int lane) {
;     ...
;             [&](int k0, LAS const unsigned char* buf) {
;                 const int j = k0 >> 6; const unsigned bit = (mysel >> j) & 1u;
;                 const unsigned long long bal = __ballot(bit);
;                 if (bal == 0ull) return;
;                 LAS const unsigned char* kb = buf + c * 144 + 16 * h; LAS const unsigned char* vb = buf + 64 * 144 + c * KV_VP + 8 * h;
;                 if (k0 + 32 > q0w + 31) {
;                     bf16x8 kf[4], vf[2][2]; load_k<4>(kb, kf); load_v(vb, vf); SCHED_BAR();
;                     f32x16 s = mma_qk<4>(kf, qf);
;                     unsigned cm = 0u;
; #pragma unroll
;                     for (int r = 0; r < 16; ++r) cm |= (k0 + kr16(r, h) <= qpos ? 1u : 0u) << r;
;                     mask_apply(s, bit ? cm : 0u);
;                     sm_fast(s, C_NSA, m, l, O); mma_pv(vf, s, O); return; }
;                 bf16x8 kf[4], kg[4]; load_k<4>(kb, kf); load_k<4>(kb + 32 * 144, kg); SCHED_BAR();
;                 f32x16 s = mma_qk<4>(kf, qf), t = mma_qk<4>(kg, qf);
;                 bf16x8 vf[2][2]; load_v(vb, vf); SCHED_BAR();
;                 if (j == qt) { unsigned cm = 0u, cn = 0u;
; #pragma unroll
;                     for (int r = 0; r < 16; ++r) { cm |= (k0 + kr16(r, h) <= qpos ? 1u : 0u) << r; cn |= (k0 + 32 + kr16(r, h) <= qpos ? 1u : 0u) << r; }
;                     mask_apply(s, cm); mask_apply(t, cn); }
.LBB0_865:
	v_add_f32_e32 v180, v180, v200
	v_add_f32_e32 v180, v180, v201
	v_cvt_pk_bf16_f32 v200, v181, v182
	v_cvt_pk_bf16_f32 v201, v183, v186
	v_cvt_pk_bf16_f32 v202, v187, v188
	v_cvt_pk_bf16_f32 v203, v189, v190
	v_cvt_pk_bf16_f32 v186, v191, v192
	v_cvt_pk_bf16_f32 v187, v193, v194
	v_cvt_pk_bf16_f32 v188, v195, v196
	v_cvt_pk_bf16_f32 v189, v198, v199
	s_setprio 1
	s_waitcnt lgkmcnt(3)
	v_mfma_f32_32x32x16_bf16 v[34:49], v[128:131], v[200:203], v[34:49]
	s_waitcnt lgkmcnt(2)
	v_mfma_f32_32x32x16_bf16 v[34:49], v[124:127], v[186:189], v[34:49]
	s_waitcnt lgkmcnt(1)
	v_mfma_f32_32x32x16_bf16 v[50:65], v[120:123], v[200:203], v[50:65]
	s_waitcnt lgkmcnt(0)
	v_mfma_f32_32x32x16_bf16 v[50:65], v[116:119], v[186:189], v[50:65]
	s_mov_b64 s[16:17], 0
.LBB0_866:
	s_and_b64 vcc, exec, s[16:17]
	s_cbranch_vccz .LBB0_872
	s_nop 8
	ds_read_b128 v[50:53], v175 offset:4608
	ds_read_b128 v[116:119], v175 offset:4640
	ds_read_b128 v[120:123], v175 offset:4672
	ds_read_b128 v[124:127], v175 offset:4704
	s_setprio 1
	s_waitcnt lgkmcnt(7)
	v_mfma_f32_32x32x16_bf16 v[34:49], v[112:115], v[80:83], 0
	s_waitcnt lgkmcnt(6)
	v_mfma_f32_32x32x16_bf16 v[34:49], v[108:111], v[84:87], v[34:49]
	s_waitcnt lgkmcnt(5)
	v_mfma_f32_32x32x16_bf16 v[34:49], v[104:107], v[88:91], v[34:49]
	s_waitcnt lgkmcnt(4)
	v_mfma_f32_32x32x16_bf16 v[34:49], v[100:103], v[92:95], v[34:49]
	s_waitcnt lgkmcnt(3)
	v_mfma_f32_32x32x16_bf16 v[50:65], v[50:53], v[80:83], 0
	s_waitcnt lgkmcnt(2)
	v_mfma_f32_32x32x16_bf16 v[50:65], v[116:119], v[84:87], v[50:65]
	s_waitcnt lgkmcnt(1)
	v_mfma_f32_32x32x16_bf16 v[50:65], v[120:123], v[88:91], v[50:65]
	s_waitcnt lgkmcnt(0)
	v_mfma_f32_32x32x16_bf16 v[50:65], v[124:127], v[92:95], v[50:65]
	s_setprio 0
	ds_read2_b64 v[112:115], v178 offset0:128 offset1:130
	ds_read2_b64 v[108:111], v178 offset0:132 offset1:134
	ds_read2_b64 v[104:107], v177 offset0:160 offset1:162
	ds_read2_b64 v[100:103], v177 offset0:164 offset1:166
	s_cmp_lg_u32 s21, s97
	s_cbranch_scc1 .LBB0_869
	v_add_u32_e32 v116, s14, v132
	v_add_u32_e32 v118, s14, v153
	v_mov_b32_e32 v198, 0xff61b1e6
	v_cmp_gt_i32_e32 vcc, v116, v142
	v_add_u32_e32 v120, s14, v154
	v_add_u32_e32 v122, s14, v155
	v_cndmask_b32_e32 v34, v34, v198, vcc
	v_cmp_gt_i32_e32 vcc, v118, v142
	v_add_u32_e32 v124, s14, v156
	v_add_u32_e32 v126, s14, v157
	v_cndmask_b32_e32 v35, v35, v198, vcc
	v_cmp_gt_i32_e32 vcc, v120, v142
	v_add_u32_e32 v128, s14, v158
	v_add_u32_e32 v130, s14, v159
	v_cndmask_b32_e32 v36, v36, v198, vcc
	v_cmp_gt_i32_e32 vcc, v122, v142
	v_add_u32_e32 v180, s14, v162
	v_add_u32_e32 v182, s14, v163
	v_cndmask_b32_e32 v37, v37, v198, vcc
	v_cmp_gt_i32_e32 vcc, v124, v142
	v_add_u32_e32 v185, s14, v164
	v_add_u32_e32 v187, s14, v165
	v_cndmask_b32_e32 v38, v38, v198, vcc
	v_cmp_gt_i32_e32 vcc, v126, v142
	v_add_u32_e32 v189, s14, v166
	v_add_u32_e32 v191, s14, v167
	v_cndmask_b32_e32 v39, v39, v198, vcc
	v_cmp_gt_i32_e32 vcc, v128, v142
	v_add_u32_e32 v193, s14, v168
	s_add_i32 s0, s14, 32
	v_cndmask_b32_e32 v40, v40, v198, vcc
	v_cmp_gt_i32_e32 vcc, v130, v142
	v_add_u32_e32 v195, s14, v169
	v_add_u32_e32 v117, s0, v132
	v_cndmask_b32_e32 v41, v41, v198, vcc
	v_cmp_gt_i32_e32 vcc, v180, v142
	v_add_u32_e32 v119, s0, v153
	v_mov_b32_e32 v116, 0xff61b1e6
	v_cndmask_b32_e32 v42, v42, v198, vcc
	v_cmp_gt_i32_e32 vcc, v182, v142
	v_add_u32_e32 v121, s0, v154
	v_add_u32_e32 v123, s0, v155
	v_cndmask_b32_e32 v43, v43, v198, vcc
	v_cmp_gt_i32_e32 vcc, v185, v142
	v_add_u32_e32 v125, s0, v156
	v_add_u32_e32 v127, s0, v157
	v_cndmask_b32_e32 v44, v44, v198, vcc
	v_cmp_gt_i32_e32 vcc, v187, v142
	v_add_u32_e32 v129, s0, v158
	v_add_u32_e32 v131, s0, v159
	v_cndmask_b32_e32 v45, v45, v198, vcc
	v_cmp_gt_i32_e32 vcc, v189, v142
	v_add_u32_e32 v181, s0, v162
	v_add_u32_e32 v183, s0, v163
	v_cndmask_b32_e32 v46, v46, v198, vcc
	v_cmp_gt_i32_e32 vcc, v191, v142
	v_add_u32_e32 v186, s0, v164
	v_add_u32_e32 v188, s0, v165
	v_cndmask_b32_e32 v47, v47, v198, vcc
	v_cmp_gt_i32_e32 vcc, v193, v142
	v_add_u32_e32 v190, s0, v166
	v_add_u32_e32 v192, s0, v167
	v_cndmask_b32_e32 v48, v48, v198, vcc
	v_cmp_gt_i32_e32 vcc, v195, v142
	v_add_u32_e32 v194, s0, v168
	v_add_u32_e32 v196, s0, v169
	v_cndmask_b32_e32 v49, v49, v198, vcc
	v_cmp_gt_i32_e32 vcc, v117, v142
	s_nop 1
	v_cndmask_b32_e32 v50, v50, v116, vcc
	v_cmp_gt_i32_e32 vcc, v119, v142
	s_nop 1
	v_cndmask_b32_e32 v51, v51, v116, vcc
	v_cmp_gt_i32_e32 vcc, v121, v142
	s_nop 1
	v_cndmask_b32_e32 v52, v52, v116, vcc
	v_cmp_gt_i32_e32 vcc, v123, v142
	s_nop 1
	v_cndmask_b32_e32 v53, v53, v116, vcc
	v_cmp_gt_i32_e32 vcc, v125, v142
	s_nop 1
	v_cndmask_b32_e32 v54, v54, v116, vcc
	v_cmp_gt_i32_e32 vcc, v127, v142
	s_nop 1
	v_cndmask_b32_e32 v55, v55, v116, vcc
	v_cmp_gt_i32_e32 vcc, v129, v142
	s_nop 1
	v_cndmask_b32_e32 v56, v56, v116, vcc
	v_cmp_gt_i32_e32 vcc, v131, v142
	s_nop 1
	v_cndmask_b32_e32 v57, v57, v116, vcc
	v_cmp_gt_i32_e32 vcc, v181, v142
	s_nop 1
	v_cndmask_b32_e32 v58, v58, v116, vcc
	v_cmp_gt_i32_e32 vcc, v183, v142
	s_nop 1
	v_cndmask_b32_e32 v59, v59, v116, vcc
	v_cmp_gt_i32_e32 vcc, v186, v142
	s_nop 1
	v_cndmask_b32_e32 v60, v60, v116, vcc
	v_cmp_gt_i32_e32 vcc, v188, v142
	s_nop 1
	v_cndmask_b32_e32 v61, v61, v116, vcc
	v_cmp_gt_i32_e32 vcc, v190, v142
	s_nop 1
	v_cndmask_b32_e32 v62, v62, v116, vcc
	v_cmp_gt_i32_e32 vcc, v192, v142
	s_nop 1
	v_cndmask_b32_e32 v63, v63, v116, vcc
	v_cmp_gt_i32_e32 vcc, v194, v142
	s_nop 1
	v_cndmask_b32_e32 v64, v64, v116, vcc
	v_cmp_gt_i32_e32 vcc, v196, v142
	s_nop 1
	v_cndmask_b32_e32 v65, v65, v116, vcc

; __device__ __forceinline__ unsigned pk2(float lo, float hi) { f32x2_t v = {lo, hi}; bf16x2_t b = __builtin_convertvector(v, bf16x2_t); return __builtin_bit_cast(unsigned, b); }
; #define SCHED_BAR() __builtin_amdgcn_sched_barrier(0)
; __device__ __forceinline__ void mma_pv(const bf16x8 (&vf)[2][2], const f32x16& p, f32x16 (&O)[2]) {
;     bf16x8 pf[2];
; #pragma unroll
;     for (int s = 0; s < 2; ++s) { u32x4 w; w.x = pk2(p[8 * s], p[8 * s + 1]); w.y = pk2(p[8 * s + 2], p[8 * s + 3]); w.z = pk2(p[8 * s + 4], p[8 * s + 5]); w.w = pk2(p[8 * s + 6], p[8 * s + 7]); pf[s] = __builtin_bit_cast(bf16x8, w); }
; #pragma unroll
;     for (int d = 0; d < 2; ++d)
; #pragma unroll
;         for (int s = 0; s < 2; ++s) { __builtin_amdgcn_s_setprio(1); O[d] = __builtin_amdgcn_mfma_f32_32x32x16_bf16(vf[d][s], pf[s], O[d], 0, 0, 0); __builtin_amdgcn_s_setprio(0); }
; }
; __device__ __forceinline__ void nsa_unit(unsigned char* ws, LAS unsigned char* kvb, int bl, int g, int qt, int tid, int wave, int lane) {
;     ...
;                 sm_fast2_lane(s, t, C_NSA, m, l, O, bit != 0u);
;                 bf16x8 vg[2][2]; load_v(vb + 64, vg); SCHED_BAR();
;             mma_pv(vf, s, O); mma_pv(vg, t, O); },
.LBB0_871:
	ds_read2_b64 v[118:121], v178 offset0:136 offset1:138
	ds_read2_b64 v[122:125], v178 offset0:140 offset1:142
	ds_read2_b64 v[126:129], v177 offset0:168 offset1:170
	ds_read2_b64 v[186:189], v177 offset0:172 offset1:174
	v_add_f32_e32 v64, v64, v65
	v_add_f32_e32 v180, v64, v173
	v_cvt_pk_bf16_f32 v191, v50, v51
	v_cvt_pk_bf16_f32 v192, v52, v53
	v_cvt_pk_bf16_f32 v50, v56, v57
	v_cvt_pk_bf16_f32 v51, v58, v59
	v_cvt_pk_bf16_f32 v52, v60, v61
	v_cvt_pk_bf16_f32 v53, v62, v63
	v_cvt_pk_bf16_f32 v190, v116, v117
	v_cvt_pk_bf16_f32 v193, v54, v55
	s_setprio 1
	s_waitcnt lgkmcnt(7)
	v_mfma_f32_32x32x16_bf16 v[18:33], v[112:115], v[190:193], v[18:33]
	s_waitcnt lgkmcnt(6)
	v_mfma_f32_32x32x16_bf16 v[18:33], v[108:111], v[50:53], v[18:33]
	s_waitcnt lgkmcnt(5)
	v_mfma_f32_32x32x16_bf16 v[2:17], v[104:107], v[190:193], v[2:17]
	s_waitcnt lgkmcnt(4)
	v_mfma_f32_32x32x16_bf16 v[2:17], v[100:103], v[50:53], v[2:17]
	s_setprio 0
	v_cvt_pk_bf16_f32 v34, v34, v35
	v_cvt_pk_bf16_f32 v35, v36, v37
	v_cvt_pk_bf16_f32 v36, v38, v39
	v_cvt_pk_bf16_f32 v37, v40, v41
	v_cvt_pk_bf16_f32 v38, v42, v43
	v_cvt_pk_bf16_f32 v39, v44, v45
	v_cvt_pk_bf16_f32 v40, v46, v47
	v_cvt_pk_bf16_f32 v41, v48, v49
	s_setprio 1
	s_waitcnt lgkmcnt(3)
	v_mfma_f32_32x32x16_bf16 v[18:33], v[118:121], v[34:37], v[18:33]
	s_waitcnt lgkmcnt(2)
	v_mfma_f32_32x32x16_bf16 v[18:33], v[122:125], v[38:41], v[18:33]
	s_waitcnt lgkmcnt(1)
	v_mfma_f32_32x32x16_bf16 v[2:17], v[126:129], v[34:37], v[2:17]
	s_waitcnt lgkmcnt(0)
	v_mfma_f32_32x32x16_bf16 v[2:17], v[186:189], v[38:41], v[2:17]
	s_nop 3
	v_mov_b64_e32 v[48:49], v[32:33]
	v_mov_b64_e32 v[46:47], v[30:31]
	v_mov_b64_e32 v[44:45], v[28:29]
	v_mov_b64_e32 v[42:43], v[26:27]
	v_mov_b64_e32 v[40:41], v[24:25]
	v_mov_b64_e32 v[38:39], v[22:23]
	v_mov_b64_e32 v[36:37], v[20:21]
	s_nop 0
	v_mov_b64_e32 v[64:65], v[16:17]
	v_mov_b64_e32 v[62:63], v[14:15]
	v_mov_b64_e32 v[60:61], v[12:13]
	v_mov_b64_e32 v[58:59], v[10:11]
	v_mov_b64_e32 v[56:57], v[8:9]
	v_mov_b64_e32 v[54:55], v[6:7]
	v_mov_b64_e32 v[52:53], v[4:5]
	v_mov_b64_e32 v[50:51], v[2:3]
	v_mov_b64_e32 v[34:35], v[18:19]

; #define LAS __attribute__((address_space(3)))
; __device__ __forceinline__ unsigned pk2(float lo, float hi) { f32x2_t v = {lo, hi}; bf16x2_t b = __builtin_convertvector(v, bf16x2_t); return __builtin_bit_cast(unsigned, b); }
; __device__ __forceinline__ void mma_pv(const bf16x8 (&vf)[2][2], const f32x16& p, f32x16 (&O)[2]) {
;     bf16x8 pf[2];
; #pragma unroll
;     for (int s = 0; s < 2; ++s) { u32x4 w; w.x = pk2(p[8 * s], p[8 * s + 1]); w.y = pk2(p[8 * s + 2], p[8 * s + 3]); w.z = pk2(p[8 * s + 4], p[8 * s + 5]); w.w = pk2(p[8 * s + 6], p[8 * s + 7]); pf[s] = __builtin_bit_cast(bf16x8, w); }
; #pragma unroll
;     for (int d = 0; d < 2; ++d)
; #pragma unroll
;         for (int s = 0; s < 2; ++s) { __builtin_amdgcn_s_setprio(1); O[d] = __builtin_amdgcn_mfma_f32_32x32x16_bf16(vf[d][s], pf[s], O[d], 0, 0, 0); __builtin_amdgcn_s_setprio(0); }
; }
; __device__ __forceinline__ void nsa_unit(unsigned char* ws, LAS unsigned char* kvb, int bl, int g, int qt, int tid, int wave, int lane) {
;     ...
;             [&](int k0, LAS const unsigned char* buf) {
;                 const int j = k0 >> 6; const unsigned bit = (mysel >> j) & 1u;
;                 const unsigned long long bal = __ballot(bit);
;                 if (bal == 0ull) return;
;                 LAS const unsigned char* kb = buf + c * 144 + 16 * h; LAS const unsigned char* vb = buf + 64 * 144 + c * KV_VP + 8 * h;
;                 if (k0 + 32 > q0w + 31) {
;                     bf16x8 kf[4], vf[2][2]; load_k<4>(kb, kf); load_v(vb, vf); SCHED_BAR();
;                     f32x16 s = mma_qk<4>(kf, qf);
;                     unsigned cm = 0u;
; #pragma unroll
;                     for (int r = 0; r < 16; ++r) cm |= (k0 + kr16(r, h) <= qpos ? 1u : 0u) << r;
;                     mask_apply(s, bit ? cm : 0u);
;                     sm_fast(s, C_NSA, m, l, O); mma_pv(vf, s, O); return; }
;                 bf16x8 kf[4], kg[4]; load_k<4>(kb, kf); load_k<4>(kb + 32 * 144, kg); SCHED_BAR();
;                 f32x16 s = mma_qk<4>(kf, qf), t = mma_qk<4>(kg, qf);
;                 bf16x8 vf[2][2]; load_v(vb, vf); SCHED_BAR();
;                 if (j == qt) { unsigned cm = 0u, cn = 0u;
; #pragma unroll
;                     for (int r = 0; r < 16; ++r) { cm |= (k0 + kr16(r, h) <= qpos ? 1u : 0u) << r; cn |= (k0 + 32 + kr16(r, h) <= qpos ? 1u : 0u) << r; }
;                     mask_apply(s, cm); mask_apply(t, cn); }
.LBB0_878:
	v_add_f32_e32 v180, v180, v199
	v_add_f32_e32 v180, v180, v200
	v_cvt_pk_bf16_f32 v200, v181, v182
	v_cvt_pk_bf16_f32 v201, v183, v185
	v_cvt_pk_bf16_f32 v202, v186, v187
	v_cvt_pk_bf16_f32 v203, v188, v189
	v_cvt_pk_bf16_f32 v186, v190, v191
	v_cvt_pk_bf16_f32 v187, v192, v193
	v_cvt_pk_bf16_f32 v188, v194, v195
	v_cvt_pk_bf16_f32 v189, v196, v198
	s_setprio 1
	s_waitcnt lgkmcnt(3)
	v_mfma_f32_32x32x16_bf16 v[34:49], v[128:131], v[200:203], v[34:49]
	s_waitcnt lgkmcnt(2)
	v_mfma_f32_32x32x16_bf16 v[34:49], v[124:127], v[186:189], v[34:49]
	s_waitcnt lgkmcnt(1)
	v_mfma_f32_32x32x16_bf16 v[50:65], v[120:123], v[200:203], v[50:65]
	s_waitcnt lgkmcnt(0)
	v_mfma_f32_32x32x16_bf16 v[50:65], v[116:119], v[186:189], v[50:65]
	s_mov_b64 s[12:13], 0
.LBB0_879:
	s_and_b64 vcc, exec, s[12:13]
	s_cbranch_vccz .LBB0_885
	s_nop 8
	ds_read_b128 v[50:53], v175 offset:22528
	ds_read_b128 v[116:119], v175 offset:22560
	ds_read_b128 v[120:123], v175 offset:22592
	ds_read_b128 v[124:127], v175 offset:22624
	s_setprio 1
	s_waitcnt lgkmcnt(7)
	v_mfma_f32_32x32x16_bf16 v[34:49], v[112:115], v[80:83], 0
	s_waitcnt lgkmcnt(6)
	v_mfma_f32_32x32x16_bf16 v[34:49], v[108:111], v[84:87], v[34:49]
	s_waitcnt lgkmcnt(5)
	v_mfma_f32_32x32x16_bf16 v[34:49], v[104:107], v[88:91], v[34:49]
	s_waitcnt lgkmcnt(4)
	v_mfma_f32_32x32x16_bf16 v[34:49], v[100:103], v[92:95], v[34:49]
	s_waitcnt lgkmcnt(3)
	v_mfma_f32_32x32x16_bf16 v[50:65], v[50:53], v[80:83], 0
	s_waitcnt lgkmcnt(2)
	v_mfma_f32_32x32x16_bf16 v[50:65], v[116:119], v[84:87], v[50:65]
	s_waitcnt lgkmcnt(1)
	v_mfma_f32_32x32x16_bf16 v[50:65], v[120:123], v[88:91], v[50:65]
	s_waitcnt lgkmcnt(0)
	v_mfma_f32_32x32x16_bf16 v[50:65], v[124:127], v[92:95], v[50:65]
	s_setprio 0
	ds_read2_b64 v[112:115], v177 offset0:64 offset1:66
	ds_read2_b64 v[108:111], v177 offset0:68 offset1:70
	ds_read2_b64 v[104:107], v176 offset0:96 offset1:98
	ds_read2_b64 v[100:103], v176 offset0:100 offset1:102
	s_cmp_lg_u32 s2, s97
	s_cbranch_scc1 .LBB0_882
	v_add_u32_e32 v116, s10, v132
	v_add_u32_e32 v118, s10, v153
	v_mov_b32_e32 v195, 0xff61b1e6
	v_cmp_gt_i32_e32 vcc, v116, v142
	v_add_u32_e32 v120, s10, v154
	v_add_u32_e32 v122, s10, v155
	v_cndmask_b32_e32 v34, v34, v195, vcc
	v_cmp_gt_i32_e32 vcc, v118, v142
	v_add_u32_e32 v124, s10, v156
	v_add_u32_e32 v126, s10, v157
	v_cndmask_b32_e32 v35, v35, v195, vcc
	v_cmp_gt_i32_e32 vcc, v120, v142
	v_add_u32_e32 v128, s10, v158
	v_add_u32_e32 v130, s10, v159
	v_cndmask_b32_e32 v36, v36, v195, vcc
	v_cmp_gt_i32_e32 vcc, v122, v142
	v_add_u32_e32 v175, s10, v162
	v_add_u32_e32 v180, s10, v163
	v_cndmask_b32_e32 v37, v37, v195, vcc
	v_cmp_gt_i32_e32 vcc, v124, v142
	v_add_u32_e32 v182, s10, v164
	v_add_u32_e32 v185, s10, v165
	v_cndmask_b32_e32 v38, v38, v195, vcc
	v_cmp_gt_i32_e32 vcc, v126, v142
	v_add_u32_e32 v187, s10, v166
	v_add_u32_e32 v189, s10, v167
	v_cndmask_b32_e32 v39, v39, v195, vcc
	v_cmp_gt_i32_e32 vcc, v128, v142
	v_add_u32_e32 v191, s10, v168
	s_add_i32 s0, s10, 32
	v_cndmask_b32_e32 v40, v40, v195, vcc
	v_cmp_gt_i32_e32 vcc, v130, v142
	v_add_u32_e32 v193, s10, v169
	v_add_u32_e32 v117, s0, v132
	v_cndmask_b32_e32 v41, v41, v195, vcc
	v_cmp_gt_i32_e32 vcc, v175, v142
	v_add_u32_e32 v119, s0, v153
	v_mov_b32_e32 v116, 0xff61b1e6
	v_cndmask_b32_e32 v42, v42, v195, vcc
	v_cmp_gt_i32_e32 vcc, v180, v142
	v_add_u32_e32 v121, s0, v154
	v_add_u32_e32 v123, s0, v155
	v_cndmask_b32_e32 v43, v43, v195, vcc
	v_cmp_gt_i32_e32 vcc, v182, v142
	v_add_u32_e32 v125, s0, v156
	v_add_u32_e32 v127, s0, v157
	v_cndmask_b32_e32 v44, v44, v195, vcc
	v_cmp_gt_i32_e32 vcc, v185, v142
	v_add_u32_e32 v129, s0, v158
	v_add_u32_e32 v131, s0, v159
	v_cndmask_b32_e32 v45, v45, v195, vcc
	v_cmp_gt_i32_e32 vcc, v187, v142
	v_add_u32_e32 v179, s0, v162
	v_add_u32_e32 v181, s0, v163
	v_cndmask_b32_e32 v46, v46, v195, vcc
	v_cmp_gt_i32_e32 vcc, v189, v142
	v_add_u32_e32 v183, s0, v164
	v_add_u32_e32 v186, s0, v165
	v_cndmask_b32_e32 v47, v47, v195, vcc
	v_cmp_gt_i32_e32 vcc, v191, v142
	v_add_u32_e32 v188, s0, v166
	v_add_u32_e32 v190, s0, v167
	v_cndmask_b32_e32 v48, v48, v195, vcc
	v_cmp_gt_i32_e32 vcc, v193, v142
	v_add_u32_e32 v192, s0, v168
	v_add_u32_e32 v194, s0, v169
	v_cndmask_b32_e32 v49, v49, v195, vcc
	v_cmp_gt_i32_e32 vcc, v117, v142
	s_nop 1
	v_cndmask_b32_e32 v50, v50, v116, vcc
	v_cmp_gt_i32_e32 vcc, v119, v142
	s_nop 1
	v_cndmask_b32_e32 v51, v51, v116, vcc
	v_cmp_gt_i32_e32 vcc, v121, v142
	s_nop 1
	v_cndmask_b32_e32 v52, v52, v116, vcc
	v_cmp_gt_i32_e32 vcc, v123, v142
	s_nop 1
	v_cndmask_b32_e32 v53, v53, v116, vcc
	v_cmp_gt_i32_e32 vcc, v125, v142
	s_nop 1
	v_cndmask_b32_e32 v54, v54, v116, vcc
	v_cmp_gt_i32_e32 vcc, v127, v142
	s_nop 1
	v_cndmask_b32_e32 v55, v55, v116, vcc
	v_cmp_gt_i32_e32 vcc, v129, v142
	s_nop 1
	v_cndmask_b32_e32 v56, v56, v116, vcc
	v_cmp_gt_i32_e32 vcc, v131, v142
	s_nop 1
	v_cndmask_b32_e32 v57, v57, v116, vcc
	v_cmp_gt_i32_e32 vcc, v179, v142
	s_nop 1
	v_cndmask_b32_e32 v58, v58, v116, vcc
	v_cmp_gt_i32_e32 vcc, v181, v142
	s_nop 1
	v_cndmask_b32_e32 v59, v59, v116, vcc
	v_cmp_gt_i32_e32 vcc, v183, v142
	s_nop 1
	v_cndmask_b32_e32 v60, v60, v116, vcc
	v_cmp_gt_i32_e32 vcc, v186, v142
	s_nop 1
	v_cndmask_b32_e32 v61, v61, v116, vcc
	v_cmp_gt_i32_e32 vcc, v188, v142
	s_nop 1
	v_cndmask_b32_e32 v62, v62, v116, vcc
	v_cmp_gt_i32_e32 vcc, v190, v142
	s_nop 1
	v_cndmask_b32_e32 v63, v63, v116, vcc
	v_cmp_gt_i32_e32 vcc, v192, v142
	s_nop 1
	v_cndmask_b32_e32 v64, v64, v116, vcc
	v_cmp_gt_i32_e32 vcc, v194, v142
	s_nop 1
	v_cndmask_b32_e32 v65, v65, v116, vcc

; __device__ __forceinline__ unsigned pk2(float lo, float hi) { f32x2_t v = {lo, hi}; bf16x2_t b = __builtin_convertvector(v, bf16x2_t); return __builtin_bit_cast(unsigned, b); }
; #define SCHED_BAR() __builtin_amdgcn_sched_barrier(0)
; __device__ __forceinline__ void mma_pv(const bf16x8 (&vf)[2][2], const f32x16& p, f32x16 (&O)[2]) {
;     bf16x8 pf[2];
; #pragma unroll
;     for (int s = 0; s < 2; ++s) { u32x4 w; w.x = pk2(p[8 * s], p[8 * s + 1]); w.y = pk2(p[8 * s + 2], p[8 * s + 3]); w.z = pk2(p[8 * s + 4], p[8 * s + 5]); w.w = pk2(p[8 * s + 6], p[8 * s + 7]); pf[s] = __builtin_bit_cast(bf16x8, w); }
; #pragma unroll
;     for (int d = 0; d < 2; ++d)
; #pragma unroll
;         for (int s = 0; s < 2; ++s) { __builtin_amdgcn_s_setprio(1); O[d] = __builtin_amdgcn_mfma_f32_32x32x16_bf16(vf[d][s], pf[s], O[d], 0, 0, 0); __builtin_amdgcn_s_setprio(0); }
; }
; __device__ __forceinline__ void nsa_unit(unsigned char* ws, LAS unsigned char* kvb, int bl, int g, int qt, int tid, int wave, int lane) {
;     ...
;                 sm_fast2_lane(s, t, C_NSA, m, l, O, bit != 0u);
;                 bf16x8 vg[2][2]; load_v(vb + 64, vg); SCHED_BAR();
;             mma_pv(vf, s, O); mma_pv(vg, t, O); },
.LBB0_884:
	ds_read2_b64 v[118:121], v177 offset0:72 offset1:74
	ds_read2_b64 v[122:125], v177 offset0:76 offset1:78
	ds_read2_b64 v[126:129], v176 offset0:104 offset1:106
	ds_read2_b64 v[174:177], v176 offset0:108 offset1:110
	v_add_f32_e32 v64, v64, v65
	v_add_f32_e32 v180, v64, v173
	v_cvt_pk_bf16_f32 v187, v50, v51
	v_cvt_pk_bf16_f32 v188, v52, v53
	v_cvt_pk_bf16_f32 v50, v56, v57
	v_cvt_pk_bf16_f32 v51, v58, v59
	v_cvt_pk_bf16_f32 v52, v60, v61
	v_cvt_pk_bf16_f32 v53, v62, v63
	v_cvt_pk_bf16_f32 v186, v116, v117
	v_cvt_pk_bf16_f32 v189, v54, v55
	s_setprio 1
	s_waitcnt lgkmcnt(7)
	v_mfma_f32_32x32x16_bf16 v[18:33], v[112:115], v[186:189], v[18:33]
	s_waitcnt lgkmcnt(6)
	v_mfma_f32_32x32x16_bf16 v[18:33], v[108:111], v[50:53], v[18:33]
	s_waitcnt lgkmcnt(5)
	v_mfma_f32_32x32x16_bf16 v[2:17], v[104:107], v[186:189], v[2:17]
	s_waitcnt lgkmcnt(4)
	v_mfma_f32_32x32x16_bf16 v[2:17], v[100:103], v[50:53], v[2:17]
	s_setprio 0
	v_cvt_pk_bf16_f32 v34, v34, v35
	v_cvt_pk_bf16_f32 v35, v36, v37
	v_cvt_pk_bf16_f32 v36, v38, v39
	v_cvt_pk_bf16_f32 v37, v40, v41
	v_cvt_pk_bf16_f32 v38, v42, v43
	v_cvt_pk_bf16_f32 v39, v44, v45
	v_cvt_pk_bf16_f32 v40, v46, v47
	v_cvt_pk_bf16_f32 v41, v48, v49
	s_setprio 1
	s_waitcnt lgkmcnt(3)
	v_mfma_f32_32x32x16_bf16 v[18:33], v[118:121], v[34:37], v[18:33]
	s_waitcnt lgkmcnt(2)
	v_mfma_f32_32x32x16_bf16 v[18:33], v[122:125], v[38:41], v[18:33]
	s_waitcnt lgkmcnt(1)
	v_mfma_f32_32x32x16_bf16 v[2:17], v[126:129], v[34:37], v[2:17]
	s_waitcnt lgkmcnt(0)
	v_mfma_f32_32x32x16_bf16 v[2:17], v[174:177], v[38:41], v[2:17]
	s_nop 3
	v_mov_b64_e32 v[48:49], v[32:33]
	v_mov_b64_e32 v[46:47], v[30:31]
	v_mov_b64_e32 v[44:45], v[28:29]
	v_mov_b64_e32 v[42:43], v[26:27]
	v_mov_b64_e32 v[40:41], v[24:25]
	v_mov_b64_e32 v[38:39], v[22:23]
	v_mov_b64_e32 v[36:37], v[20:21]
	s_nop 0
	v_mov_b64_e32 v[64:65], v[16:17]
	v_mov_b64_e32 v[62:63], v[14:15]
	v_mov_b64_e32 v[60:61], v[12:13]
	v_mov_b64_e32 v[58:59], v[10:11]
	v_mov_b64_e32 v[56:57], v[8:9]
	v_mov_b64_e32 v[54:55], v[6:7]
	v_mov_b64_e32 v[52:53], v[4:5]
	v_mov_b64_e32 v[50:51], v[2:3]
	v_mov_b64_e32 v[34:35], v[18:19]

; #define LAS __attribute__((address_space(3)))
; __device__ __forceinline__ int kr16(int r, int h) { return (r & 3) + 8 * (r >> 2) + 4 * h; }
; #define SCHED_BAR() __builtin_amdgcn_sched_barrier(0)
; __device__ __forceinline__ void nsa_unit(unsigned char* ws, LAS unsigned char* kvb, int bl, int g, int qt, int tid, int wave, int lane) {
;     ...
;                 const bool none0 = (k0 > q0w + 31) || (q0w - (k0 + 31) >= 512), none1 = (k0 + 32 > q0w + 31) || (q0w - (k0 + 63) >= 512);
;                 const bool full0 = (k0 + 31 <= q0w) && (q0w + 31 - k0 < 512), full1 = (k0 + 63 <= q0w) && (q0w - 1 - k0 < 512);
;                 LAS const unsigned char* kb = buf + c * 144 + 16 * h; LAS const unsigned char* vb = buf + 64 * 144 + c * KV_VP + 8 * h;
;                 if (none0 && none1) return;
;                 if (none0 || none1) {
;                     const int o = none0 ? 32 : 0;
;                     bf16x8 kf[4], vf[2][2]; load_k<4>(kb + o * 144, kf); load_v(vb + 2 * o, vf); SCHED_BAR();
;                     f32x16 s = mma_qk<4>(kf, qf);
;                     if (!(none0 ? full1 : full0)) { unsigned valid = 0u;
; #pragma unroll
;                         for (int r = 0; r < 16; ++r) { const int dist = qpos - (k0 + o + kr16(r, h)); valid |= ((dist >= 0 && dist < 512) ? 1u : 0u) << r; }
;                         mask_apply(s, valid); }
;                     sm_fast(s, C_NSA, m, l, O); mma_pv(vf, s, O); return; }
;                 bf16x8 kf[4], kg[4]; load_k<4>(kb, kf); load_k<4>(kb + 32 * 144, kg); SCHED_BAR();
;                 f32x16 s = mma_qk<4>(kf, qf), t = mma_qk<4>(kg, qf);
;                 bf16x8 vf[2][2]; load_v(vb, vf); SCHED_BAR();
;                 if (!full0) { unsigned valid = 0u;
; #pragma unroll
;                     for (int r = 0; r < 16; ++r) { const int dist = qpos - (k0 + kr16(r, h)); valid |= ((dist >= 0 && dist < 512) ? 1u : 0u) << r; }
;                     mask_apply(s, valid); }
.LBB0_902:
	s_cmp_gt_i32 s14, s11
	s_cselect_b64 s[0:1], -1, 0
	s_or_b32 s2, s14, 31
	s_cmp_lt_i32 s2, s22
	s_cselect_b64 s[4:5], -1, 0
	s_or_b64 s[4:5], s[0:1], s[4:5]
	s_cmp_ge_i32 s14, s89
	s_cselect_b64 s[0:1], -1, 0
	s_or_b32 s7, s14, 63
	s_cmp_lt_i32 s7, s22
	s_cselect_b64 s[16:17], -1, 0
	s_or_b64 s[18:19], s[0:1], s[16:17]
	s_and_b64 s[0:1], s[4:5], s[18:19]
	v_add3_u32 v15, v2, v144, v145
	v_add3_u32 v14, v2, v120, v184
	s_and_b64 vcc, exec, s[0:1]
	s_cbranch_vccnz .LBB0_918
	s_cmp_le_i32 s2, s89
	s_cselect_b64 s[0:1], -1, 0
	s_cmp_gt_i32 s14, s23
	s_cselect_b64 s[16:17], -1, 0
	s_and_b64 s[16:17], s[0:1], s[16:17]
	s_cmp_le_i32 s7, s89
	s_cselect_b64 s[0:1], -1, 0
	s_sub_i32 s2, s14, s89
	s_cmpk_gt_i32 s2, 0xfdff
	s_cselect_b64 s[26:27], -1, 0
	s_or_b64 s[18:19], s[4:5], s[18:19]
	s_mov_b64 s[20:21], -1
	s_andn2_b64 vcc, exec, s[18:19]
	s_and_b64 s[18:19], s[0:1], s[26:27]
	s_cbranch_vccz .LBB0_911
	ds_read_b128 v[2:5], v15
	ds_read_b128 v[6:9], v15 offset:32
	ds_read_b128 v[10:13], v15 offset:64
	ds_read_b128 v[64:67], v15 offset:96
	ds_read_b128 v[68:71], v15 offset:4608
	ds_read_b128 v[112:115], v15 offset:4640
	ds_read_b128 v[180:183], v15 offset:4672
	ds_read_b128 v[188:191], v15 offset:4704
	s_xor_b64 s[0:1], s[16:17], -1
	s_setprio 1
	s_waitcnt lgkmcnt(7)
	v_mfma_f32_32x32x16_bf16 v[48:63], v[2:5], v[80:83], 0
	s_waitcnt lgkmcnt(6)
	v_mfma_f32_32x32x16_bf16 v[48:63], v[6:9], v[84:87], v[48:63]
	s_waitcnt lgkmcnt(5)
	v_mfma_f32_32x32x16_bf16 v[48:63], v[10:13], v[88:91], v[48:63]
	s_waitcnt lgkmcnt(4)
	v_mfma_f32_32x32x16_bf16 v[48:63], v[64:67], v[92:95], v[48:63]
	s_waitcnt lgkmcnt(3)
	v_mfma_f32_32x32x16_bf16 v[64:79], v[68:71], v[80:83], 0
	s_waitcnt lgkmcnt(2)
	v_mfma_f32_32x32x16_bf16 v[64:79], v[112:115], v[84:87], v[64:79]
	s_waitcnt lgkmcnt(1)
	v_mfma_f32_32x32x16_bf16 v[64:79], v[180:183], v[88:91], v[64:79]
	s_waitcnt lgkmcnt(0)
	v_mfma_f32_32x32x16_bf16 v[64:79], v[188:191], v[92:95], v[64:79]
	s_setprio 0
	v_add_u32_e32 v190, 0x2000, v14
	v_add_u32_e32 v189, 0x3000, v14
	ds_read2_b64 v[112:115], v190 offset0:128 offset1:130
	ds_read2_b64 v[10:13], v190 offset0:132 offset1:134
	ds_read2_b64 v[6:9], v189 offset0:160 offset1:162
	ds_read2_b64 v[2:5], v189 offset0:164 offset1:166
	s_andn2_b64 vcc, exec, s[0:1]
	v_subrev_u32_e32 v180, s14, v142
	s_cbranch_vccnz .LBB0_906
	v_add_u32_e32 v181, v180, v121
	s_movk_i32 s0, 0x200
	v_sub_u32_e32 v182, s14, v122
	v_mov_b32_e32 v204, 0xff61b1e6
	v_cmp_gt_u32_e32 vcc, s0, v181
	s_movk_i32 s1, 0xfe00
	v_add_u32_e32 v183, v180, v123
	v_add_u32_e32 v188, v180, v124
	v_cndmask_b32_e32 v48, v204, v48, vcc
	v_cmp_gt_u32_e32 vcc, s1, v182
	s_movk_i32 s1, 0x1ff
	v_add_u32_e32 v191, v180, v125
	v_cndmask_b32_e32 v49, v49, v204, vcc
	v_cmp_lt_u32_e32 vcc, s1, v183
	v_add_u32_e32 v192, v180, v126
	v_add_u32_e32 v193, v180, v127
	v_cndmask_b32_e32 v50, v50, v204, vcc
	v_cmp_lt_u32_e32 vcc, s1, v188
	v_add_u32_e32 v194, v180, v128
	v_add_u32_e32 v195, v180, v129
	v_cndmask_b32_e32 v51, v51, v204, vcc
	v_cmp_lt_u32_e32 vcc, s1, v191
	v_add_u32_e32 v196, v180, v130
	v_add_u32_e32 v198, v180, v131
	v_cndmask_b32_e32 v52, v52, v204, vcc
	v_cmp_lt_u32_e32 vcc, s1, v192
	v_add_u32_e32 v199, v180, v134
	v_add_u32_e32 v200, v180, v135
	v_cndmask_b32_e32 v53, v53, v204, vcc
	v_cmp_lt_u32_e32 vcc, s1, v193
	v_add_u32_e32 v201, v180, v136
	v_add_u32_e32 v202, v180, v137
	v_cndmask_b32_e32 v54, v54, v204, vcc
	v_cmp_lt_u32_e32 vcc, s1, v194
	v_add_u32_e32 v203, v180, v138
	s_nop 0
	v_cndmask_b32_e32 v55, v55, v204, vcc
	v_cmp_gt_u32_e32 vcc, s0, v195
	s_nop 1
	v_cndmask_b32_e32 v56, v204, v56, vcc
	v_cmp_gt_u32_e32 vcc, s0, v196
	s_nop 1
	v_cndmask_b32_e32 v57, v204, v57, vcc
	v_cmp_lt_u32_e32 vcc, s1, v198
	s_nop 1
	v_cndmask_b32_e32 v58, v58, v204, vcc
	v_cmp_lt_u32_e32 vcc, s1, v199
	s_nop 1
	v_cndmask_b32_e32 v59, v59, v204, vcc
	v_cmp_lt_u32_e32 vcc, s1, v200
	s_nop 1
	v_cndmask_b32_e32 v60, v60, v204, vcc
	v_cmp_lt_u32_e32 vcc, s1, v201
	s_nop 1
	v_cndmask_b32_e32 v61, v61, v204, vcc
	v_cmp_lt_u32_e32 vcc, s1, v202
	s_nop 1
	v_cndmask_b32_e32 v62, v62, v204, vcc
	v_cmp_lt_u32_e32 vcc, s1, v203
	s_nop 1
	v_cndmask_b32_e32 v63, v63, v204, vcc

; __device__ __forceinline__ unsigned pk2(float lo, float hi) { f32x2_t v = {lo, hi}; bf16x2_t b = __builtin_convertvector(v, bf16x2_t); return __builtin_bit_cast(unsigned, b); }
; #define SCHED_BAR() __builtin_amdgcn_sched_barrier(0)
; __device__ __forceinline__ void mma_pv(const bf16x8 (&vf)[2][2], const f32x16& p, f32x16 (&O)[2]) {
;     bf16x8 pf[2];
; #pragma unroll
;     for (int s = 0; s < 2; ++s) { u32x4 w; w.x = pk2(p[8 * s], p[8 * s + 1]); w.y = pk2(p[8 * s + 2], p[8 * s + 3]); w.z = pk2(p[8 * s + 4], p[8 * s + 5]); w.w = pk2(p[8 * s + 6], p[8 * s + 7]); pf[s] = __builtin_bit_cast(bf16x8, w); }
; #pragma unroll
;     for (int d = 0; d < 2; ++d)
; #pragma unroll
;         for (int s = 0; s < 2; ++s) { __builtin_amdgcn_s_setprio(1); O[d] = __builtin_amdgcn_mfma_f32_32x32x16_bf16(vf[d][s], pf[s], O[d], 0, 0, 0); __builtin_amdgcn_s_setprio(0); }
; }
; __device__ __forceinline__ void nsa_unit(unsigned char* ws, LAS unsigned char* kvb, int bl, int g, int qt, int tid, int wave, int lane) {
;     ...
;                 sm_fast2(s, t, C_NSA, m, l, O);
;                 bf16x8 vg[2][2]; load_v(vb + 64, vg); SCHED_BAR();
;             mma_pv(vf, s, O); mma_pv(vg, t, O); },
.LBB0_910:
	v_add_f32_e32 v180, v180, v205
	v_add_f32_e32 v180, v180, v222
	ds_read2_b64 v[222:225], v190 offset0:136 offset1:138
	ds_read2_b64 v[226:229], v190 offset0:140 offset1:142
	ds_read2_b64 v[230:233], v189 offset0:168 offset1:170
	ds_read2_b64 v[234:237], v189 offset0:172 offset1:174
	v_cvt_pk_bf16_f32 v238, v209, v210
	v_cvt_pk_bf16_f32 v239, v213, v214
	v_cvt_pk_bf16_f32 v240, v217, v218
	v_cvt_pk_bf16_f32 v241, v196, v199
	v_cvt_pk_bf16_f32 v242, v201, v202
	v_cvt_pk_bf16_f32 v243, v194, v195
	v_cvt_pk_bf16_f32 v244, v181, v182
	v_cvt_pk_bf16_f32 v245, v183, v198
	s_setprio 1
	s_waitcnt lgkmcnt(7)
	v_mfma_f32_32x32x16_bf16 v[48:63], v[112:115], v[238:241], v[48:63]
	s_waitcnt lgkmcnt(6)
	v_mfma_f32_32x32x16_bf16 v[48:63], v[10:13], v[242:245], v[48:63]
	s_waitcnt lgkmcnt(5)
	v_mfma_f32_32x32x16_bf16 v[64:79], v[6:9], v[238:241], v[64:79]
	s_waitcnt lgkmcnt(4)
	v_mfma_f32_32x32x16_bf16 v[64:79], v[2:5], v[242:245], v[64:79]
	s_setprio 0
	v_cvt_pk_bf16_f32 v2, v191, v192
	v_cvt_pk_bf16_f32 v3, v193, v206
	v_cvt_pk_bf16_f32 v4, v207, v208
	v_cvt_pk_bf16_f32 v5, v211, v212
	v_cvt_pk_bf16_f32 v6, v215, v216
	v_cvt_pk_bf16_f32 v7, v219, v220
	v_cvt_pk_bf16_f32 v8, v221, v200
	v_cvt_pk_bf16_f32 v9, v203, v204
	s_setprio 1
	s_waitcnt lgkmcnt(3)
	v_mfma_f32_32x32x16_bf16 v[48:63], v[222:225], v[2:5], v[48:63]
	s_waitcnt lgkmcnt(2)
	v_mfma_f32_32x32x16_bf16 v[48:63], v[226:229], v[6:9], v[48:63]
	s_waitcnt lgkmcnt(1)
	v_mfma_f32_32x32x16_bf16 v[64:79], v[230:233], v[2:5], v[64:79]
	s_waitcnt lgkmcnt(0)
	v_mfma_f32_32x32x16_bf16 v[64:79], v[234:237], v[6:9], v[64:79]
	s_mov_b64 s[20:21], 0
	v_mov_b64_e32 v[238:239], v[246:247]
	v_mov_b64_e32 v[240:241], v[248:249]
	v_mov_b32_e32 v242, v250

; __device__ __forceinline__ unsigned pk2(float lo, float hi) { f32x2_t v = {lo, hi}; bf16x2_t b = __builtin_convertvector(v, bf16x2_t); return __builtin_bit_cast(unsigned, b); }
; __device__ __forceinline__ int kr16(int r, int h) { return (r & 3) + 8 * (r >> 2) + 4 * h; }
; #define SCHED_BAR() __builtin_amdgcn_sched_barrier(0)
; __device__ __forceinline__ void mma_pv(const bf16x8 (&vf)[2][2], const f32x16& p, f32x16 (&O)[2]) {
;     bf16x8 pf[2];
; #pragma unroll
;     for (int s = 0; s < 2; ++s) { u32x4 w; w.x = pk2(p[8 * s], p[8 * s + 1]); w.y = pk2(p[8 * s + 2], p[8 * s + 3]); w.z = pk2(p[8 * s + 4], p[8 * s + 5]); w.w = pk2(p[8 * s + 6], p[8 * s + 7]); pf[s] = __builtin_bit_cast(bf16x8, w); }
; #pragma unroll
;     for (int d = 0; d < 2; ++d)
; #pragma unroll
;         for (int s = 0; s < 2; ++s) { __builtin_amdgcn_s_setprio(1); O[d] = __builtin_amdgcn_mfma_f32_32x32x16_bf16(vf[d][s], pf[s], O[d], 0, 0, 0); __builtin_amdgcn_s_setprio(0); }
; }
; __device__ __forceinline__ void nsa_unit(unsigned char* ws, LAS unsigned char* kvb, int bl, int g, int qt, int tid, int wave, int lane) {
;     ...
;                     bf16x8 kf[4], vf[2][2]; load_k<4>(kb + o * 144, kf); load_v(vb + 2 * o, vf); SCHED_BAR();
;                     f32x16 s = mma_qk<4>(kf, qf);
;                     if (!(none0 ? full1 : full0)) { unsigned valid = 0u;
; #pragma unroll
;                         for (int r = 0; r < 16; ++r) { const int dist = qpos - (k0 + o + kr16(r, h)); valid |= ((dist >= 0 && dist < 512) ? 1u : 0u) << r; }
;                         mask_apply(s, valid); }
;                     sm_fast(s, C_NSA, m, l, O); mma_pv(vf, s, O); return; }
.LBB0_916:
	v_add_f32_e32 v68, v68, v69
	v_add_f32_e32 v180, v68, v186
	v_cvt_pk_bf16_f32 v48, v48, v49
	v_cvt_pk_bf16_f32 v49, v50, v51
	v_cvt_pk_bf16_f32 v50, v52, v53
	v_cvt_pk_bf16_f32 v51, v54, v55
	v_cvt_pk_bf16_f32 v52, v56, v57
	v_cvt_pk_bf16_f32 v53, v58, v59
	v_cvt_pk_bf16_f32 v54, v60, v61
	v_cvt_pk_bf16_f32 v55, v62, v63
	s_setprio 1
	s_waitcnt lgkmcnt(3)
	v_mfma_f32_32x32x16_bf16 v[32:47], v[64:67], v[48:51], v[32:47]
	s_waitcnt lgkmcnt(2)
	v_mfma_f32_32x32x16_bf16 v[32:47], v[10:13], v[52:55], v[32:47]
	s_waitcnt lgkmcnt(1)
	v_mfma_f32_32x32x16_bf16 v[16:31], v[6:9], v[48:51], v[16:31]
	s_waitcnt lgkmcnt(0)
	v_mfma_f32_32x32x16_bf16 v[16:31], v[2:5], v[52:55], v[16:31]
	s_nop 3
	v_mov_b64_e32 v[62:63], v[46:47]
	v_mov_b64_e32 v[60:61], v[44:45]
	v_mov_b64_e32 v[58:59], v[42:43]
	v_mov_b64_e32 v[56:57], v[40:41]
	v_mov_b64_e32 v[54:55], v[38:39]
	v_mov_b64_e32 v[52:53], v[36:37]
	v_mov_b64_e32 v[50:51], v[34:35]
	s_nop 0
	v_mov_b64_e32 v[78:79], v[30:31]
	v_mov_b64_e32 v[76:77], v[28:29]
	v_mov_b64_e32 v[74:75], v[26:27]
	v_mov_b64_e32 v[72:73], v[24:25]
	v_mov_b64_e32 v[70:71], v[22:23]
	v_mov_b64_e32 v[68:69], v[20:21]
	v_mov_b64_e32 v[66:67], v[18:19]
	v_mov_b64_e32 v[64:65], v[16:17]
	v_mov_b64_e32 v[48:49], v[32:33]

; #define LAS __attribute__((address_space(3)))
; __device__ __forceinline__ int kr16(int r, int h) { return (r & 3) + 8 * (r >> 2) + 4 * h; }
; #define SCHED_BAR() __builtin_amdgcn_sched_barrier(0)
; __device__ __forceinline__ void nsa_unit(unsigned char* ws, LAS unsigned char* kvb, int bl, int g, int qt, int tid, int wave, int lane) {
;     ...
;             [&](int k0, LAS const unsigned char* buf) {
;                 const bool none0 = (k0 > q0w + 31) || (q0w - (k0 + 31) >= 512), none1 = (k0 + 32 > q0w + 31) || (q0w - (k0 + 63) >= 512);
;                 const bool full0 = (k0 + 31 <= q0w) && (q0w + 31 - k0 < 512), full1 = (k0 + 63 <= q0w) && (q0w - 1 - k0 < 512);
;                 LAS const unsigned char* kb = buf + c * 144 + 16 * h; LAS const unsigned char* vb = buf + 64 * 144 + c * KV_VP + 8 * h;
;                 if (none0 && none1) return;
;                 if (none0 || none1) {
;                     const int o = none0 ? 32 : 0;
;                     bf16x8 kf[4], vf[2][2]; load_k<4>(kb + o * 144, kf); load_v(vb + 2 * o, vf); SCHED_BAR();
;                     f32x16 s = mma_qk<4>(kf, qf);
;                     if (!(none0 ? full1 : full0)) { unsigned valid = 0u;
; #pragma unroll
;                         for (int r = 0; r < 16; ++r) { const int dist = qpos - (k0 + o + kr16(r, h)); valid |= ((dist >= 0 && dist < 512) ? 1u : 0u) << r; }
;                         mask_apply(s, valid); }
;                     sm_fast(s, C_NSA, m, l, O); mma_pv(vf, s, O); return; }
;                 bf16x8 kf[4], kg[4]; load_k<4>(kb, kf); load_k<4>(kb + 32 * 144, kg); SCHED_BAR();
;                 f32x16 s = mma_qk<4>(kf, qf), t = mma_qk<4>(kg, qf);
;                 bf16x8 vf[2][2]; load_v(vb, vf); SCHED_BAR();
;                 if (!full0) { unsigned valid = 0u;
; #pragma unroll
;                     for (int r = 0; r < 16; ++r) { const int dist = qpos - (k0 + kr16(r, h)); valid |= ((dist >= 0 && dist < 512) ? 1u : 0u) << r; }
;                     mask_apply(s, valid); }
.LBB0_918:
	s_andn2_b64 vcc, exec, s[12:13]
	s_cbranch_vccnz .LBB0_935
	s_cmp_gt_i32 s10, s11
	s_cselect_b64 s[0:1], -1, 0
	s_add_i32 s2, s10, 31
	s_cmp_lt_i32 s2, s22
	s_cselect_b64 s[4:5], -1, 0
	s_or_b64 s[4:5], s[0:1], s[4:5]
	s_cmp_ge_i32 s10, s89
	s_cselect_b64 s[0:1], -1, 0
	s_add_i32 s7, s10, 63
	s_cmp_lt_i32 s7, s22
	s_cselect_b64 s[12:13], -1, 0
	s_or_b64 s[14:15], s[0:1], s[12:13]
	s_and_b64 s[0:1], s[4:5], s[14:15]
	s_and_b64 vcc, exec, s[0:1]
	s_cbranch_vccnz .LBB0_935
	s_cmp_le_i32 s2, s89
	s_cselect_b64 s[0:1], -1, 0
	s_cmp_gt_i32 s10, s23
	s_cselect_b64 s[12:13], -1, 0
	s_and_b64 s[12:13], s[0:1], s[12:13]
	s_cmp_le_i32 s7, s89
	s_cselect_b64 s[0:1], -1, 0
	s_cmp_gt_i32 s10, s24
	s_cselect_b64 s[18:19], -1, 0
	s_or_b64 s[14:15], s[4:5], s[14:15]
	s_mov_b64 s[16:17], -1
	s_andn2_b64 vcc, exec, s[14:15]
	s_and_b64 s[14:15], s[18:19], s[0:1]
	s_cbranch_vccz .LBB0_928
	ds_read_b128 v[2:5], v15 offset:17920
	ds_read_b128 v[6:9], v15 offset:17952
	ds_read_b128 v[10:13], v15 offset:17984
	ds_read_b128 v[64:67], v15 offset:18016
	ds_read_b128 v[68:71], v15 offset:22528
	ds_read_b128 v[112:115], v15 offset:22560
	ds_read_b128 v[180:183], v15 offset:22592
	ds_read_b128 v[188:191], v15 offset:22624
	s_xor_b64 s[0:1], s[12:13], -1
	s_setprio 1
	s_waitcnt lgkmcnt(7)
	v_mfma_f32_32x32x16_bf16 v[48:63], v[2:5], v[80:83], 0
	s_waitcnt lgkmcnt(6)
	v_mfma_f32_32x32x16_bf16 v[48:63], v[6:9], v[84:87], v[48:63]
	s_waitcnt lgkmcnt(5)
	v_mfma_f32_32x32x16_bf16 v[48:63], v[10:13], v[88:91], v[48:63]
	s_waitcnt lgkmcnt(4)
	v_mfma_f32_32x32x16_bf16 v[48:63], v[64:67], v[92:95], v[48:63]
	s_waitcnt lgkmcnt(3)
	v_mfma_f32_32x32x16_bf16 v[64:79], v[68:71], v[80:83], 0
	s_waitcnt lgkmcnt(2)
	v_mfma_f32_32x32x16_bf16 v[64:79], v[112:115], v[84:87], v[64:79]
	s_waitcnt lgkmcnt(1)
	v_mfma_f32_32x32x16_bf16 v[64:79], v[180:183], v[88:91], v[64:79]
	s_waitcnt lgkmcnt(0)
	v_mfma_f32_32x32x16_bf16 v[64:79], v[188:191], v[92:95], v[64:79]
	s_setprio 0
	v_add_u32_e32 v190, 0x6800, v14
	v_add_u32_e32 v189, 0x7800, v14
	ds_read2_b64 v[112:115], v190 offset0:64 offset1:66
	ds_read2_b64 v[10:13], v190 offset0:68 offset1:70
	ds_read2_b64 v[6:9], v189 offset0:96 offset1:98
	ds_read2_b64 v[2:5], v189 offset0:100 offset1:102
	s_andn2_b64 vcc, exec, s[0:1]
	v_subrev_u32_e32 v180, s10, v142
	s_cbranch_vccnz .LBB0_923
	v_add_u32_e32 v181, v180, v121
	s_movk_i32 s0, 0x200
	v_sub_u32_e32 v182, s10, v122
	v_mov_b32_e32 v204, 0xff61b1e6
	v_cmp_gt_u32_e32 vcc, s0, v181
	s_movk_i32 s1, 0xfe00
	v_add_u32_e32 v183, v180, v123
	v_add_u32_e32 v188, v180, v124
	v_cndmask_b32_e32 v48, v204, v48, vcc
	v_cmp_gt_u32_e32 vcc, s1, v182
	s_movk_i32 s1, 0x1ff
	v_add_u32_e32 v191, v180, v125
	v_cndmask_b32_e32 v49, v49, v204, vcc
	v_cmp_lt_u32_e32 vcc, s1, v183
	v_add_u32_e32 v192, v180, v126
	v_add_u32_e32 v193, v180, v127
	v_cndmask_b32_e32 v50, v50, v204, vcc
	v_cmp_lt_u32_e32 vcc, s1, v188
	v_add_u32_e32 v194, v180, v128
	v_add_u32_e32 v195, v180, v129
	v_cndmask_b32_e32 v51, v51, v204, vcc
	v_cmp_lt_u32_e32 vcc, s1, v191
	v_add_u32_e32 v196, v180, v130
	v_add_u32_e32 v198, v180, v131
	v_cndmask_b32_e32 v52, v52, v204, vcc
	v_cmp_lt_u32_e32 vcc, s1, v192
	v_add_u32_e32 v199, v180, v134
	v_add_u32_e32 v200, v180, v135
	v_cndmask_b32_e32 v53, v53, v204, vcc
	v_cmp_lt_u32_e32 vcc, s1, v193
	v_add_u32_e32 v201, v180, v136
	v_add_u32_e32 v202, v180, v137
	v_cndmask_b32_e32 v54, v54, v204, vcc
	v_cmp_lt_u32_e32 vcc, s1, v194
	v_add_u32_e32 v203, v180, v138
	s_nop 0
	v_cndmask_b32_e32 v55, v55, v204, vcc
	v_cmp_gt_u32_e32 vcc, s0, v195
	s_nop 1
	v_cndmask_b32_e32 v56, v204, v56, vcc
	v_cmp_gt_u32_e32 vcc, s0, v196
	s_nop 1
	v_cndmask_b32_e32 v57, v204, v57, vcc
	v_cmp_lt_u32_e32 vcc, s1, v198
	s_nop 1
	v_cndmask_b32_e32 v58, v58, v204, vcc
	v_cmp_lt_u32_e32 vcc, s1, v199
	s_nop 1
	v_cndmask_b32_e32 v59, v59, v204, vcc
	v_cmp_lt_u32_e32 vcc, s1, v200
	s_nop 1
	v_cndmask_b32_e32 v60, v60, v204, vcc
	v_cmp_lt_u32_e32 vcc, s1, v201
	s_nop 1
	v_cndmask_b32_e32 v61, v61, v204, vcc
	v_cmp_lt_u32_e32 vcc, s1, v202
	s_nop 1
	v_cndmask_b32_e32 v62, v62, v204, vcc
	v_cmp_lt_u32_e32 vcc, s1, v203
	s_nop 1
	v_cndmask_b32_e32 v63, v63, v204, vcc

; __device__ __forceinline__ unsigned pk2(float lo, float hi) { f32x2_t v = {lo, hi}; bf16x2_t b = __builtin_convertvector(v, bf16x2_t); return __builtin_bit_cast(unsigned, b); }
; #define SCHED_BAR() __builtin_amdgcn_sched_barrier(0)
; __device__ __forceinline__ void mma_pv(const bf16x8 (&vf)[2][2], const f32x16& p, f32x16 (&O)[2]) {
;     bf16x8 pf[2];
; #pragma unroll
;     for (int s = 0; s < 2; ++s) { u32x4 w; w.x = pk2(p[8 * s], p[8 * s + 1]); w.y = pk2(p[8 * s + 2], p[8 * s + 3]); w.z = pk2(p[8 * s + 4], p[8 * s + 5]); w.w = pk2(p[8 * s + 6], p[8 * s + 7]); pf[s] = __builtin_bit_cast(bf16x8, w); }
; #pragma unroll
;     for (int d = 0; d < 2; ++d)
; #pragma unroll
;         for (int s = 0; s < 2; ++s) { __builtin_amdgcn_s_setprio(1); O[d] = __builtin_amdgcn_mfma_f32_32x32x16_bf16(vf[d][s], pf[s], O[d], 0, 0, 0); __builtin_amdgcn_s_setprio(0); }
; }
; __device__ __forceinline__ void nsa_unit(unsigned char* ws, LAS unsigned char* kvb, int bl, int g, int qt, int tid, int wave, int lane) {
;     ...
;                 sm_fast2(s, t, C_NSA, m, l, O);
;                 bf16x8 vg[2][2]; load_v(vb + 64, vg); SCHED_BAR();
;             mma_pv(vf, s, O); mma_pv(vg, t, O); },
.LBB0_927:
	v_add_f32_e32 v180, v180, v205
	v_add_f32_e32 v180, v180, v222
	ds_read2_b64 v[222:225], v190 offset0:72 offset1:74
	ds_read2_b64 v[226:229], v190 offset0:76 offset1:78
	ds_read2_b64 v[230:233], v189 offset0:104 offset1:106
	ds_read2_b64 v[234:237], v189 offset0:108 offset1:110
	v_cvt_pk_bf16_f32 v238, v209, v210
	v_cvt_pk_bf16_f32 v239, v213, v214
	v_cvt_pk_bf16_f32 v240, v217, v218
	v_cvt_pk_bf16_f32 v241, v196, v199
	v_cvt_pk_bf16_f32 v242, v201, v202
	v_cvt_pk_bf16_f32 v243, v194, v195
	v_cvt_pk_bf16_f32 v244, v181, v182
	v_cvt_pk_bf16_f32 v245, v183, v198
	s_setprio 1
	s_waitcnt lgkmcnt(7)
	v_mfma_f32_32x32x16_bf16 v[48:63], v[112:115], v[238:241], v[48:63]
	s_waitcnt lgkmcnt(6)
	v_mfma_f32_32x32x16_bf16 v[48:63], v[10:13], v[242:245], v[48:63]
	s_waitcnt lgkmcnt(5)
	v_mfma_f32_32x32x16_bf16 v[64:79], v[6:9], v[238:241], v[64:79]
	s_waitcnt lgkmcnt(4)
	v_mfma_f32_32x32x16_bf16 v[64:79], v[2:5], v[242:245], v[64:79]
	s_setprio 0
	v_cvt_pk_bf16_f32 v2, v191, v192
	v_cvt_pk_bf16_f32 v3, v193, v206
	v_cvt_pk_bf16_f32 v4, v207, v208
	v_cvt_pk_bf16_f32 v5, v211, v212
	v_cvt_pk_bf16_f32 v6, v215, v216
	v_cvt_pk_bf16_f32 v7, v219, v220
	v_cvt_pk_bf16_f32 v8, v221, v200
	v_cvt_pk_bf16_f32 v9, v203, v204
	s_setprio 1
	s_waitcnt lgkmcnt(3)
	v_mfma_f32_32x32x16_bf16 v[48:63], v[222:225], v[2:5], v[48:63]
	s_waitcnt lgkmcnt(2)
	v_mfma_f32_32x32x16_bf16 v[48:63], v[226:229], v[6:9], v[48:63]
	s_waitcnt lgkmcnt(1)
	v_mfma_f32_32x32x16_bf16 v[64:79], v[230:233], v[2:5], v[64:79]
	s_waitcnt lgkmcnt(0)
	v_mfma_f32_32x32x16_bf16 v[64:79], v[234:237], v[6:9], v[64:79]
	s_mov_b64 s[16:17], 0
	v_mov_b64_e32 v[238:239], v[246:247]
	v_mov_b64_e32 v[240:241], v[248:249]
	v_mov_b32_e32 v242, v250

; __device__ __forceinline__ unsigned pk2(float lo, float hi) { f32x2_t v = {lo, hi}; bf16x2_t b = __builtin_convertvector(v, bf16x2_t); return __builtin_bit_cast(unsigned, b); }
; __device__ __forceinline__ int kr16(int r, int h) { return (r & 3) + 8 * (r >> 2) + 4 * h; }
; #define SCHED_BAR() __builtin_amdgcn_sched_barrier(0)
; __device__ __forceinline__ void mma_pv(const bf16x8 (&vf)[2][2], const f32x16& p, f32x16 (&O)[2]) {
;     bf16x8 pf[2];
; #pragma unroll
;     for (int s = 0; s < 2; ++s) { u32x4 w; w.x = pk2(p[8 * s], p[8 * s + 1]); w.y = pk2(p[8 * s + 2], p[8 * s + 3]); w.z = pk2(p[8 * s + 4], p[8 * s + 5]); w.w = pk2(p[8 * s + 6], p[8 * s + 7]); pf[s] = __builtin_bit_cast(bf16x8, w); }
; #pragma unroll
;     for (int d = 0; d < 2; ++d)
; #pragma unroll
;         for (int s = 0; s < 2; ++s) { __builtin_amdgcn_s_setprio(1); O[d] = __builtin_amdgcn_mfma_f32_32x32x16_bf16(vf[d][s], pf[s], O[d], 0, 0, 0); __builtin_amdgcn_s_setprio(0); }
; }
; __device__ __forceinline__ void nsa_unit(unsigned char* ws, LAS unsigned char* kvb, int bl, int g, int qt, int tid, int wave, int lane) {
;     ...
;                     bf16x8 kf[4], vf[2][2]; load_k<4>(kb + o * 144, kf); load_v(vb + 2 * o, vf); SCHED_BAR();
;                     f32x16 s = mma_qk<4>(kf, qf);
;                     if (!(none0 ? full1 : full0)) { unsigned valid = 0u;
; #pragma unroll
;                         for (int r = 0; r < 16; ++r) { const int dist = qpos - (k0 + o + kr16(r, h)); valid |= ((dist >= 0 && dist < 512) ? 1u : 0u) << r; }
;                         mask_apply(s, valid); }
;                     sm_fast(s, C_NSA, m, l, O); mma_pv(vf, s, O); return; }
.LBB0_933:
	v_add_f32_e32 v62, v62, v63
	v_add_f32_e32 v180, v62, v186
	v_cvt_pk_bf16_f32 v68, v14, v15
	v_cvt_pk_bf16_f32 v69, v48, v49
	v_cvt_pk_bf16_f32 v70, v50, v51
	v_cvt_pk_bf16_f32 v71, v52, v53
	v_cvt_pk_bf16_f32 v48, v54, v55
	v_cvt_pk_bf16_f32 v49, v56, v57
	v_cvt_pk_bf16_f32 v50, v58, v59
	v_cvt_pk_bf16_f32 v51, v60, v61
	s_setprio 1
	s_waitcnt lgkmcnt(3)
	v_mfma_f32_32x32x16_bf16 v[32:47], v[64:67], v[68:71], v[32:47]
	s_waitcnt lgkmcnt(2)
	v_mfma_f32_32x32x16_bf16 v[32:47], v[10:13], v[48:51], v[32:47]
	s_waitcnt lgkmcnt(1)
	v_mfma_f32_32x32x16_bf16 v[16:31], v[6:9], v[68:71], v[16:31]
	s_waitcnt lgkmcnt(0)
	v_mfma_f32_32x32x16_bf16 v[16:31], v[2:5], v[48:51], v[16:31]
	s_nop 3
	v_mov_b64_e32 v[62:63], v[46:47]
	v_mov_b64_e32 v[60:61], v[44:45]
	v_mov_b64_e32 v[58:59], v[42:43]
	v_mov_b64_e32 v[56:57], v[40:41]
	v_mov_b64_e32 v[54:55], v[38:39]
	v_mov_b64_e32 v[52:53], v[36:37]
	v_mov_b64_e32 v[50:51], v[34:35]
	s_nop 0
	v_mov_b64_e32 v[78:79], v[30:31]
	v_mov_b64_e32 v[76:77], v[28:29]
	v_mov_b64_e32 v[74:75], v[26:27]
	v_mov_b64_e32 v[72:73], v[24:25]
	v_mov_b64_e32 v[70:71], v[22:23]
	v_mov_b64_e32 v[68:69], v[20:21]
	v_mov_b64_e32 v[66:67], v[18:19]
	v_mov_b64_e32 v[64:65], v[16:17]
	v_mov_b64_e32 v[48:49], v[32:33]
